# speedup vs baseline: 1.0385x; 1.0217x over previous
; #define ROWLOOP _Pragma("unroll") for(int ai=0;ai<2;++ai) _Pragma("unroll") for(int m=0;m<4;++m)
; #define PK8(a0,a1,a2,a3,b0,b1,b2,b3) make_uint4(cvtpk2(a0,a1), cvtpk2(a2,a3), cvtpk2(b0,b1), cvtpk2(b2,b3))
; #define ROWSUM4(v) do { v += __shfl_xor(v, 16); v += __shfl_xor(v, 32); } while (0)
; template <int EPI>
; __device__ __forceinline__ void gemm_run(const GD& c, const bool has_next, const GD& nx, const Ctx& e, bf16* shm, float* rs, float* rs_nxt, float* racc_) {
;     ...
;     ROWLOOP { const int lrow = LROW; const long row = brow + lrow; float ss = 0.f;
;       long orow = -1;
;       if (e.final_) {
;         int ri = (int)row;
;         if (ri < ROWS_P) { int s = ri / LP, pos = ri - s * LP; if (pos >= 16) orow = (long)s * 4096 + pos - 16; }
;         else if (ri < TREAL) { int q = ri - ROWS_P; int s = q / LS, pos = q - s * LS; if (pos >= 16) orow = 65536L + (long)s * 8192 + pos - 16; }
;       }
; #pragma unroll
;       for (int bj = 0; bj < 2; ++bj) {
;         const int col = bcol + bj * 128 + wc * 32 + cq8;
;         const long idx = row * 1024 + col;
;         const uint4 hh = *reinterpret_cast<const uint4*>(e.hb + idx);
;         float h[8];
;         h[0] = BFLO(hh.x) + sc * acc[ai][bj][m][0][0]; h[1] = BFHI(hh.x) + sc * acc[ai][bj][m][0][1];
;         h[2] = BFLO(hh.y) + sc * acc[ai][bj][m][0][2]; h[3] = BFHI(hh.y) + sc * acc[ai][bj][m][0][3];
;         h[4] = BFLO(hh.z) + sc * acc[ai][bj][m][1][0]; h[5] = BFHI(hh.z) + sc * acc[ai][bj][m][1][1];
;         h[6] = BFLO(hh.w) + sc * acc[ai][bj][m][1][2]; h[7] = BFHI(hh.w) + sc * acc[ai][bj][m][1][3];
;         if (e.final_) { if (orow >= 0) { *reinterpret_cast<float4*>(e.out + orow * 1024 + col) = make_float4(h[0], h[1], h[2], h[3]);
;                                          *reinterpret_cast<float4*>(e.out + orow * 1024 + col + 4) = make_float4(h[4], h[5], h[6], h[7]); } }
;         else { const uint4 pk = PK8(h[0], h[1], h[2], h[3], h[4], h[5], h[6], h[7]); *reinterpret_cast<uint4*>(e.hb + idx) = pk;
;                const float q0 = BFLO(pk.x), q1 = BFHI(pk.x), q2 = BFLO(pk.y), q3 = BFHI(pk.y), q4 = BFLO(pk.z), q5 = BFHI(pk.z), q6 = BFLO(pk.w), q7 = BFHI(pk.w);
;                ss += (q0 * q0 + q1 * q1 + q2 * q2 + q3 * q3) + (q4 * q4 + q5 * q5 + q6 * q6 + q7 * q7); }
;       }
;       if (!e.final_) { ROWSUM4(ss); if (fq == 0) racc[wc * 256 + lrow] = ss; }
.LBB0_331:
	v_mov_b32_e32 v0, v165
	s_movk_i32 s4, 0xffc0
	v_and_b32_e32 v130, 15, v0
	v_ashrrev_i32_e32 v134, 2, v0
	v_bfe_u32 v131, v0, 6, 2
	v_bfe_u32 v132, v0, 4, 2
	v_and_or_b32 v134, v134, s4, v130
	v_lshlrev_b32_e32 v133, 3, v132
	v_lshlrev_b32_e32 v130, 5, v131
	v_cmp_eq_u32_e32 vcc, 0, v132
	v_add_u32_e32 v132, s15, v134
	v_or3_b32 v130, v130, v133, s25
	v_ashrrev_i32_e32 v133, 31, v132
	v_readlane_b32 s4, v254, 25
	v_lshlrev_b64 v[136:137], 11, v[132:133]
	v_lshl_add_u64 v[136:137], s[10:11], 0, v[136:137]
	v_lshl_add_u32 v135, v131, 10, s4
	v_ashrrev_i32_e32 v131, 31, v130
	v_lshl_add_u64 v[142:143], v[130:131], 1, v[136:137]
	v_mov_b32_e32 v160, 0x8000
	v_mov_b32_e32 v161, 0
	v_mov_b32_e32 v162, 0x40000
	v_mov_b32_e32 v163, 0
	v_lshl_add_u64 v[146:147], v[142:143], 0, v[160:161]
	v_lshl_add_u64 v[148:149], v[146:147], 0, v[160:161]
	v_lshl_add_u64 v[150:151], v[148:149], 0, v[160:161]
	v_lshl_add_u64 v[152:153], v[142:143], 0, v[162:163]
	v_lshl_add_u64 v[154:155], v[146:147], 0, v[162:163]
	v_lshl_add_u64 v[156:157], v[148:149], 0, v[162:163]
	v_lshl_add_u64 v[158:159], v[150:151], 0, v[162:163]
	global_load_dwordx4 v[186:189], v[142:143], off
	global_load_dwordx4 v[190:193], v[142:143], off offset:256
	global_load_dwordx4 v[194:197], v[146:147], off
	global_load_dwordx4 v[198:201], v[146:147], off offset:256
	global_load_dwordx4 v[202:205], v[148:149], off
	global_load_dwordx4 v[206:209], v[148:149], off offset:256
	global_load_dwordx4 v[210:213], v[150:151], off
	global_load_dwordx4 v[214:217], v[150:151], off offset:256
	global_load_dwordx4 v[218:221], v[152:153], off
	global_load_dwordx4 v[222:225], v[152:153], off offset:256
	global_load_dwordx4 v[226:229], v[154:155], off
	global_load_dwordx4 v[230:233], v[154:155], off offset:256
	global_load_dwordx4 v[234:237], v[156:157], off
	global_load_dwordx4 v[238:241], v[156:157], off offset:256
	global_load_dwordx4 v[242:245], v[158:159], off
	global_load_dwordx4 v[246:249], v[158:159], off offset:256
	s_waitcnt vmcnt(15)
	v_mov_b64_e32 v[136:137], v[186:187]
	v_mov_b64_e32 v[138:139], v[188:189]
	v_lshlrev_b32_e32 v144, 16, v136
	v_and_b32_e32 v145, 0xffff0000, v136
	v_lshlrev_b32_e32 v136, 16, v137
	v_and_b32_e32 v137, 0xffff0000, v137
	v_pk_fma_f32 v[128:129], v[128:129], 0.5, v[136:137] op_sel_hi:[1,0,1]
	v_lshlrev_b32_e32 v136, 16, v138
	v_and_b32_e32 v137, 0xffff0000, v138
	v_pk_fma_f32 v[136:137], v[122:123], 0.5, v[136:137] op_sel_hi:[1,0,1]
	v_lshlrev_b32_e32 v122, 16, v139
	v_and_b32_e32 v123, 0xffff0000, v139
	v_pk_fma_f32 v[126:127], v[126:127], 0.5, v[144:145] op_sel_hi:[1,0,1]
	v_pk_fma_f32 v[138:139], v[124:125], 0.5, v[122:123] op_sel_hi:[1,0,1]
	v_cvt_pk_bf16_f32 v122, v126, v127
	v_cvt_pk_bf16_f32 v123, v128, v129
	v_cvt_pk_bf16_f32 v124, v136, v137
	v_cvt_pk_bf16_f32 v125, v138, v139
	global_store_dwordx4 v[142:143], v[122:125], off
	v_lshlrev_b32_e32 v126, 16, v122
	v_lshlrev_b32_e32 v127, 16, v123
	v_and_b32_e32 v122, 0xffff0000, v122
	v_mul_f32_e32 v122, v122, v122
	v_fmac_f32_e32 v122, v126, v126
	v_and_b32_e32 v123, 0xffff0000, v123
	v_lshlrev_b32_e32 v128, 16, v124
	v_and_b32_e32 v124, 0xffff0000, v124
	v_fmac_f32_e32 v122, v127, v127
	v_fmac_f32_e32 v122, v123, v123
	v_mul_f32_e32 v123, v124, v124
	v_lshlrev_b32_e32 v129, 16, v125
	v_fmac_f32_e32 v123, v128, v128
	v_and_b32_e32 v125, 0xffff0000, v125
	v_fmac_f32_e32 v123, v129, v129
	v_fmac_f32_e32 v123, v125, v125
	v_add_f32_e32 v128, v122, v123
	s_waitcnt vmcnt(15)
	v_mov_b64_e32 v[122:123], v[190:191]
	v_mov_b64_e32 v[124:125], v[192:193]
	v_lshlrev_b32_e32 v126, 16, v122
	v_and_b32_e32 v127, 0xffff0000, v122
	v_lshlrev_b32_e32 v122, 16, v123
	v_and_b32_e32 v123, 0xffff0000, v123
	v_pk_fma_f32 v[120:121], v[120:121], 0.5, v[122:123] op_sel_hi:[1,0,1]
	v_lshlrev_b32_e32 v122, 16, v124
	v_and_b32_e32 v123, 0xffff0000, v124
	v_pk_fma_f32 v[122:123], v[114:115], 0.5, v[122:123] op_sel_hi:[1,0,1]
	v_lshlrev_b32_e32 v114, 16, v125
	v_and_b32_e32 v115, 0xffff0000, v125
	v_pk_fma_f32 v[118:119], v[118:119], 0.5, v[126:127] op_sel_hi:[1,0,1]
	v_pk_fma_f32 v[124:125], v[116:117], 0.5, v[114:115] op_sel_hi:[1,0,1]
	v_cvt_pk_bf16_f32 v114, v118, v119
	v_cvt_pk_bf16_f32 v115, v120, v121
	v_cvt_pk_bf16_f32 v116, v122, v123
	v_cvt_pk_bf16_f32 v117, v124, v125
	global_store_dwordx4 v[142:143], v[114:117], off offset:256
	v_lshlrev_b32_e32 v118, 16, v114
	v_lshlrev_b32_e32 v119, 16, v115
	v_and_b32_e32 v114, 0xffff0000, v114
	v_mul_f32_e32 v114, v114, v114
	v_fmac_f32_e32 v114, v118, v118
	v_and_b32_e32 v115, 0xffff0000, v115
	v_lshlrev_b32_e32 v120, 16, v116
	v_and_b32_e32 v116, 0xffff0000, v116
	v_fmac_f32_e32 v114, v119, v119
	v_fmac_f32_e32 v114, v115, v115
	v_mul_f32_e32 v115, v116, v116
	v_lshlrev_b32_e32 v121, 16, v117
	v_fmac_f32_e32 v115, v120, v120
	v_and_b32_e32 v117, 0xffff0000, v117
	v_fmac_f32_e32 v115, v121, v121
	v_fmac_f32_e32 v115, v117, v117
	v_and_b32_e32 v116, 64, v180
	v_add_f32_e32 v114, v114, v115
	v_xor_b32_e32 v115, 16, v180
	v_add_u32_e32 v117, 64, v116
	v_cmp_lt_i32_e64 s[4:5], v115, v117
	v_add_f32_e32 v114, v128, v114
	s_nop 0
	v_cndmask_b32_e64 v115, v180, v115, s[4:5]
	v_lshlrev_b32_e32 v116, 2, v115
	ds_bpermute_b32 v115, v116, v114
	s_waitcnt lgkmcnt(0)
	v_add_f32_e32 v114, v114, v115
	v_xor_b32_e32 v115, 32, v180
	v_cmp_lt_i32_e64 s[4:5], v115, v117
	v_lshl_add_u32 v117, v134, 2, v135
	s_nop 0
	v_cndmask_b32_e64 v115, v180, v115, s[4:5]
	v_lshlrev_b32_e32 v118, 2, v115
	ds_bpermute_b32 v115, v118, v114
	s_and_saveexec_b64 s[4:5], vcc
	s_cbranch_execz .LBB0_333
	s_waitcnt lgkmcnt(0)
	v_add_f32_e32 v114, v114, v115
	ds_write_b32 v117, v114
; #define ROWLOOP _Pragma("unroll") for(int ai=0;ai<2;++ai) _Pragma("unroll") for(int m=0;m<4;++m)
; #define PK8(a0,a1,a2,a3,b0,b1,b2,b3) make_uint4(cvtpk2(a0,a1), cvtpk2(a2,a3), cvtpk2(b0,b1), cvtpk2(b2,b3))
; #define ROWSUM4(v) do { v += __shfl_xor(v, 16); v += __shfl_xor(v, 32); } while (0)
; template <int EPI>
; __device__ __forceinline__ void gemm_run(const GD& c, const bool has_next, const GD& nx, const Ctx& e, bf16* shm, float* rs, float* rs_nxt, float* racc_) {
;     ...
;     ROWLOOP { const int lrow = LROW; const long row = brow + lrow; float ss = 0.f;
;       long orow = -1;
;       if (e.final_) {
;         int ri = (int)row;
;         if (ri < ROWS_P) { int s = ri / LP, pos = ri - s * LP; if (pos >= 16) orow = (long)s * 4096 + pos - 16; }
;         else if (ri < TREAL) { int q = ri - ROWS_P; int s = q / LS, pos = q - s * LS; if (pos >= 16) orow = 65536L + (long)s * 8192 + pos - 16; }
;       }
; #pragma unroll
;       for (int bj = 0; bj < 2; ++bj) {
;         const int col = bcol + bj * 128 + wc * 32 + cq8;
;         const long idx = row * 1024 + col;
;         const uint4 hh = *reinterpret_cast<const uint4*>(e.hb + idx);
;         float h[8];
;         h[0] = BFLO(hh.x) + sc * acc[ai][bj][m][0][0]; h[1] = BFHI(hh.x) + sc * acc[ai][bj][m][0][1];
;         h[2] = BFLO(hh.y) + sc * acc[ai][bj][m][0][2]; h[3] = BFHI(hh.y) + sc * acc[ai][bj][m][0][3];
;         h[4] = BFLO(hh.z) + sc * acc[ai][bj][m][1][0]; h[5] = BFHI(hh.z) + sc * acc[ai][bj][m][1][1];
;         h[6] = BFLO(hh.w) + sc * acc[ai][bj][m][1][2]; h[7] = BFHI(hh.w) + sc * acc[ai][bj][m][1][3];
;         if (e.final_) { if (orow >= 0) { *reinterpret_cast<float4*>(e.out + orow * 1024 + col) = make_float4(h[0], h[1], h[2], h[3]);
;                                          *reinterpret_cast<float4*>(e.out + orow * 1024 + col + 4) = make_float4(h[4], h[5], h[6], h[7]); } }
;         else { const uint4 pk = PK8(h[0], h[1], h[2], h[3], h[4], h[5], h[6], h[7]); *reinterpret_cast<uint4*>(e.hb + idx) = pk;
;                const float q0 = BFLO(pk.x), q1 = BFHI(pk.x), q2 = BFLO(pk.y), q3 = BFHI(pk.y), q4 = BFLO(pk.z), q5 = BFHI(pk.z), q6 = BFLO(pk.w), q7 = BFHI(pk.w);
;                ss += (q0 * q0 + q1 * q1 + q2 * q2 + q3 * q3) + (q4 * q4 + q5 * q5 + q6 * q6 + q7 * q7); }
;       }
;       if (!e.final_) { ROWSUM4(ss); if (fq == 0) racc[wc * 256 + lrow] = ss; }
.LBB0_333:
	s_or_b64 exec, exec, s[4:5]
	v_add3_u32 v114, s15, v134, 16
	s_waitcnt lgkmcnt(0)
	v_ashrrev_i32_e32 v115, 31, v114
	v_lshlrev_b64 v[114:115], 11, v[114:115]
	v_lshl_add_u64 v[114:115], s[10:11], 0, v[114:115]
	v_lshl_add_u64 v[114:115], v[130:131], 1, v[114:115]
	s_waitcnt vmcnt(15)
	v_mov_b64_e32 v[120:121], v[194:195]
	v_mov_b64_e32 v[122:123], v[196:197]
	v_lshlrev_b32_e32 v124, 16, v120
	v_and_b32_e32 v125, 0xffff0000, v120
	v_lshlrev_b32_e32 v120, 16, v121
	v_and_b32_e32 v121, 0xffff0000, v121
	v_pk_fma_f32 v[112:113], v[112:113], 0.5, v[120:121] op_sel_hi:[1,0,1]
	v_lshlrev_b32_e32 v120, 16, v122
	v_and_b32_e32 v121, 0xffff0000, v122
	v_pk_fma_f32 v[120:121], v[106:107], 0.5, v[120:121] op_sel_hi:[1,0,1]
	v_lshlrev_b32_e32 v106, 16, v123
	v_and_b32_e32 v107, 0xffff0000, v123
	v_pk_fma_f32 v[110:111], v[110:111], 0.5, v[124:125] op_sel_hi:[1,0,1]
	v_pk_fma_f32 v[122:123], v[108:109], 0.5, v[106:107] op_sel_hi:[1,0,1]
	v_cvt_pk_bf16_f32 v106, v110, v111
	v_cvt_pk_bf16_f32 v107, v112, v113
	v_cvt_pk_bf16_f32 v108, v120, v121
	v_cvt_pk_bf16_f32 v109, v122, v123
	global_store_dwordx4 v[114:115], v[106:109], off
	v_lshlrev_b32_e32 v110, 16, v106
	v_lshlrev_b32_e32 v111, 16, v107
	v_and_b32_e32 v106, 0xffff0000, v106
	v_mul_f32_e32 v106, v106, v106
	v_fmac_f32_e32 v106, v110, v110
	v_and_b32_e32 v107, 0xffff0000, v107
	v_lshlrev_b32_e32 v112, 16, v108
	v_and_b32_e32 v108, 0xffff0000, v108
	v_fmac_f32_e32 v106, v111, v111
	v_fmac_f32_e32 v106, v107, v107
	v_mul_f32_e32 v107, v108, v108
	v_lshlrev_b32_e32 v113, 16, v109
	v_fmac_f32_e32 v107, v112, v112
	v_and_b32_e32 v109, 0xffff0000, v109
	v_fmac_f32_e32 v107, v113, v113
	v_fmac_f32_e32 v107, v109, v109
	v_add_f32_e32 v112, v106, v107
	s_waitcnt vmcnt(15)
	v_mov_b64_e32 v[106:107], v[198:199]
	v_mov_b64_e32 v[108:109], v[200:201]
	v_lshlrev_b32_e32 v110, 16, v106
	v_and_b32_e32 v111, 0xffff0000, v106
	v_lshlrev_b32_e32 v106, 16, v107
	v_and_b32_e32 v107, 0xffff0000, v107
	v_pk_fma_f32 v[104:105], v[104:105], 0.5, v[106:107] op_sel_hi:[1,0,1]
	v_lshlrev_b32_e32 v106, 16, v108
	v_and_b32_e32 v107, 0xffff0000, v108
	v_pk_fma_f32 v[106:107], v[98:99], 0.5, v[106:107] op_sel_hi:[1,0,1]
	v_lshlrev_b32_e32 v98, 16, v109
	v_and_b32_e32 v99, 0xffff0000, v109
	v_pk_fma_f32 v[102:103], v[102:103], 0.5, v[110:111] op_sel_hi:[1,0,1]
	v_pk_fma_f32 v[108:109], v[100:101], 0.5, v[98:99] op_sel_hi:[1,0,1]
	v_cvt_pk_bf16_f32 v98, v102, v103
	v_cvt_pk_bf16_f32 v99, v104, v105
	v_cvt_pk_bf16_f32 v100, v106, v107
	v_cvt_pk_bf16_f32 v101, v108, v109
	global_store_dwordx4 v[114:115], v[98:101], off offset:256
	v_lshlrev_b32_e32 v102, 16, v98
	v_lshlrev_b32_e32 v103, 16, v99
	v_and_b32_e32 v98, 0xffff0000, v98
	v_mul_f32_e32 v98, v98, v98
	v_fmac_f32_e32 v98, v102, v102
	v_and_b32_e32 v99, 0xffff0000, v99
	v_lshlrev_b32_e32 v104, 16, v100
	v_and_b32_e32 v100, 0xffff0000, v100
	v_fmac_f32_e32 v98, v103, v103
	v_fmac_f32_e32 v98, v99, v99
	v_mul_f32_e32 v99, v100, v100
	v_lshlrev_b32_e32 v105, 16, v101
	v_fmac_f32_e32 v99, v104, v104
	v_and_b32_e32 v101, 0xffff0000, v101
	v_fmac_f32_e32 v99, v105, v105
	v_fmac_f32_e32 v99, v101, v101
	v_add_f32_e32 v98, v98, v99
	v_add_f32_e32 v98, v112, v98
	ds_bpermute_b32 v99, v116, v98
	s_waitcnt lgkmcnt(0)
	v_add_f32_e32 v98, v98, v99
	ds_bpermute_b32 v99, v118, v98
	s_and_saveexec_b64 s[4:5], vcc
	s_cbranch_execz .LBB0_335
	s_waitcnt lgkmcnt(0)
	v_add_f32_e32 v98, v98, v99
	ds_write_b32 v117, v98 offset:64
.LBB0_335:
	s_or_b64 exec, exec, s[4:5]
	v_add3_u32 v98, s15, v134, 32
	s_waitcnt lgkmcnt(0)
	v_ashrrev_i32_e32 v99, 31, v98
	v_lshlrev_b64 v[98:99], 11, v[98:99]
	v_lshl_add_u64 v[98:99], s[10:11], 0, v[98:99]
	v_lshl_add_u64 v[98:99], v[130:131], 1, v[98:99]
	s_waitcnt vmcnt(15)
	v_mov_b64_e32 v[100:101], v[202:203]
	v_mov_b64_e32 v[102:103], v[204:205]
	v_lshlrev_b32_e32 v104, 16, v100
	v_and_b32_e32 v105, 0xffff0000, v100
	v_lshlrev_b32_e32 v100, 16, v101
	v_and_b32_e32 v101, 0xffff0000, v101
	v_pk_fma_f32 v[96:97], v[96:97], 0.5, v[100:101] op_sel_hi:[1,0,1]
	v_lshlrev_b32_e32 v100, 16, v102
	v_and_b32_e32 v101, 0xffff0000, v102
	v_pk_fma_f32 v[100:101], v[90:91], 0.5, v[100:101] op_sel_hi:[1,0,1]
	v_lshlrev_b32_e32 v90, 16, v103
	v_and_b32_e32 v91, 0xffff0000, v103
	v_pk_fma_f32 v[94:95], v[94:95], 0.5, v[104:105] op_sel_hi:[1,0,1]
	v_pk_fma_f32 v[102:103], v[92:93], 0.5, v[90:91] op_sel_hi:[1,0,1]
	v_cvt_pk_bf16_f32 v90, v94, v95
	v_cvt_pk_bf16_f32 v91, v96, v97
	v_cvt_pk_bf16_f32 v92, v100, v101
	v_cvt_pk_bf16_f32 v93, v102, v103
	global_store_dwordx4 v[98:99], v[90:93], off
	v_lshlrev_b32_e32 v94, 16, v90
	v_lshlrev_b32_e32 v95, 16, v91
	v_and_b32_e32 v90, 0xffff0000, v90
	v_mul_f32_e32 v90, v90, v90
	v_fmac_f32_e32 v90, v94, v94
	v_and_b32_e32 v91, 0xffff0000, v91
	v_lshlrev_b32_e32 v96, 16, v92
	v_and_b32_e32 v92, 0xffff0000, v92
	v_fmac_f32_e32 v90, v95, v95
	v_fmac_f32_e32 v90, v91, v91
	v_mul_f32_e32 v91, v92, v92
	v_lshlrev_b32_e32 v97, 16, v93
	v_fmac_f32_e32 v91, v96, v96
	v_and_b32_e32 v93, 0xffff0000, v93
	v_fmac_f32_e32 v91, v97, v97
	v_fmac_f32_e32 v91, v93, v93
	v_add_f32_e32 v96, v90, v91
	s_waitcnt vmcnt(15)
	v_mov_b64_e32 v[90:91], v[206:207]
	v_mov_b64_e32 v[92:93], v[208:209]
	v_lshlrev_b32_e32 v94, 16, v90
	v_and_b32_e32 v95, 0xffff0000, v90
	v_lshlrev_b32_e32 v90, 16, v91
	v_and_b32_e32 v91, 0xffff0000, v91
	v_pk_fma_f32 v[88:89], v[88:89], 0.5, v[90:91] op_sel_hi:[1,0,1]
	v_lshlrev_b32_e32 v90, 16, v92
	v_and_b32_e32 v91, 0xffff0000, v92
	v_pk_fma_f32 v[90:91], v[82:83], 0.5, v[90:91] op_sel_hi:[1,0,1]
	v_lshlrev_b32_e32 v82, 16, v93
	v_and_b32_e32 v83, 0xffff0000, v93
	v_pk_fma_f32 v[86:87], v[86:87], 0.5, v[94:95] op_sel_hi:[1,0,1]
	v_pk_fma_f32 v[92:93], v[84:85], 0.5, v[82:83] op_sel_hi:[1,0,1]
	v_cvt_pk_bf16_f32 v82, v86, v87
	v_cvt_pk_bf16_f32 v83, v88, v89
	v_cvt_pk_bf16_f32 v84, v90, v91
	v_cvt_pk_bf16_f32 v85, v92, v93
	global_store_dwordx4 v[98:99], v[82:85], off offset:256
	v_lshlrev_b32_e32 v86, 16, v82
	v_lshlrev_b32_e32 v87, 16, v83
	v_and_b32_e32 v82, 0xffff0000, v82
	v_mul_f32_e32 v82, v82, v82
	v_fmac_f32_e32 v82, v86, v86
	v_and_b32_e32 v83, 0xffff0000, v83
	v_lshlrev_b32_e32 v88, 16, v84
	v_and_b32_e32 v84, 0xffff0000, v84
	v_fmac_f32_e32 v82, v87, v87
	v_fmac_f32_e32 v82, v83, v83
	v_mul_f32_e32 v83, v84, v84
	v_lshlrev_b32_e32 v89, 16, v85
	v_fmac_f32_e32 v83, v88, v88
	v_and_b32_e32 v85, 0xffff0000, v85
	v_fmac_f32_e32 v83, v89, v89
	v_fmac_f32_e32 v83, v85, v85
	v_add_f32_e32 v82, v82, v83
	v_add_f32_e32 v82, v96, v82
	ds_bpermute_b32 v83, v116, v82
	s_waitcnt lgkmcnt(0)
	v_add_f32_e32 v82, v82, v83
	ds_bpermute_b32 v83, v118, v82
	s_and_saveexec_b64 s[4:5], vcc
	s_cbranch_execz .LBB0_337
	s_waitcnt lgkmcnt(0)
	v_add_f32_e32 v82, v82, v83
	ds_write_b32 v117, v82 offset:128
; #define ROWLOOP _Pragma("unroll") for(int ai=0;ai<2;++ai) _Pragma("unroll") for(int m=0;m<4;++m)
; #define PK8(a0,a1,a2,a3,b0,b1,b2,b3) make_uint4(cvtpk2(a0,a1), cvtpk2(a2,a3), cvtpk2(b0,b1), cvtpk2(b2,b3))
; #define ROWSUM4(v) do { v += __shfl_xor(v, 16); v += __shfl_xor(v, 32); } while (0)
; template <int EPI>
; __device__ __forceinline__ void gemm_run(const GD& c, const bool has_next, const GD& nx, const Ctx& e, bf16* shm, float* rs, float* rs_nxt, float* racc_) {
;     ...
;     ROWLOOP { const int lrow = LROW; const long row = brow + lrow; float ss = 0.f;
;       long orow = -1;
;       if (e.final_) {
;         int ri = (int)row;
;         if (ri < ROWS_P) { int s = ri / LP, pos = ri - s * LP; if (pos >= 16) orow = (long)s * 4096 + pos - 16; }
;         else if (ri < TREAL) { int q = ri - ROWS_P; int s = q / LS, pos = q - s * LS; if (pos >= 16) orow = 65536L + (long)s * 8192 + pos - 16; }
;       }
; #pragma unroll
;       for (int bj = 0; bj < 2; ++bj) {
;         const int col = bcol + bj * 128 + wc * 32 + cq8;
;         const long idx = row * 1024 + col;
;         const uint4 hh = *reinterpret_cast<const uint4*>(e.hb + idx);
;         float h[8];
;         h[0] = BFLO(hh.x) + sc * acc[ai][bj][m][0][0]; h[1] = BFHI(hh.x) + sc * acc[ai][bj][m][0][1];
;         h[2] = BFLO(hh.y) + sc * acc[ai][bj][m][0][2]; h[3] = BFHI(hh.y) + sc * acc[ai][bj][m][0][3];
;         h[4] = BFLO(hh.z) + sc * acc[ai][bj][m][1][0]; h[5] = BFHI(hh.z) + sc * acc[ai][bj][m][1][1];
;         h[6] = BFLO(hh.w) + sc * acc[ai][bj][m][1][2]; h[7] = BFHI(hh.w) + sc * acc[ai][bj][m][1][3];
;         if (e.final_) { if (orow >= 0) { *reinterpret_cast<float4*>(e.out + orow * 1024 + col) = make_float4(h[0], h[1], h[2], h[3]);
;                                          *reinterpret_cast<float4*>(e.out + orow * 1024 + col + 4) = make_float4(h[4], h[5], h[6], h[7]); } }
;         else { const uint4 pk = PK8(h[0], h[1], h[2], h[3], h[4], h[5], h[6], h[7]); *reinterpret_cast<uint4*>(e.hb + idx) = pk;
;                const float q0 = BFLO(pk.x), q1 = BFHI(pk.x), q2 = BFLO(pk.y), q3 = BFHI(pk.y), q4 = BFLO(pk.z), q5 = BFHI(pk.z), q6 = BFLO(pk.w), q7 = BFHI(pk.w);
;                ss += (q0 * q0 + q1 * q1 + q2 * q2 + q3 * q3) + (q4 * q4 + q5 * q5 + q6 * q6 + q7 * q7); }
;       }
;       if (!e.final_) { ROWSUM4(ss); if (fq == 0) racc[wc * 256 + lrow] = ss; }
.LBB0_337:
	s_or_b64 exec, exec, s[4:5]
	v_add3_u32 v82, s15, v134, 48
	s_waitcnt lgkmcnt(0)
	v_ashrrev_i32_e32 v83, 31, v82
	v_lshlrev_b64 v[82:83], 11, v[82:83]
	v_lshl_add_u64 v[82:83], s[10:11], 0, v[82:83]
	v_lshl_add_u64 v[82:83], v[130:131], 1, v[82:83]
	s_waitcnt vmcnt(15)
	v_mov_b64_e32 v[84:85], v[210:211]
	v_mov_b64_e32 v[86:87], v[212:213]
	v_lshlrev_b32_e32 v88, 16, v84
	v_and_b32_e32 v89, 0xffff0000, v84
	v_lshlrev_b32_e32 v84, 16, v85
	v_and_b32_e32 v85, 0xffff0000, v85
	v_pk_fma_f32 v[80:81], v[80:81], 0.5, v[84:85] op_sel_hi:[1,0,1]
	v_lshlrev_b32_e32 v84, 16, v86
	v_and_b32_e32 v85, 0xffff0000, v86
	v_pk_fma_f32 v[84:85], v[74:75], 0.5, v[84:85] op_sel_hi:[1,0,1]
	v_lshlrev_b32_e32 v74, 16, v87
	v_and_b32_e32 v75, 0xffff0000, v87
	v_pk_fma_f32 v[78:79], v[78:79], 0.5, v[88:89] op_sel_hi:[1,0,1]
	v_pk_fma_f32 v[86:87], v[76:77], 0.5, v[74:75] op_sel_hi:[1,0,1]
	v_cvt_pk_bf16_f32 v74, v78, v79
	v_cvt_pk_bf16_f32 v75, v80, v81
	v_cvt_pk_bf16_f32 v76, v84, v85
	v_cvt_pk_bf16_f32 v77, v86, v87
	global_store_dwordx4 v[82:83], v[74:77], off
	v_lshlrev_b32_e32 v78, 16, v74
	v_lshlrev_b32_e32 v79, 16, v75
	v_and_b32_e32 v74, 0xffff0000, v74
	v_mul_f32_e32 v74, v74, v74
	v_fmac_f32_e32 v74, v78, v78
	v_and_b32_e32 v75, 0xffff0000, v75
	v_lshlrev_b32_e32 v80, 16, v76
	v_and_b32_e32 v76, 0xffff0000, v76
	v_fmac_f32_e32 v74, v79, v79
	v_fmac_f32_e32 v74, v75, v75
	v_mul_f32_e32 v75, v76, v76
	v_lshlrev_b32_e32 v81, 16, v77
	v_fmac_f32_e32 v75, v80, v80
	v_and_b32_e32 v77, 0xffff0000, v77
	v_fmac_f32_e32 v75, v81, v81
	v_fmac_f32_e32 v75, v77, v77
	v_add_f32_e32 v80, v74, v75
	s_waitcnt vmcnt(15)
	v_mov_b64_e32 v[74:75], v[214:215]
	v_mov_b64_e32 v[76:77], v[216:217]
	v_lshlrev_b32_e32 v78, 16, v74
	v_and_b32_e32 v79, 0xffff0000, v74
	v_lshlrev_b32_e32 v74, 16, v75
	v_and_b32_e32 v75, 0xffff0000, v75
	v_pk_fma_f32 v[72:73], v[72:73], 0.5, v[74:75] op_sel_hi:[1,0,1]
	v_lshlrev_b32_e32 v74, 16, v76
	v_and_b32_e32 v75, 0xffff0000, v76
	v_pk_fma_f32 v[74:75], v[66:67], 0.5, v[74:75] op_sel_hi:[1,0,1]
	v_lshlrev_b32_e32 v66, 16, v77
	v_and_b32_e32 v67, 0xffff0000, v77
	v_pk_fma_f32 v[70:71], v[70:71], 0.5, v[78:79] op_sel_hi:[1,0,1]
	v_pk_fma_f32 v[76:77], v[68:69], 0.5, v[66:67] op_sel_hi:[1,0,1]
	v_cvt_pk_bf16_f32 v66, v70, v71
	v_cvt_pk_bf16_f32 v67, v72, v73
	v_cvt_pk_bf16_f32 v68, v74, v75
	v_cvt_pk_bf16_f32 v69, v76, v77
	global_store_dwordx4 v[82:83], v[66:69], off offset:256
	v_lshlrev_b32_e32 v70, 16, v66
	v_lshlrev_b32_e32 v71, 16, v67
	v_and_b32_e32 v66, 0xffff0000, v66
	v_mul_f32_e32 v66, v66, v66
	v_fmac_f32_e32 v66, v70, v70
	v_and_b32_e32 v67, 0xffff0000, v67
	v_lshlrev_b32_e32 v72, 16, v68
	v_and_b32_e32 v68, 0xffff0000, v68
	v_fmac_f32_e32 v66, v71, v71
	v_fmac_f32_e32 v66, v67, v67
	v_mul_f32_e32 v67, v68, v68
	v_lshlrev_b32_e32 v73, 16, v69
	v_fmac_f32_e32 v67, v72, v72
	v_and_b32_e32 v69, 0xffff0000, v69
	v_fmac_f32_e32 v67, v73, v73
	v_fmac_f32_e32 v67, v69, v69
	v_add_f32_e32 v66, v66, v67
	v_add_f32_e32 v66, v80, v66
	ds_bpermute_b32 v67, v116, v66
	s_waitcnt lgkmcnt(0)
	v_add_f32_e32 v66, v66, v67
	ds_bpermute_b32 v67, v118, v66
	s_and_saveexec_b64 s[4:5], vcc
	s_cbranch_execz .LBB0_339
	s_waitcnt lgkmcnt(0)
	v_add_f32_e32 v66, v66, v67
	ds_write_b32 v117, v66 offset:192
.LBB0_339:
	s_or_b64 exec, exec, s[4:5]
	v_add_u32_e32 v66, 0x80, v132
	s_waitcnt lgkmcnt(0)
	v_ashrrev_i32_e32 v67, 31, v66
	v_lshlrev_b64 v[66:67], 11, v[66:67]
	v_lshl_add_u64 v[66:67], s[10:11], 0, v[66:67]
	v_lshl_add_u64 v[66:67], v[130:131], 1, v[66:67]
	s_waitcnt vmcnt(15)
	v_mov_b64_e32 v[68:69], v[218:219]
	v_mov_b64_e32 v[70:71], v[220:221]
	v_lshlrev_b32_e32 v72, 16, v68
	v_and_b32_e32 v73, 0xffff0000, v68
	v_lshlrev_b32_e32 v68, 16, v69
	v_and_b32_e32 v69, 0xffff0000, v69
	v_pk_fma_f32 v[64:65], v[64:65], 0.5, v[68:69] op_sel_hi:[1,0,1]
	v_lshlrev_b32_e32 v68, 16, v70
	v_and_b32_e32 v69, 0xffff0000, v70
	v_pk_fma_f32 v[68:69], v[58:59], 0.5, v[68:69] op_sel_hi:[1,0,1]
	v_lshlrev_b32_e32 v58, 16, v71
	v_and_b32_e32 v59, 0xffff0000, v71
	v_pk_fma_f32 v[62:63], v[62:63], 0.5, v[72:73] op_sel_hi:[1,0,1]
	v_pk_fma_f32 v[70:71], v[60:61], 0.5, v[58:59] op_sel_hi:[1,0,1]
	v_cvt_pk_bf16_f32 v58, v62, v63
	v_cvt_pk_bf16_f32 v59, v64, v65
	v_cvt_pk_bf16_f32 v60, v68, v69
	v_cvt_pk_bf16_f32 v61, v70, v71
	global_store_dwordx4 v[66:67], v[58:61], off
	v_lshlrev_b32_e32 v62, 16, v58
	v_lshlrev_b32_e32 v63, 16, v59
	v_and_b32_e32 v58, 0xffff0000, v58
	v_mul_f32_e32 v58, v58, v58
	v_fmac_f32_e32 v58, v62, v62
	v_and_b32_e32 v59, 0xffff0000, v59
	v_lshlrev_b32_e32 v64, 16, v60
	v_and_b32_e32 v60, 0xffff0000, v60
	v_fmac_f32_e32 v58, v63, v63
	v_fmac_f32_e32 v58, v59, v59
	v_mul_f32_e32 v59, v60, v60
	v_lshlrev_b32_e32 v65, 16, v61
	v_fmac_f32_e32 v59, v64, v64
	v_and_b32_e32 v61, 0xffff0000, v61
	v_fmac_f32_e32 v59, v65, v65
	v_fmac_f32_e32 v59, v61, v61
	v_add_f32_e32 v64, v58, v59
	s_waitcnt vmcnt(15)
	v_mov_b64_e32 v[58:59], v[222:223]
	v_mov_b64_e32 v[60:61], v[224:225]
	v_lshlrev_b32_e32 v62, 16, v58
	v_and_b32_e32 v63, 0xffff0000, v58
	v_lshlrev_b32_e32 v58, 16, v59
	v_and_b32_e32 v59, 0xffff0000, v59
	v_pk_fma_f32 v[56:57], v[56:57], 0.5, v[58:59] op_sel_hi:[1,0,1]
	v_lshlrev_b32_e32 v58, 16, v60
	v_and_b32_e32 v59, 0xffff0000, v60
	v_pk_fma_f32 v[58:59], v[50:51], 0.5, v[58:59] op_sel_hi:[1,0,1]
	v_lshlrev_b32_e32 v50, 16, v61
	v_and_b32_e32 v51, 0xffff0000, v61
	v_pk_fma_f32 v[54:55], v[54:55], 0.5, v[62:63] op_sel_hi:[1,0,1]
	v_pk_fma_f32 v[60:61], v[52:53], 0.5, v[50:51] op_sel_hi:[1,0,1]
	v_cvt_pk_bf16_f32 v50, v54, v55
	v_cvt_pk_bf16_f32 v51, v56, v57
	v_cvt_pk_bf16_f32 v52, v58, v59
	v_cvt_pk_bf16_f32 v53, v60, v61
	global_store_dwordx4 v[66:67], v[50:53], off offset:256
	v_lshlrev_b32_e32 v54, 16, v50
	v_lshlrev_b32_e32 v55, 16, v51
	v_and_b32_e32 v50, 0xffff0000, v50
	v_mul_f32_e32 v50, v50, v50
	v_fmac_f32_e32 v50, v54, v54
	v_and_b32_e32 v51, 0xffff0000, v51
	v_lshlrev_b32_e32 v56, 16, v52
	v_and_b32_e32 v52, 0xffff0000, v52
	v_fmac_f32_e32 v50, v55, v55
	v_fmac_f32_e32 v50, v51, v51
	v_mul_f32_e32 v51, v52, v52
	v_lshlrev_b32_e32 v57, 16, v53
	v_fmac_f32_e32 v51, v56, v56
	v_and_b32_e32 v53, 0xffff0000, v53
	v_fmac_f32_e32 v51, v57, v57
	v_fmac_f32_e32 v51, v53, v53
	v_add_f32_e32 v50, v50, v51
	v_add_f32_e32 v50, v64, v50
	ds_bpermute_b32 v51, v116, v50
	s_waitcnt lgkmcnt(0)
	v_add_f32_e32 v50, v50, v51
	ds_bpermute_b32 v51, v118, v50
	s_and_saveexec_b64 s[4:5], vcc
	s_cbranch_execz .LBB0_341
	s_waitcnt lgkmcnt(0)
	v_add_f32_e32 v50, v50, v51
	ds_write_b32 v117, v50 offset:512
; #define ROWLOOP _Pragma("unroll") for(int ai=0;ai<2;++ai) _Pragma("unroll") for(int m=0;m<4;++m)
; #define PK8(a0,a1,a2,a3,b0,b1,b2,b3) make_uint4(cvtpk2(a0,a1), cvtpk2(a2,a3), cvtpk2(b0,b1), cvtpk2(b2,b3))
; #define ROWSUM4(v) do { v += __shfl_xor(v, 16); v += __shfl_xor(v, 32); } while (0)
; template <int EPI>
; __device__ __forceinline__ void gemm_run(const GD& c, const bool has_next, const GD& nx, const Ctx& e, bf16* shm, float* rs, float* rs_nxt, float* racc_) {
;     ...
;     ROWLOOP { const int lrow = LROW; const long row = brow + lrow; float ss = 0.f;
;       long orow = -1;
;       if (e.final_) {
;         int ri = (int)row;
;         if (ri < ROWS_P) { int s = ri / LP, pos = ri - s * LP; if (pos >= 16) orow = (long)s * 4096 + pos - 16; }
;         else if (ri < TREAL) { int q = ri - ROWS_P; int s = q / LS, pos = q - s * LS; if (pos >= 16) orow = 65536L + (long)s * 8192 + pos - 16; }
;       }
; #pragma unroll
;       for (int bj = 0; bj < 2; ++bj) {
;         const int col = bcol + bj * 128 + wc * 32 + cq8;
;         const long idx = row * 1024 + col;
;         const uint4 hh = *reinterpret_cast<const uint4*>(e.hb + idx);
;         float h[8];
;         h[0] = BFLO(hh.x) + sc * acc[ai][bj][m][0][0]; h[1] = BFHI(hh.x) + sc * acc[ai][bj][m][0][1];
;         h[2] = BFLO(hh.y) + sc * acc[ai][bj][m][0][2]; h[3] = BFHI(hh.y) + sc * acc[ai][bj][m][0][3];
;         h[4] = BFLO(hh.z) + sc * acc[ai][bj][m][1][0]; h[5] = BFHI(hh.z) + sc * acc[ai][bj][m][1][1];
;         h[6] = BFLO(hh.w) + sc * acc[ai][bj][m][1][2]; h[7] = BFHI(hh.w) + sc * acc[ai][bj][m][1][3];
;         if (e.final_) { if (orow >= 0) { *reinterpret_cast<float4*>(e.out + orow * 1024 + col) = make_float4(h[0], h[1], h[2], h[3]);
;                                          *reinterpret_cast<float4*>(e.out + orow * 1024 + col + 4) = make_float4(h[4], h[5], h[6], h[7]); } }
;         else { const uint4 pk = PK8(h[0], h[1], h[2], h[3], h[4], h[5], h[6], h[7]); *reinterpret_cast<uint4*>(e.hb + idx) = pk;
;                const float q0 = BFLO(pk.x), q1 = BFHI(pk.x), q2 = BFLO(pk.y), q3 = BFHI(pk.y), q4 = BFLO(pk.z), q5 = BFHI(pk.z), q6 = BFLO(pk.w), q7 = BFHI(pk.w);
;                ss += (q0 * q0 + q1 * q1 + q2 * q2 + q3 * q3) + (q4 * q4 + q5 * q5 + q6 * q6 + q7 * q7); }
;       }
;       if (!e.final_) { ROWSUM4(ss); if (fq == 0) racc[wc * 256 + lrow] = ss; }
.LBB0_341:
	s_or_b64 exec, exec, s[4:5]
	v_add_u32_e32 v50, 0x90, v132
	s_waitcnt lgkmcnt(0)
	v_ashrrev_i32_e32 v51, 31, v50
	v_lshlrev_b64 v[50:51], 11, v[50:51]
	v_lshl_add_u64 v[50:51], s[10:11], 0, v[50:51]
	v_lshl_add_u64 v[50:51], v[130:131], 1, v[50:51]
	s_waitcnt vmcnt(15)
	v_mov_b64_e32 v[52:53], v[226:227]
	v_mov_b64_e32 v[54:55], v[228:229]
	v_lshlrev_b32_e32 v56, 16, v52
	v_and_b32_e32 v57, 0xffff0000, v52
	v_lshlrev_b32_e32 v52, 16, v53
	v_and_b32_e32 v53, 0xffff0000, v53
	v_pk_fma_f32 v[48:49], v[48:49], 0.5, v[52:53] op_sel_hi:[1,0,1]
	v_lshlrev_b32_e32 v52, 16, v54
	v_and_b32_e32 v53, 0xffff0000, v54
	v_pk_fma_f32 v[52:53], v[42:43], 0.5, v[52:53] op_sel_hi:[1,0,1]
	v_lshlrev_b32_e32 v42, 16, v55
	v_and_b32_e32 v43, 0xffff0000, v55
	v_pk_fma_f32 v[46:47], v[46:47], 0.5, v[56:57] op_sel_hi:[1,0,1]
	v_pk_fma_f32 v[54:55], v[44:45], 0.5, v[42:43] op_sel_hi:[1,0,1]
	v_cvt_pk_bf16_f32 v42, v46, v47
	v_cvt_pk_bf16_f32 v43, v48, v49
	v_cvt_pk_bf16_f32 v44, v52, v53
	v_cvt_pk_bf16_f32 v45, v54, v55
	global_store_dwordx4 v[50:51], v[42:45], off
	v_lshlrev_b32_e32 v46, 16, v42
	v_lshlrev_b32_e32 v47, 16, v43
	v_and_b32_e32 v42, 0xffff0000, v42
	v_mul_f32_e32 v42, v42, v42
	v_fmac_f32_e32 v42, v46, v46
	v_and_b32_e32 v43, 0xffff0000, v43
	v_lshlrev_b32_e32 v48, 16, v44
	v_and_b32_e32 v44, 0xffff0000, v44
	v_fmac_f32_e32 v42, v47, v47
	v_fmac_f32_e32 v42, v43, v43
	v_mul_f32_e32 v43, v44, v44
	v_lshlrev_b32_e32 v49, 16, v45
	v_fmac_f32_e32 v43, v48, v48
	v_and_b32_e32 v45, 0xffff0000, v45
	v_fmac_f32_e32 v43, v49, v49
	v_fmac_f32_e32 v43, v45, v45
	v_add_f32_e32 v48, v42, v43
	s_waitcnt vmcnt(15)
	v_mov_b64_e32 v[42:43], v[230:231]
	v_mov_b64_e32 v[44:45], v[232:233]
	v_lshlrev_b32_e32 v46, 16, v42
	v_and_b32_e32 v47, 0xffff0000, v42
	v_lshlrev_b32_e32 v42, 16, v43
	v_and_b32_e32 v43, 0xffff0000, v43
	v_pk_fma_f32 v[40:41], v[40:41], 0.5, v[42:43] op_sel_hi:[1,0,1]
	v_lshlrev_b32_e32 v42, 16, v44
	v_and_b32_e32 v43, 0xffff0000, v44
	v_pk_fma_f32 v[42:43], v[34:35], 0.5, v[42:43] op_sel_hi:[1,0,1]
	v_lshlrev_b32_e32 v34, 16, v45
	v_and_b32_e32 v35, 0xffff0000, v45
	v_pk_fma_f32 v[38:39], v[38:39], 0.5, v[46:47] op_sel_hi:[1,0,1]
	v_pk_fma_f32 v[44:45], v[36:37], 0.5, v[34:35] op_sel_hi:[1,0,1]
	v_cvt_pk_bf16_f32 v34, v38, v39
	v_cvt_pk_bf16_f32 v35, v40, v41
	v_cvt_pk_bf16_f32 v36, v42, v43
	v_cvt_pk_bf16_f32 v37, v44, v45
	global_store_dwordx4 v[50:51], v[34:37], off offset:256
	v_lshlrev_b32_e32 v38, 16, v34
	v_lshlrev_b32_e32 v39, 16, v35
	v_and_b32_e32 v34, 0xffff0000, v34
	v_mul_f32_e32 v34, v34, v34
	v_fmac_f32_e32 v34, v38, v38
	v_and_b32_e32 v35, 0xffff0000, v35
	v_lshlrev_b32_e32 v40, 16, v36
	v_and_b32_e32 v36, 0xffff0000, v36
	v_fmac_f32_e32 v34, v39, v39
	v_fmac_f32_e32 v34, v35, v35
	v_mul_f32_e32 v35, v36, v36
	v_lshlrev_b32_e32 v41, 16, v37
	v_fmac_f32_e32 v35, v40, v40
	v_and_b32_e32 v37, 0xffff0000, v37
	v_fmac_f32_e32 v35, v41, v41
	v_fmac_f32_e32 v35, v37, v37
	v_add_f32_e32 v34, v34, v35
	v_add_f32_e32 v34, v48, v34
	ds_bpermute_b32 v35, v116, v34
	s_waitcnt lgkmcnt(0)
	v_add_f32_e32 v34, v34, v35
	ds_bpermute_b32 v35, v118, v34
	s_and_saveexec_b64 s[4:5], vcc
	s_cbranch_execz .LBB0_343
	s_waitcnt lgkmcnt(0)
	v_add_f32_e32 v34, v34, v35
	ds_write_b32 v117, v34 offset:576
; #define ROWLOOP _Pragma("unroll") for(int ai=0;ai<2;++ai) _Pragma("unroll") for(int m=0;m<4;++m)
; #define PK8(a0,a1,a2,a3,b0,b1,b2,b3) make_uint4(cvtpk2(a0,a1), cvtpk2(a2,a3), cvtpk2(b0,b1), cvtpk2(b2,b3))
; #define ROWSUM4(v) do { v += __shfl_xor(v, 16); v += __shfl_xor(v, 32); } while (0)
; template <int EPI>
; __device__ __forceinline__ void gemm_run(const GD& c, const bool has_next, const GD& nx, const Ctx& e, bf16* shm, float* rs, float* rs_nxt, float* racc_) {
;     ...
;     ROWLOOP { const int lrow = LROW; const long row = brow + lrow; float ss = 0.f;
;       long orow = -1;
;       if (e.final_) {
;         int ri = (int)row;
;         if (ri < ROWS_P) { int s = ri / LP, pos = ri - s * LP; if (pos >= 16) orow = (long)s * 4096 + pos - 16; }
;         else if (ri < TREAL) { int q = ri - ROWS_P; int s = q / LS, pos = q - s * LS; if (pos >= 16) orow = 65536L + (long)s * 8192 + pos - 16; }
;       }
; #pragma unroll
;       for (int bj = 0; bj < 2; ++bj) {
;         const int col = bcol + bj * 128 + wc * 32 + cq8;
;         const long idx = row * 1024 + col;
;         const uint4 hh = *reinterpret_cast<const uint4*>(e.hb + idx);
;         float h[8];
;         h[0] = BFLO(hh.x) + sc * acc[ai][bj][m][0][0]; h[1] = BFHI(hh.x) + sc * acc[ai][bj][m][0][1];
;         h[2] = BFLO(hh.y) + sc * acc[ai][bj][m][0][2]; h[3] = BFHI(hh.y) + sc * acc[ai][bj][m][0][3];
;         h[4] = BFLO(hh.z) + sc * acc[ai][bj][m][1][0]; h[5] = BFHI(hh.z) + sc * acc[ai][bj][m][1][1];
;         h[6] = BFLO(hh.w) + sc * acc[ai][bj][m][1][2]; h[7] = BFHI(hh.w) + sc * acc[ai][bj][m][1][3];
;         if (e.final_) { if (orow >= 0) { *reinterpret_cast<float4*>(e.out + orow * 1024 + col) = make_float4(h[0], h[1], h[2], h[3]);
;                                          *reinterpret_cast<float4*>(e.out + orow * 1024 + col + 4) = make_float4(h[4], h[5], h[6], h[7]); } }
;         else { const uint4 pk = PK8(h[0], h[1], h[2], h[3], h[4], h[5], h[6], h[7]); *reinterpret_cast<uint4*>(e.hb + idx) = pk;
;                const float q0 = BFLO(pk.x), q1 = BFHI(pk.x), q2 = BFLO(pk.y), q3 = BFHI(pk.y), q4 = BFLO(pk.z), q5 = BFHI(pk.z), q6 = BFLO(pk.w), q7 = BFHI(pk.w);
;                ss += (q0 * q0 + q1 * q1 + q2 * q2 + q3 * q3) + (q4 * q4 + q5 * q5 + q6 * q6 + q7 * q7); }
;       }
;       if (!e.final_) { ROWSUM4(ss); if (fq == 0) racc[wc * 256 + lrow] = ss; }
.LBB0_343:
	s_or_b64 exec, exec, s[4:5]
	v_add_u32_e32 v34, 0xa0, v132
	s_waitcnt lgkmcnt(0)
	v_ashrrev_i32_e32 v35, 31, v34
	v_lshlrev_b64 v[34:35], 11, v[34:35]
	v_lshl_add_u64 v[34:35], s[10:11], 0, v[34:35]
	v_lshl_add_u64 v[34:35], v[130:131], 1, v[34:35]
	s_waitcnt vmcnt(15)
	v_mov_b64_e32 v[36:37], v[234:235]
	v_mov_b64_e32 v[38:39], v[236:237]
	v_lshlrev_b32_e32 v40, 16, v36
	v_and_b32_e32 v41, 0xffff0000, v36
	v_lshlrev_b32_e32 v36, 16, v37
	v_and_b32_e32 v37, 0xffff0000, v37
	v_pk_fma_f32 v[32:33], v[32:33], 0.5, v[36:37] op_sel_hi:[1,0,1]
	v_lshlrev_b32_e32 v36, 16, v38
	v_and_b32_e32 v37, 0xffff0000, v38
	v_pk_fma_f32 v[36:37], v[26:27], 0.5, v[36:37] op_sel_hi:[1,0,1]
	v_lshlrev_b32_e32 v26, 16, v39
	v_and_b32_e32 v27, 0xffff0000, v39
	v_pk_fma_f32 v[30:31], v[30:31], 0.5, v[40:41] op_sel_hi:[1,0,1]
	v_pk_fma_f32 v[38:39], v[28:29], 0.5, v[26:27] op_sel_hi:[1,0,1]
	v_cvt_pk_bf16_f32 v26, v30, v31
	v_cvt_pk_bf16_f32 v27, v32, v33
	v_cvt_pk_bf16_f32 v28, v36, v37
	v_cvt_pk_bf16_f32 v29, v38, v39
	global_store_dwordx4 v[34:35], v[26:29], off
	v_lshlrev_b32_e32 v30, 16, v26
	v_lshlrev_b32_e32 v31, 16, v27
	v_and_b32_e32 v26, 0xffff0000, v26
	v_mul_f32_e32 v26, v26, v26
	v_fmac_f32_e32 v26, v30, v30
	v_and_b32_e32 v27, 0xffff0000, v27
	v_lshlrev_b32_e32 v32, 16, v28
	v_and_b32_e32 v28, 0xffff0000, v28
	v_fmac_f32_e32 v26, v31, v31
	v_fmac_f32_e32 v26, v27, v27
	v_mul_f32_e32 v27, v28, v28
	v_lshlrev_b32_e32 v33, 16, v29
	v_fmac_f32_e32 v27, v32, v32
	v_and_b32_e32 v29, 0xffff0000, v29
	v_fmac_f32_e32 v27, v33, v33
	v_fmac_f32_e32 v27, v29, v29
	v_add_f32_e32 v32, v26, v27
	s_waitcnt vmcnt(15)
	v_mov_b64_e32 v[26:27], v[238:239]
	v_mov_b64_e32 v[28:29], v[240:241]
	v_lshlrev_b32_e32 v30, 16, v26
	v_and_b32_e32 v31, 0xffff0000, v26
	v_lshlrev_b32_e32 v26, 16, v27
	v_and_b32_e32 v27, 0xffff0000, v27
	v_pk_fma_f32 v[24:25], v[24:25], 0.5, v[26:27] op_sel_hi:[1,0,1]
	v_lshlrev_b32_e32 v26, 16, v28
	v_and_b32_e32 v27, 0xffff0000, v28
	v_pk_fma_f32 v[26:27], v[18:19], 0.5, v[26:27] op_sel_hi:[1,0,1]
	v_lshlrev_b32_e32 v18, 16, v29
	v_and_b32_e32 v19, 0xffff0000, v29
	v_pk_fma_f32 v[22:23], v[22:23], 0.5, v[30:31] op_sel_hi:[1,0,1]
	v_pk_fma_f32 v[28:29], v[20:21], 0.5, v[18:19] op_sel_hi:[1,0,1]
	v_cvt_pk_bf16_f32 v18, v22, v23
	v_cvt_pk_bf16_f32 v19, v24, v25
	v_cvt_pk_bf16_f32 v20, v26, v27
	v_cvt_pk_bf16_f32 v21, v28, v29
	global_store_dwordx4 v[34:35], v[18:21], off offset:256
	v_lshlrev_b32_e32 v22, 16, v18
	v_lshlrev_b32_e32 v23, 16, v19
	v_and_b32_e32 v18, 0xffff0000, v18
	v_mul_f32_e32 v18, v18, v18
	v_fmac_f32_e32 v18, v22, v22
	v_and_b32_e32 v19, 0xffff0000, v19
	v_lshlrev_b32_e32 v24, 16, v20
	v_and_b32_e32 v20, 0xffff0000, v20
	v_fmac_f32_e32 v18, v23, v23
	v_fmac_f32_e32 v18, v19, v19
	v_mul_f32_e32 v19, v20, v20
	v_lshlrev_b32_e32 v25, 16, v21
	v_fmac_f32_e32 v19, v24, v24
	v_and_b32_e32 v21, 0xffff0000, v21
	v_fmac_f32_e32 v19, v25, v25
	v_fmac_f32_e32 v19, v21, v21
	v_add_f32_e32 v18, v18, v19
	v_add_f32_e32 v18, v32, v18
	ds_bpermute_b32 v19, v116, v18
	s_waitcnt lgkmcnt(0)
	v_add_f32_e32 v18, v18, v19
	ds_bpermute_b32 v19, v118, v18
	s_and_saveexec_b64 s[4:5], vcc
	s_cbranch_execz .LBB0_345
	s_waitcnt lgkmcnt(0)
	v_add_f32_e32 v18, v18, v19
	ds_write_b32 v117, v18 offset:640
.LBB0_345:
	s_or_b64 exec, exec, s[4:5]
	v_add_u32_e32 v18, 0xb0, v132
	s_waitcnt lgkmcnt(0)
	v_ashrrev_i32_e32 v19, 31, v18
	v_lshlrev_b64 v[18:19], 11, v[18:19]
	v_lshl_add_u64 v[18:19], s[10:11], 0, v[18:19]
	v_lshl_add_u64 v[18:19], v[130:131], 1, v[18:19]
	s_waitcnt vmcnt(15)
	v_mov_b64_e32 v[20:21], v[242:243]
	v_mov_b64_e32 v[22:23], v[244:245]
	v_lshlrev_b32_e32 v24, 16, v20
	v_and_b32_e32 v25, 0xffff0000, v20
	v_lshlrev_b32_e32 v20, 16, v21
	v_and_b32_e32 v21, 0xffff0000, v21
	v_pk_fma_f32 v[16:17], v[16:17], 0.5, v[20:21] op_sel_hi:[1,0,1]
	v_lshlrev_b32_e32 v20, 16, v22
	v_and_b32_e32 v21, 0xffff0000, v22
	v_pk_fma_f32 v[20:21], v[10:11], 0.5, v[20:21] op_sel_hi:[1,0,1]
	v_lshlrev_b32_e32 v10, 16, v23
	v_and_b32_e32 v11, 0xffff0000, v23
	v_pk_fma_f32 v[14:15], v[14:15], 0.5, v[24:25] op_sel_hi:[1,0,1]
	v_pk_fma_f32 v[22:23], v[12:13], 0.5, v[10:11] op_sel_hi:[1,0,1]
	v_cvt_pk_bf16_f32 v10, v14, v15
	v_cvt_pk_bf16_f32 v11, v16, v17
	v_cvt_pk_bf16_f32 v12, v20, v21
	v_cvt_pk_bf16_f32 v13, v22, v23
	global_store_dwordx4 v[18:19], v[10:13], off
	v_lshlrev_b32_e32 v14, 16, v10
	v_lshlrev_b32_e32 v15, 16, v11
	v_and_b32_e32 v10, 0xffff0000, v10
	v_mul_f32_e32 v10, v10, v10
	v_fmac_f32_e32 v10, v14, v14
	v_and_b32_e32 v11, 0xffff0000, v11
	v_lshlrev_b32_e32 v16, 16, v12
	v_and_b32_e32 v12, 0xffff0000, v12
	v_fmac_f32_e32 v10, v15, v15
	v_fmac_f32_e32 v10, v11, v11
	v_mul_f32_e32 v11, v12, v12
	v_lshlrev_b32_e32 v17, 16, v13
	v_fmac_f32_e32 v11, v16, v16
	v_and_b32_e32 v13, 0xffff0000, v13
	v_fmac_f32_e32 v11, v17, v17
	v_fmac_f32_e32 v11, v13, v13
	v_add_f32_e32 v16, v10, v11
	s_waitcnt vmcnt(15)
	v_mov_b64_e32 v[10:11], v[246:247]
	v_mov_b64_e32 v[12:13], v[248:249]
	v_lshlrev_b32_e32 v14, 16, v10
	v_and_b32_e32 v15, 0xffff0000, v10
	v_lshlrev_b32_e32 v10, 16, v11
	v_and_b32_e32 v11, 0xffff0000, v11
	v_pk_fma_f32 v[8:9], v[8:9], 0.5, v[10:11] op_sel_hi:[1,0,1]
	v_lshlrev_b32_e32 v10, 16, v12
	v_and_b32_e32 v11, 0xffff0000, v12
	v_pk_fma_f32 v[10:11], v[2:3], 0.5, v[10:11] op_sel_hi:[1,0,1]
	v_lshlrev_b32_e32 v2, 16, v13
	v_and_b32_e32 v3, 0xffff0000, v13
	v_pk_fma_f32 v[6:7], v[6:7], 0.5, v[14:15] op_sel_hi:[1,0,1]
	v_pk_fma_f32 v[12:13], v[4:5], 0.5, v[2:3] op_sel_hi:[1,0,1]
	v_cvt_pk_bf16_f32 v2, v6, v7
	v_cvt_pk_bf16_f32 v3, v8, v9
	v_cvt_pk_bf16_f32 v4, v10, v11
	v_cvt_pk_bf16_f32 v5, v12, v13
	global_store_dwordx4 v[18:19], v[2:5], off offset:256
	v_lshlrev_b32_e32 v6, 16, v2
	v_lshlrev_b32_e32 v7, 16, v3
	v_and_b32_e32 v2, 0xffff0000, v2
	v_mul_f32_e32 v2, v2, v2
	v_fmac_f32_e32 v2, v6, v6
	v_and_b32_e32 v3, 0xffff0000, v3
	v_lshlrev_b32_e32 v8, 16, v4
	v_and_b32_e32 v4, 0xffff0000, v4
	v_fmac_f32_e32 v2, v7, v7
	v_fmac_f32_e32 v2, v3, v3
	v_mul_f32_e32 v3, v4, v4
	v_lshlrev_b32_e32 v9, 16, v5
	v_fmac_f32_e32 v3, v8, v8
	v_and_b32_e32 v5, 0xffff0000, v5
	v_fmac_f32_e32 v3, v9, v9
	v_fmac_f32_e32 v3, v5, v5
	v_add_f32_e32 v2, v2, v3
	v_add_f32_e32 v2, v16, v2
	ds_bpermute_b32 v3, v116, v2
	s_waitcnt lgkmcnt(0)
	v_add_f32_e32 v2, v2, v3
	ds_bpermute_b32 v3, v118, v2
	s_and_saveexec_b64 s[4:5], vcc
	s_cbranch_execz .LBB0_347
	s_waitcnt lgkmcnt(0)
	v_add_f32_e32 v2, v2, v3
	ds_write_b32 v117, v2 offset:704

; __device__ __forceinline__ int v_rd_base(int lane) { return ((lane & 3) << 3) | (((lane >> 2) & 3) << 6) | (((lane >> 4) & 1) << 5) | (((lane >> 5) & 1) << 8); }
; #define SLOAD(i, key0) do { sr_[i].v = *reinterpret_cast<const bf16x8*>(&Vh[(long)((key0) + vr) * ldv + vc]); \
;     sr_[i].k0 = *reinterpret_cast<const bf16x8*>(&Kh[(long)((key0) + kr0) * ldk + kc0]); \
;     if (k2) sr_[i].k1 = *reinterpret_cast<const bf16x8*>(&Kh[(long)((key0) + kr1) * ldk + kc1]); } while (0)
; __device__ __forceinline__ int v_st(int k, int c) { const int kk = (k & ~0xC) | ((k & 4) << 1) | ((k & 8) >> 1); return ((kk >> 3) * 4 + (c >> 5)) * 512 + ((kk & 7) * 32 + (c & 31)) * 2; }
; template <int DQK, bool FIX>
; __device__ __forceinline__ void attn_item(const bf16* Qb, const bf16* __restrict__ Kh, const bf16* __restrict__ Vh,
;                                           u16* Ob, int q0, int L, int NT, char* lds, float mC) {
;     ...
;   int tid = threadIdx.x; asm volatile("" : "+v"(tid));
;   const int wid = tid >> 6, lane = tid & 63, r32 = lane & 31, hi = lane >> 5;
;   bf16* V_lds = (bf16*)lds; bf16* K_lds = (bf16*)(lds + 2 * SHM_V);
;   float* ws = (float*)(lds + 2 * SHM_V + 2 * SHM_K) + wid * 64; float* li_l = ws; float* al_l = ws + 32;
;   float m_reg = -1e30f, l_reg = 0; f32x16 o[2] = {}; bf16x8 qr[ND];
;   __syncthreads();
;   { int qrow = q0 + wid * 32 + r32; if (qrow > L - 1) qrow = L - 1;
;     const bf16* Qw = Qb + (long)qrow * ldq + hi * 8;
; #pragma unroll
;     for (int d0 = 0; d0 < ND; ++d0) qr[d0] = *reinterpret_cast<const bf16x8*>(Qw + d0 * 16); }
;   const int vr = tid >> 3, vc = (tid & 7) * 8, vst = v_st(vr, vc);
;   const int kr0 = tid / KCH, kc0 = (tid % KCH) * 8, kr1 = (tid + 512) / KCH, kc1 = ((tid + 512) % KCH) * 8;
;   const bool k2 = (DQK == 96) && (tid < 256);
;   const int ksw0 = KSWZ(kr0, kc0 * 2), ksw1 = KSWZ(kr1, kc1 * 2);
;   const int vb0 = (int)(uintptr_t)V_lds + v_rd_base(lane);
;   struct { bf16x8 v, k0, k1; } sr_[2];
;     ...
;   f32x16 pA0, pA1, pB0, pB1; float mnA = 0.f, mnB = 0.f, alA = 1.f, alB = 1.f; bf16x8 pa0, pa1, pa2, pa3;
;   constexpr int SE = 0, SO = 1;
;   const bool act = (q0 + wid * 32) < L;
;   SLOAD(SE, 0); asm volatile("s_waitcnt vmcnt(0)" ::: "memory"); SWRITE(0, SE); __syncthreads();
;   if (act) { qkt<DQK>(pA0, pA1, K_lds, qr, r32, hi, 0, L); partialSM<DQK, FIX>(pA0, pA1, m_reg, mnA, alA, mC); }
.LBB0_822:
	s_ashr_i32 s19, s4, 1
	s_and_b32 s18, s4, 3
	s_and_b32 s6, s19, -2
	s_cmp_gt_u32 s18, 1
	s_mov_b64 s[2:3], -1
	s_cbranch_scc0 .LBB0_866
	v_writelane_b32 v254, s6, 61
	s_add_i32 s2, s18, s6
	s_add_i32 s4, s2, -2
	s_lshl_b64 s[2:3], s[82:83], 10
	v_readlane_b32 s5, v254, 41
	s_add_u32 s5, s5, s2
	v_readlane_b32 s2, v254, 42
	s_addc_u32 s6, s2, s3
	s_lshl_b32 s2, s4, 6
	s_ashr_i32 s3, s2, 31
	s_lshl_b64 s[2:3], s[2:3], 1
	s_add_u32 s10, s5, s2
	s_addc_u32 s11, s6, s3
	s_lshl_b64 s[6:7], s[82:83], 8
	v_readlane_b32 s2, v254, 49
	s_add_u32 s8, s2, s6
	v_readlane_b32 s2, v254, 50
	s_addc_u32 s9, s2, s7
	s_lshl_b32 s2, s4, 4
	s_andn2_b32 s2, s2, 63
	s_ashr_i32 s3, s2, 31
	s_lshl_b64 s[4:5], s[2:3], 1
	s_add_u32 s12, s8, s4
	s_addc_u32 s13, s9, s5
	v_readlane_b32 s2, v254, 43
	s_add_u32 s2, s2, s6
	v_readlane_b32 s3, v254, 44
	s_addc_u32 s3, s3, s7
	s_add_u32 s14, s2, s4
	v_mov_b32_e32 v158, v165
	s_addc_u32 s15, s3, s5
	s_lshl_b32 s2, s16, 8
	v_writelane_b32 v254, s10, 62
	v_ashrrev_i32_e32 v157, 6, v158
	v_and_b32_e32 v156, 31, v158
	v_lshl_add_u32 v154, v157, 5, s2
	v_or_b32_e32 v0, v154, v156
	s_add_i32 s2, s96, -1
	v_min_i32_e32 v2, s2, v0
	v_ashrrev_i32_e32 v3, 31, v2
	v_bfe_u32 v155, v158, 5, 1
	v_lshlrev_b64 v[2:3], 10, v[2:3]
	v_lshl_add_u64 v[4:5], s[10:11], 0, v[2:3]
	v_lshlrev_b32_e32 v2, 4, v155
	v_mov_b32_e32 v3, v1
	v_lshl_add_u64 v[4:5], v[4:5], 0, v[2:3]
	v_ashrrev_i32_e32 v18, 3, v158
	s_waitcnt lgkmcnt(0)
	s_barrier
	global_load_dwordx4 v[98:101], v[4:5], off
	global_load_dwordx4 v[102:105], v[4:5], off offset:32
	global_load_dwordx4 v[106:109], v[4:5], off offset:64
	global_load_dwordx4 v[110:113], v[4:5], off offset:96
	v_and_b32_e32 v3, 0xfffff8, v18
	v_lshlrev_b32_e32 v4, 1, v18
	v_lshlrev_b32_e32 v0, 3, v158
	v_and_or_b32 v3, v4, 0, v3
	v_and_b32_e32 v6, 56, v0
	v_lshrrev_b32_e32 v3, 1, v3
	v_bfe_u32 v0, v0, 5, 1
	v_lshrrev_b32_e32 v4, 1, v18
	v_or_b32_e32 v0, v3, v0
	v_and_b32_e32 v3, 7, v18
	v_and_or_b32 v4, v4, 0, v3
	v_lshlrev_b32_e32 v3, 4, v158
	v_and_b32_e32 v5, 48, v3
	v_lshl_or_b32 v4, v4, 6, v5
	v_lshl_or_b32 v0, v0, 9, v4
	v_ashrrev_i32_e32 v4, 31, v158
	v_lshrrev_b32_e32 v4, 29, v4
	v_add_u32_e32 v4, v158, v4
	v_ashrrev_i32_e32 v22, 3, v4
	v_and_b32_e32 v4, -8, v4
	v_sub_u32_e32 v4, v158, v4
	v_ashrrev_i32_e32 v19, 31, v18
	v_ashrrev_i32_e32 v23, 31, v22
	v_lshlrev_b32_e32 v26, 3, v4
	v_lshlrev_b32_e32 v5, 8, v22
	v_bitop3_b32 v4, v22, v4, 7 bitop3:0x6c
	v_lshlrev_b64 v[20:21], 8, v[18:19]
	v_lshlrev_b64 v[24:25], 8, v[22:23]
	v_lshl_add_u32 v12, v4, 4, v5
	v_lshl_add_u64 v[4:5], s[14:15], 0, v[20:21]
	v_lshlrev_b32_e32 v28, 1, v6
	v_mov_b32_e32 v29, v1
	v_ashrrev_i32_e32 v27, 31, v26
	v_lshl_add_u64 v[8:9], s[12:13], 0, v[24:25]
	v_lshl_add_u64 v[4:5], v[4:5], 0, v[28:29]
	v_lshl_add_u64 v[8:9], v[26:27], 1, v[8:9]
	global_load_dwordx4 v[4:7], v[4:5], off
	v_add_u32_e32 v160, 0, v0
	global_load_dwordx4 v[8:11], v[8:9], off
	s_waitcnt vmcnt(0)
	v_and_b32_e32 v0, 0x70, v3
	s_movk_i32 s2, 0x60
	v_writelane_b32 v254, s11, 63
	v_cmp_gt_i32_e64 s[8:9], s96, v154
	v_cmp_le_i32_e32 vcc, s96, v154
	v_add_u32_e32 v161, 0, v12
	v_bitop3_b32 v31, v2, v0, 32 bitop3:0x36
	v_bitop3_b32 v32, v2, v0, 64 bitop3:0x36
	v_bitop3_b32 v33, v2, v0, s2 bitop3:0x36
	s_waitcnt vmcnt(1)
	ds_write_b128 v160, v[4:7]
	s_waitcnt vmcnt(0)
	ds_write_b128 v161, v[8:11] offset:32768
	s_waitcnt lgkmcnt(0)
	s_barrier
	s_and_saveexec_b64 s[2:3], vcc
	s_xor_b64 s[2:3], exec, s[2:3]
	s_movk_i32 s10, 0x60
	v_bitop3_b32 v31, v2, v0, 32 bitop3:0x36
	v_bitop3_b32 v32, v2, v0, 64 bitop3:0x36
	v_bitop3_b32 v33, v2, v0, s10 bitop3:0x36
	s_or_saveexec_b64 s[2:3], s[2:3]
	s_movk_i32 s10, 0x70
	v_bitop3_b32 v66, v2, v3, s10 bitop3:0x78
	v_readlane_b32 s10, v254, 53
	v_readlane_b32 s11, v254, 54
	v_lshlrev_b32_e32 v30, 8, v156
	s_nop 0
	v_cndmask_b32_e64 v2, 0, 1, s[10:11]
	v_cmp_ne_u32_e64 s[10:11], 1, v2
	s_xor_b64 exec, exec, s[2:3]
	s_cbranch_execz .LBB0_829
	v_add3_u32 v29, 0, v66, v30
	ds_read_b128 v[2:5], v29 offset:32768
	ds_read_b128 v[34:37], v29 offset:40960
	v_add3_u32 v29, 0, v31, v30
	ds_read_b128 v[50:53], v29 offset:32768
	s_and_b64 vcc, exec, s[10:11]
	s_waitcnt lgkmcnt(2)
	v_mfma_f32_32x32x16_bf16 v[2:17], v[2:5], v[98:101], 0
	s_waitcnt lgkmcnt(0)
	v_mfma_f32_32x32x16_bf16 v[2:17], v[50:53], v[102:105], v[2:17]
	ds_read_b128 v[50:53], v29 offset:40960
	v_add3_u32 v29, 0, v32, v30
	v_mfma_f32_32x32x16_bf16 v[34:49], v[34:37], v[98:101], 0
	s_waitcnt lgkmcnt(0)
	v_mfma_f32_32x32x16_bf16 v[34:49], v[50:53], v[102:105], v[34:49]
	ds_read_b128 v[50:53], v29 offset:32768
	s_waitcnt lgkmcnt(0)
	v_mfma_f32_32x32x16_bf16 v[2:17], v[50:53], v[106:109], v[2:17]
	ds_read_b128 v[50:53], v29 offset:40960
	v_add3_u32 v29, 0, v33, v30
	s_waitcnt lgkmcnt(0)
	v_mfma_f32_32x32x16_bf16 v[34:49], v[50:53], v[106:109], v[34:49]
	ds_read_b128 v[50:53], v29 offset:32768
	s_waitcnt lgkmcnt(0)
	v_mfma_f32_32x32x16_bf16 v[2:17], v[50:53], v[110:113], v[2:17]
	ds_read_b128 v[50:53], v29 offset:40960
	s_waitcnt lgkmcnt(0)
	v_mfma_f32_32x32x16_bf16 v[34:49], v[50:53], v[110:113], v[34:49]
	s_cbranch_vccnz .LBB0_828
	s_nop 7
	v_sub_f32_e32 v17, v17, v174
	v_sub_f32_e32 v16, v16, v174
	v_sub_f32_e32 v15, v15, v174
	v_sub_f32_e32 v14, v14, v174
	v_sub_f32_e32 v13, v13, v174
	v_sub_f32_e32 v12, v12, v174
	v_sub_f32_e32 v11, v11, v174
	v_sub_f32_e32 v10, v10, v174
	v_sub_f32_e32 v9, v9, v174
	v_sub_f32_e32 v8, v8, v174
	v_sub_f32_e32 v7, v7, v174
	v_sub_f32_e32 v6, v6, v174
	v_sub_f32_e32 v5, v5, v174
	v_sub_f32_e32 v4, v4, v174
	v_sub_f32_e32 v3, v3, v174
	v_sub_f32_e32 v2, v2, v174
	v_sub_f32_e32 v49, v49, v174
	v_sub_f32_e32 v48, v48, v174
	v_sub_f32_e32 v47, v47, v174
	v_sub_f32_e32 v46, v46, v174
	v_sub_f32_e32 v45, v45, v174
	v_sub_f32_e32 v44, v44, v174
	v_sub_f32_e32 v43, v43, v174
	v_sub_f32_e32 v42, v42, v174
	v_sub_f32_e32 v41, v41, v174
	v_sub_f32_e32 v40, v40, v174
	v_sub_f32_e32 v39, v39, v174
	v_sub_f32_e32 v38, v38, v174
	v_sub_f32_e32 v37, v37, v174
	v_sub_f32_e32 v36, v36, v174
	v_sub_f32_e32 v35, v35, v174
	v_sub_f32_e32 v34, v34, v174

; #define SBAR() __builtin_amdgcn_sched_barrier(0)
; #define SLOAD(i, key0) do { sr_[i].v = *reinterpret_cast<const bf16x8*>(&Vh[(long)((key0) + vr) * ldv + vc]); \
;     sr_[i].k0 = *reinterpret_cast<const bf16x8*>(&Kh[(long)((key0) + kr0) * ldk + kc0]); \
;     if (k2) sr_[i].k1 = *reinterpret_cast<const bf16x8*>(&Kh[(long)((key0) + kr1) * ldk + kc1]); } while (0)
; #define SWRITE(b, i) do { *(bf16x8*)((char*)V_lds + (b) * SHM_V + vst) = sr_[i].v; \
;     *(bf16x8*)((char*)K_lds + (b) * SHM_K + ksw0) = sr_[i].k0; \
;     if (k2) *(bf16x8*)((char*)K_lds + (b) * SHM_K + ksw1) = sr_[i].k1; } while (0)
; __device__ __forceinline__ void finishSM(f32x16& p0, f32x16& p1, float alpha, float& l_reg, bf16x8& pa0, bf16x8& pa1, bf16x8& pa2, bf16x8& pa3) {
; #pragma unroll
;   for (int r = 0; r < 16; ++r) p1[r] = __builtin_amdgcn_exp2f(p1[r]);
;   float ps = 0;
; #pragma unroll
;   for (int r = 0; r < 16; ++r) ps += p0[r];
; #pragma unroll
;   for (int r = 0; r < 16; ++r) ps += p1[r];
;   { auto rr = __builtin_amdgcn_permlane32_swap(__float_as_uint(ps), __float_as_uint(ps), false, false);
;     ps = __uint_as_float(rr[0]) + __uint_as_float(rr[1]); }
;   l_reg = l_reg * alpha + ps;
;     ...
;   PK4(p0, 0, pa0); PK4(p0, 8, pa1); PK4(p1, 0, pa2); PK4(p1, 8, pa3);
;     ...
; }
; template <int DQK, bool FIX>
; __device__ __forceinline__ void attn_item(const bf16* Qb, const bf16* __restrict__ Kh, const bf16* __restrict__ Vh,
;                                           u16* Ob, int q0, int L, int NT, char* lds, float mC) {
;     ...
;   for (int j = 1; j + 1 < NT; j += 2) {
;     if (act) { SBAR(); qkt<DQK>(pB0, pB1, (bf16*)((char*)K_lds + SHM_K), qr, r32, hi, j * KVBLK, L);
;       finishSM(pA0, pA1, alA, l_reg, pa0, pa1, pa2, pa3); SBAR(); }
;     SLOAD(SO, (j + 2) * KVBLK); SBAR();
;     if (act) { pv_d0(o, vb0, pa0, pa1, pa2, pa3); partialSM<DQK, FIX>(pB0, pB1, m_reg, mnB, alB, mC); }
;     __syncthreads(); SWAIT(); SWRITE(0, SE);
;     if (act) { RESC(alB); } __syncthreads();
;     if (act) { SBAR(); qkt<DQK>(pA0, pA1, K_lds, qr, r32, hi, (j + 1) * KVBLK, L);
;       finishSM(pB0, pB1, alB, l_reg, pa0, pa1, pa2, pa3); SBAR(); }
;     if (j + 3 < NT) SLOAD(SE, (j + 3) * KVBLK); SBAR();
;     if (act) { pv_d0(o, vb0 + (int)SHM_V, pa0, pa1, pa2, pa3); partialSM<DQK, FIX>(pA0, pA1, m_reg, mnA, alA, mC); }
;     __syncthreads(); SWAIT(); SWRITE(1, SO);
;     if (act) { RESC(alA); } __syncthreads();
.LBB0_831:
	s_or_b64 exec, exec, s[6:7]
	s_barrier
	s_waitcnt vmcnt(2)
	s_mov_b64 s[6:7], 0x8000
	s_addk_i32 s78, 0x80
	v_lshl_add_u64 v[146:147], v[146:147], 0, s[6:7]
	v_lshl_add_u64 v[148:149], v[148:149], 0, s[6:7]
	s_add_i32 s73, s73, 2
	s_and_b64 vcc, exec, s[2:3]
	s_cbranch_vccz .Lt64b_w
	s_waitcnt vmcnt(0)
.Lt64b_w:
	ds_write_b128 v160, v[122:125] offset:16384
	ds_write_b128 v161, v[126:129] offset:49152
	s_waitcnt lgkmcnt(0)
	s_barrier
	s_cbranch_vccnz .LBB0_853
.LBB0_832:
	s_and_saveexec_b64 s[2:3], s[8:9]
	s_cbranch_execz .LBB0_838
	s_add_i32 s6, s78, 64
	s_cmp_le_u32 s6, s79
	s_cbranch_scc0 .Lslow64a
	s_and_b64 vcc, exec, s[10:11]
	s_cbranch_vccz .Lslow64a
	ds_read_b128 v[222:225], v167 offset:49152
	ds_read_b128 v[226:229], v168 offset:49152
	ds_read_b128 v[230:233], v167 offset:57344
	ds_read_b128 v[234:237], v168 offset:57344
	ds_read_b128 v[238:241], v169 offset:49152
	ds_read_b128 v[242:245], v169 offset:57344
	ds_read_b128 v[246:249], v171 offset:49152
	ds_read_b128 v[250:253], v171 offset:57344
	v_cvt_pk_bf16_f32 v130, v50, v51
	v_cvt_pk_bf16_f32 v131, v52, v53
	v_cvt_pk_bf16_f32 v132, v54, v55
	v_cvt_pk_bf16_f32 v133, v56, v57
	v_cvt_pk_bf16_f32 v134, v58, v59
	v_cvt_pk_bf16_f32 v135, v60, v61
	v_cvt_pk_bf16_f32 v136, v62, v63
	v_cvt_pk_bf16_f32 v137, v64, v65
	s_waitcnt lgkmcnt(7)
	v_mfma_f32_32x32x16_bf16 v[66:81], v[222:225], v[98:101], 0
	ds_read_b64_tr_b16 v[186:187], v166 offset:0
	ds_read_b64_tr_b16 v[188:189], v166 offset:2048
	ds_read_b64_tr_b16 v[190:191], v166 offset:4096
	ds_read_b64_tr_b16 v[192:193], v166 offset:6144
	v_exp_f32_e32 v34, v34
	v_exp_f32_e32 v35, v35
	v_exp_f32_e32 v36, v36
	s_waitcnt lgkmcnt(10)
	v_mfma_f32_32x32x16_bf16 v[66:81], v[226:229], v[102:105], v[66:81]
	ds_read_b64_tr_b16 v[194:195], v166 offset:8192
	ds_read_b64_tr_b16 v[196:197], v166 offset:10240
	ds_read_b64_tr_b16 v[198:199], v166 offset:12288
	ds_read_b64_tr_b16 v[200:201], v166 offset:14336
	v_exp_f32_e32 v37, v37
	v_exp_f32_e32 v38, v38
	v_exp_f32_e32 v39, v39
	s_waitcnt lgkmcnt(13)
	v_mfma_f32_32x32x16_bf16 v[82:97], v[230:233], v[98:101], 0
	v_exp_f32_e32 v40, v40
	v_exp_f32_e32 v41, v41
	v_exp_f32_e32 v42, v42
	s_waitcnt lgkmcnt(12)
	v_mfma_f32_32x32x16_bf16 v[82:97], v[234:237], v[102:105], v[82:97]
	v_exp_f32_e32 v43, v43
	v_exp_f32_e32 v44, v44
	v_exp_f32_e32 v45, v45
	s_waitcnt lgkmcnt(11)
	v_mfma_f32_32x32x16_bf16 v[66:81], v[238:241], v[106:109], v[66:81]
	v_exp_f32_e32 v46, v46
	v_exp_f32_e32 v47, v47
	v_exp_f32_e32 v48, v48
	s_waitcnt lgkmcnt(10)
	v_mfma_f32_32x32x16_bf16 v[82:97], v[242:245], v[106:109], v[82:97]
	ds_read_b64_tr_b16 v[222:223], v166 offset:512
	ds_read_b64_tr_b16 v[224:225], v166 offset:2560
	ds_read_b64_tr_b16 v[226:227], v166 offset:4608
	ds_read_b64_tr_b16 v[228:229], v166 offset:6656
	v_exp_f32_e32 v49, v49
	v_cvt_pk_bf16_f32 v138, v34, v35
	v_cvt_pk_bf16_f32 v139, v36, v37
	v_cvt_pk_bf16_f32 v140, v38, v39
	s_waitcnt lgkmcnt(13)
	v_mfma_f32_32x32x16_bf16 v[66:81], v[246:249], v[110:113], v[66:81]
	v_cvt_pk_bf16_f32 v141, v40, v41
	v_cvt_pk_bf16_f32 v142, v42, v43
	v_cvt_pk_bf16_f32 v143, v44, v45
	v_cvt_pk_bf16_f32 v144, v46, v47
	s_waitcnt lgkmcnt(12)
	v_mfma_f32_32x32x16_bf16 v[82:97], v[250:253], v[110:113], v[82:97]
	ds_read_b64_tr_b16 v[230:231], v166 offset:8704
	ds_read_b64_tr_b16 v[232:233], v166 offset:10752
	ds_read_b64_tr_b16 v[234:235], v166 offset:12800
	s_waitcnt lgkmcnt(14)
	ds_read_b64_tr_b16 v[236:237], v166 offset:14848
	v_cvt_pk_bf16_f32 v145, v48, v49
	s_or_b64 exec, exec, s[2:3]
	v_lshl_add_u64 v[152:153], v[148:149], 0, s[4:5]
	v_add_co_u32_e32 v122, vcc, 0x2ced0000, v152
	v_lshl_add_u64 v[150:151], v[146:147], 0, s[4:5]
	s_nop 0
	v_addc_co_u32_e32 v123, vcc, 0, v153, vcc
	v_add_co_u32_e32 v126, vcc, 0x119cc000, v150
	global_load_dwordx4 v[122:125], v[122:123], off offset:2048
	s_nop 0
	v_addc_co_u32_e32 v127, vcc, 0, v151, vcc
	global_load_dwordx4 v[126:129], v[126:127], off
	s_and_saveexec_b64 s[2:3], s[8:9]
	s_waitcnt lgkmcnt(14)
	v_mfma_f32_32x32x16_bf16 v[2:17], v[130:133], v[186:189], v[2:17]
	v_add_f32_e32 v252, 0, v50
	v_add_f32_e32 v252, v51, v252
	v_add_f32_e32 v252, v52, v252
	v_add_f32_e32 v252, v53, v252
	v_exp_f32_e32 v66, v66
	v_exp_f32_e32 v67, v67
	s_waitcnt lgkmcnt(12)
	v_mfma_f32_32x32x16_bf16 v[2:17], v[134:137], v[190:193], v[2:17]
	v_add_f32_e32 v252, v54, v252
	v_add_f32_e32 v252, v55, v252
	v_add_f32_e32 v252, v56, v252
	v_add_f32_e32 v252, v57, v252
	v_exp_f32_e32 v68, v68
	v_exp_f32_e32 v69, v69
	s_waitcnt lgkmcnt(10)
	v_mfma_f32_32x32x16_bf16 v[2:17], v[138:141], v[194:197], v[2:17]
	v_add_f32_e32 v252, v58, v252
	v_add_f32_e32 v252, v59, v252
	v_add_f32_e32 v252, v60, v252
	v_add_f32_e32 v252, v61, v252
	v_exp_f32_e32 v70, v70
	v_exp_f32_e32 v71, v71
	s_waitcnt lgkmcnt(8)
	v_mfma_f32_32x32x16_bf16 v[2:17], v[142:145], v[198:201], v[2:17]
	v_add_f32_e32 v252, v62, v252
	v_add_f32_e32 v252, v63, v252
	v_add_f32_e32 v252, v64, v252
	v_add_f32_e32 v252, v65, v252
	v_exp_f32_e32 v72, v72
	v_exp_f32_e32 v73, v73
	s_waitcnt lgkmcnt(6)
	v_mfma_f32_32x32x16_bf16 v[18:33], v[130:133], v[222:225], v[18:33]
	v_add_f32_e32 v252, v34, v252
	v_add_f32_e32 v252, v35, v252
	v_add_f32_e32 v252, v36, v252
	v_add_f32_e32 v252, v37, v252
	v_exp_f32_e32 v74, v74
	v_exp_f32_e32 v75, v75
	s_waitcnt lgkmcnt(4)
	v_mfma_f32_32x32x16_bf16 v[18:33], v[134:137], v[226:229], v[18:33]
	v_add_f32_e32 v252, v38, v252
	v_add_f32_e32 v252, v39, v252
	v_add_f32_e32 v252, v40, v252
	v_add_f32_e32 v252, v41, v252
	v_exp_f32_e32 v76, v76
	v_exp_f32_e32 v77, v77
	s_waitcnt lgkmcnt(2)
	v_mfma_f32_32x32x16_bf16 v[18:33], v[138:141], v[230:233], v[18:33]
	v_add_f32_e32 v252, v42, v252
	v_add_f32_e32 v252, v43, v252
	v_add_f32_e32 v252, v44, v252
	v_add_f32_e32 v252, v45, v252
	v_exp_f32_e32 v78, v78
	v_exp_f32_e32 v79, v79
	s_waitcnt lgkmcnt(0)
	v_mfma_f32_32x32x16_bf16 v[18:33], v[142:145], v[234:237], v[18:33]
	v_add_f32_e32 v252, v46, v252
	v_add_f32_e32 v252, v47, v252
	v_add_f32_e32 v252, v48, v252
	v_add_f32_e32 v252, v49, v252
	v_exp_f32_e32 v80, v80
	v_exp_f32_e32 v81, v81
	v_mov_b32_e32 v253, v252
	s_nop 1
	v_permlane32_swap_b32_e32 v252, v253
	v_add_f32_e32 v252, v252, v253
	v_add_f32_e32 v163, v163, v252
	s_branch .LBB0_842

; __device__ __forceinline__ void finishSM(f32x16& p0, f32x16& p1, float alpha, float& l_reg, bf16x8& pa0, bf16x8& pa1, bf16x8& pa2, bf16x8& pa3) {
; #pragma unroll
;   for (int r = 0; r < 16; ++r) p1[r] = __builtin_amdgcn_exp2f(p1[r]);
;   float ps = 0;
; #pragma unroll
;   for (int r = 0; r < 16; ++r) ps += p0[r];
; #pragma unroll
;   for (int r = 0; r < 16; ++r) ps += p1[r];
;   { auto rr = __builtin_amdgcn_permlane32_swap(__float_as_uint(ps), __float_as_uint(ps), false, false);
;     ps = __uint_as_float(rr[0]) + __uint_as_float(rr[1]); }
;   l_reg = l_reg * alpha + ps;
;     ...
;   PK4(p0, 0, pa0); PK4(p0, 8, pa1); PK4(p1, 0, pa2); PK4(p1, 8, pa3);
;     ...
; }
; template <int DQK>
; __device__ __forceinline__ void qkt(f32x16& p0, f32x16& p1, const bf16* Ks, const bf16x8* qr, int r32, int hi, int k0, int L) {
;   p0 = f32x16{}; p1 = f32x16{};
; #pragma unroll
;   for (int d0 = 0; d0 < DQK / 16; ++d0) { int cb = (d0 * 16 + hi * 8) * 2;
;     bf16x8 b0 = *reinterpret_cast<const bf16x8*>((const char*)Ks + KSWZ(r32, cb));
;     bf16x8 b1 = *reinterpret_cast<const bf16x8*>((const char*)Ks + KSWZ(32 + r32, cb));
;     p0 = __builtin_amdgcn_mfma_f32_32x32x16_bf16(b0, qr[d0], p0, 0, 0, 0);
;     p1 = __builtin_amdgcn_mfma_f32_32x32x16_bf16(b1, qr[d0], p1, 0, 0, 0); }
;   if (k0 + KVBLK > L) {
; #pragma unroll
;     for (int r = 0; r < 16; ++r) { const int key = k0 + crow(r, hi);
;       if (key >= L) p0[r] = -1e30f;
;       if (key + 32 >= L) p1[r] = -1e30f; }
;   }
; }
; __device__ __forceinline__ int v_st(int k, int c) { const int kk = (k & ~0xC) | ((k & 4) << 1) | ((k & 8) >> 1); return ((kk >> 3) * 4 + (c >> 5)) * 512 + ((kk & 7) * 32 + (c & 31)) * 2; }
; __device__ __forceinline__ int v_rd_base(int lane) { return ((lane & 3) << 3) | (((lane >> 2) & 3) << 6) | (((lane >> 4) & 1) << 5) | (((lane >> 5) & 1) << 8); }
; template <int OFF> __device__ __forceinline__ s16x4 tr_read(int vb) {
;   s16x4 r; asm volatile("ds_read_b64_tr_b16 %0, %1 offset:%2" : "=&v"(r) : "v"(vb), "i"(OFF) : "memory"); return r;
; }
; template <int D0> __device__ __forceinline__ void pv_one(f32x16& od, int vb, bf16x8 pa0, bf16x8 pa1, bf16x8 pa2, bf16x8 pa3) {
;   const s16x4 l0 = tr_read<v_rd_off(D0, 0, 0)>(vb), h0 = tr_read<v_rd_off(D0, 0, 1)>(vb), l1 = tr_read<v_rd_off(D0, 1, 0)>(vb), h1 = tr_read<v_rd_off(D0, 1, 1)>(vb);
.LBB0_837:
	v_add_f32_e32 v122, 0, v50
	v_add_f32_e32 v122, v51, v122
	v_add_f32_e32 v122, v52, v122
	v_add_f32_e32 v122, v53, v122
	v_add_f32_e32 v122, v54, v122
	v_add_f32_e32 v122, v55, v122
	v_add_f32_e32 v122, v56, v122
	v_add_f32_e32 v122, v57, v122
	v_add_f32_e32 v122, v58, v122
	v_add_f32_e32 v122, v59, v122
	v_add_f32_e32 v122, v60, v122
	v_add_f32_e32 v122, v61, v122
	v_exp_f32_e32 v34, v34
	v_add_f32_e32 v122, v62, v122
	v_exp_f32_e32 v35, v35
	v_add_f32_e32 v122, v63, v122
	v_exp_f32_e32 v36, v36
	v_add_f32_e32 v122, v64, v122
	v_exp_f32_e32 v37, v37
	v_add_f32_e32 v122, v65, v122
	v_exp_f32_e32 v38, v38
	v_add_f32_e32 v122, v34, v122
	v_exp_f32_e32 v39, v39
	v_add_f32_e32 v122, v35, v122
	v_exp_f32_e32 v40, v40
	v_add_f32_e32 v122, v36, v122
	v_exp_f32_e32 v41, v41
	v_add_f32_e32 v122, v37, v122
	v_exp_f32_e32 v42, v42
	v_add_f32_e32 v122, v38, v122
	v_exp_f32_e32 v43, v43
	v_add_f32_e32 v122, v39, v122
	v_exp_f32_e32 v44, v44
	v_add_f32_e32 v122, v40, v122
	v_exp_f32_e32 v45, v45
	v_add_f32_e32 v122, v41, v122
	v_exp_f32_e32 v46, v46
	v_add_f32_e32 v122, v42, v122
	v_exp_f32_e32 v47, v47
	v_add_f32_e32 v122, v43, v122
	v_exp_f32_e32 v48, v48
	v_add_f32_e32 v122, v44, v122
	v_exp_f32_e32 v49, v49
	v_add_f32_e32 v122, v45, v122
	v_add_f32_e32 v122, v46, v122
	v_add_f32_e32 v122, v47, v122
	v_add_f32_e32 v122, v48, v122
	v_add_f32_e32 v122, v49, v122
	v_mov_b32_e32 v123, v122
	s_nop 1
	v_permlane32_swap_b32_e32 v122, v123
	v_add_f32_e32 v122, v122, v123
	v_cvt_pk_bf16_f32 v130, v50, v51
	v_cvt_pk_bf16_f32 v131, v52, v53
	v_cvt_pk_bf16_f32 v132, v54, v55
	v_cvt_pk_bf16_f32 v133, v56, v57
	v_cvt_pk_bf16_f32 v134, v58, v59
	v_cvt_pk_bf16_f32 v135, v60, v61
	v_cvt_pk_bf16_f32 v136, v62, v63
	v_cvt_pk_bf16_f32 v137, v64, v65
	v_cvt_pk_bf16_f32 v138, v34, v35
	v_cvt_pk_bf16_f32 v139, v36, v37
	v_cvt_pk_bf16_f32 v140, v38, v39
	v_cvt_pk_bf16_f32 v141, v40, v41
	v_cvt_pk_bf16_f32 v142, v42, v43
	v_cvt_pk_bf16_f32 v143, v44, v45
	v_cvt_pk_bf16_f32 v144, v46, v47
	v_cvt_pk_bf16_f32 v145, v48, v49
	v_add_f32_e32 v163, v163, v122
.LBB0_838:
	s_or_b64 exec, exec, s[2:3]
	v_lshl_add_u64 v[152:153], v[148:149], 0, s[4:5]
	v_add_co_u32_e32 v122, vcc, 0x2ced0000, v152
	v_lshl_add_u64 v[150:151], v[146:147], 0, s[4:5]
	s_nop 0
	v_addc_co_u32_e32 v123, vcc, 0, v153, vcc
	v_add_co_u32_e32 v126, vcc, 0x119cc000, v150
	global_load_dwordx4 v[122:125], v[122:123], off offset:2048
	s_nop 0
	v_addc_co_u32_e32 v127, vcc, 0, v151, vcc
	global_load_dwordx4 v[126:129], v[126:127], off
	s_and_saveexec_b64 s[2:3], s[8:9]
	s_cbranch_execz .LBB0_842
	ds_read_b64_tr_b16 v[186:187], v166 offset:0
	ds_read_b64_tr_b16 v[188:189], v166 offset:0x800
	ds_read_b64_tr_b16 v[190:191], v166 offset:0x1000
	ds_read_b64_tr_b16 v[192:193], v166 offset:0x1800
	ds_read_b64_tr_b16 v[194:195], v166 offset:0x2000
	ds_read_b64_tr_b16 v[196:197], v166 offset:0x2800
	ds_read_b64_tr_b16 v[198:199], v166 offset:0x3000
	ds_read_b64_tr_b16 v[200:201], v166 offset:0x3800
	s_waitcnt lgkmcnt(0)
	s_nop 0
	v_mfma_f32_32x32x16_bf16 v[2:17], v[130:133], v[186:189], v[2:17]
	ds_read_b64_tr_b16 v[186:187], v166 offset:0x200
	ds_read_b64_tr_b16 v[188:189], v166 offset:0xa00
	v_mfma_f32_32x32x16_bf16 v[2:17], v[134:137], v[190:193], v[2:17]
	ds_read_b64_tr_b16 v[190:191], v166 offset:0x1200
	ds_read_b64_tr_b16 v[192:193], v166 offset:0x1a00
	v_mfma_f32_32x32x16_bf16 v[2:17], v[138:141], v[194:197], v[2:17]
	ds_read_b64_tr_b16 v[194:195], v166 offset:0x2200
	ds_read_b64_tr_b16 v[196:197], v166 offset:0x2a00
	v_mfma_f32_32x32x16_bf16 v[2:17], v[142:145], v[198:201], v[2:17]
	ds_read_b64_tr_b16 v[198:199], v166 offset:0x3200
	ds_read_b64_tr_b16 v[200:201], v166 offset:0x3a00
	s_waitcnt lgkmcnt(0)
	v_mfma_f32_32x32x16_bf16 v[18:33], v[130:133], v[186:189], v[18:33]
	s_and_b64 vcc, exec, s[10:11]
	v_mfma_f32_32x32x16_bf16 v[18:33], v[134:137], v[190:193], v[18:33]
	v_mfma_f32_32x32x16_bf16 v[18:33], v[138:141], v[194:197], v[18:33]
	v_mfma_f32_32x32x16_bf16 v[18:33], v[142:145], v[198:201], v[18:33]
	s_cbranch_vccnz .LBB0_841
	v_sub_f32_e32 v81, v81, v174
	v_sub_f32_e32 v80, v80, v174
	v_sub_f32_e32 v79, v79, v174
	v_sub_f32_e32 v78, v78, v174
	v_sub_f32_e32 v77, v77, v174
	v_sub_f32_e32 v76, v76, v174
	v_sub_f32_e32 v75, v75, v174
	v_sub_f32_e32 v74, v74, v174
	v_sub_f32_e32 v73, v73, v174
	v_sub_f32_e32 v72, v72, v174
	v_sub_f32_e32 v71, v71, v174
	v_sub_f32_e32 v70, v70, v174
	v_sub_f32_e32 v69, v69, v174
	v_sub_f32_e32 v68, v68, v174
	v_sub_f32_e32 v67, v67, v174
	v_sub_f32_e32 v66, v66, v174
	v_sub_f32_e32 v97, v97, v174
	v_sub_f32_e32 v96, v96, v174
	v_sub_f32_e32 v95, v95, v174
	v_sub_f32_e32 v94, v94, v174
	v_sub_f32_e32 v93, v93, v174
	v_sub_f32_e32 v92, v92, v174
	v_sub_f32_e32 v91, v91, v174
	v_sub_f32_e32 v90, v90, v174
	v_sub_f32_e32 v89, v89, v174
	v_sub_f32_e32 v88, v88, v174
	v_sub_f32_e32 v87, v87, v174
	v_sub_f32_e32 v86, v86, v174
	v_sub_f32_e32 v85, v85, v174
	v_sub_f32_e32 v84, v84, v174
	v_sub_f32_e32 v83, v83, v174
	v_sub_f32_e32 v82, v82, v174

; #define SBAR() __builtin_amdgcn_sched_barrier(0)
; #define SLOAD(i, key0) do { sr_[i].v = *reinterpret_cast<const bf16x8*>(&Vh[(long)((key0) + vr) * ldv + vc]); \
;     sr_[i].k0 = *reinterpret_cast<const bf16x8*>(&Kh[(long)((key0) + kr0) * ldk + kc0]); \
;     if (k2) sr_[i].k1 = *reinterpret_cast<const bf16x8*>(&Kh[(long)((key0) + kr1) * ldk + kc1]); } while (0)
; #define SWAIT() asm volatile("s_waitcnt vmcnt(2)" ::: "memory")
; __device__ __forceinline__ void finishSM(f32x16& p0, f32x16& p1, float alpha, float& l_reg, bf16x8& pa0, bf16x8& pa1, bf16x8& pa2, bf16x8& pa3) {
; #pragma unroll
;   for (int r = 0; r < 16; ++r) p1[r] = __builtin_amdgcn_exp2f(p1[r]);
;   float ps = 0;
; #pragma unroll
;   for (int r = 0; r < 16; ++r) ps += p0[r];
; #pragma unroll
;   for (int r = 0; r < 16; ++r) ps += p1[r];
;   { auto rr = __builtin_amdgcn_permlane32_swap(__float_as_uint(ps), __float_as_uint(ps), false, false);
;     ps = __uint_as_float(rr[0]) + __uint_as_float(rr[1]); }
;   l_reg = l_reg * alpha + ps;
;     ...
;   PK4(p0, 0, pa0); PK4(p0, 8, pa1); PK4(p1, 0, pa2); PK4(p1, 8, pa3);
;     ...
; }
; template <int DQK>
; __device__ __forceinline__ void qkt(f32x16& p0, f32x16& p1, const bf16* Ks, const bf16x8* qr, int r32, int hi, int k0, int L) {
;   p0 = f32x16{}; p1 = f32x16{};
; #pragma unroll
;   for (int d0 = 0; d0 < DQK / 16; ++d0) { int cb = (d0 * 16 + hi * 8) * 2;
;     bf16x8 b0 = *reinterpret_cast<const bf16x8*>((const char*)Ks + KSWZ(r32, cb));
;     bf16x8 b1 = *reinterpret_cast<const bf16x8*>((const char*)Ks + KSWZ(32 + r32, cb));
;     p0 = __builtin_amdgcn_mfma_f32_32x32x16_bf16(b0, qr[d0], p0, 0, 0, 0);
;     p1 = __builtin_amdgcn_mfma_f32_32x32x16_bf16(b1, qr[d0], p1, 0, 0, 0); }
; template <int DQK, bool FIX>
; __device__ __forceinline__ void attn_item(const bf16* Qb, const bf16* __restrict__ Kh, const bf16* __restrict__ Vh,
;                                           u16* Ob, int q0, int L, int NT, char* lds, float mC) {
;     ...
;     __syncthreads(); SWAIT(); SWRITE(0, SE);
;     if (act) { RESC(alB); } __syncthreads();
;     if (act) { SBAR(); qkt<DQK>(pA0, pA1, K_lds, qr, r32, hi, (j + 1) * KVBLK, L);
;       finishSM(pB0, pB1, alB, l_reg, pa0, pa1, pa2, pa3); SBAR(); }
;     if (j + 3 < NT) SLOAD(SE, (j + 3) * KVBLK); SBAR();
.LBB0_842:
	s_or_b64 exec, exec, s[2:3]
	s_barrier
	s_waitcnt vmcnt(2)
	s_waitcnt vmcnt(2)
	ds_write_b128 v160, v[114:117]
	ds_write_b128 v161, v[118:121] offset:32768
	s_waitcnt lgkmcnt(0)
	s_barrier
	s_and_saveexec_b64 s[2:3], s[8:9]
	s_cbranch_execz .LBB0_848
	s_add_i32 s6, s78, 0x80
	s_cmp_le_u32 s6, s79
	s_cbranch_scc0 .Lslow64b
	s_and_b64 vcc, exec, s[10:11]
	s_cbranch_vccz .Lslow64b
	ds_read_b128 v[222:225], v167 offset:32768
	ds_read_b128 v[226:229], v168 offset:32768
	ds_read_b128 v[230:233], v167 offset:40960
	ds_read_b128 v[234:237], v168 offset:40960
	ds_read_b128 v[238:241], v169 offset:32768
	ds_read_b128 v[242:245], v169 offset:40960
	ds_read_b128 v[246:249], v171 offset:32768
	ds_read_b128 v[250:253], v171 offset:40960
	v_cvt_pk_bf16_f32 v130, v66, v67
	v_cvt_pk_bf16_f32 v131, v68, v69
	v_cvt_pk_bf16_f32 v132, v70, v71
	v_cvt_pk_bf16_f32 v133, v72, v73
	v_cvt_pk_bf16_f32 v134, v74, v75
	v_cvt_pk_bf16_f32 v135, v76, v77
	v_cvt_pk_bf16_f32 v136, v78, v79
	v_cvt_pk_bf16_f32 v137, v80, v81
	s_waitcnt lgkmcnt(7)
	v_mfma_f32_32x32x16_bf16 v[50:65], v[222:225], v[98:101], 0
	ds_read_b64_tr_b16 v[186:187], v170 offset:0
	ds_read_b64_tr_b16 v[188:189], v170 offset:2048
	ds_read_b64_tr_b16 v[190:191], v170 offset:4096
	ds_read_b64_tr_b16 v[192:193], v170 offset:6144
	v_exp_f32_e32 v82, v82
	v_exp_f32_e32 v83, v83
	v_exp_f32_e32 v84, v84
	s_waitcnt lgkmcnt(10)
	v_mfma_f32_32x32x16_bf16 v[50:65], v[226:229], v[102:105], v[50:65]
	ds_read_b64_tr_b16 v[194:195], v170 offset:8192
	ds_read_b64_tr_b16 v[196:197], v170 offset:10240
	ds_read_b64_tr_b16 v[198:199], v170 offset:12288
	ds_read_b64_tr_b16 v[200:201], v170 offset:14336
	v_exp_f32_e32 v85, v85
	v_exp_f32_e32 v86, v86
	v_exp_f32_e32 v87, v87
	s_waitcnt lgkmcnt(13)
	v_mfma_f32_32x32x16_bf16 v[34:49], v[230:233], v[98:101], 0
	v_exp_f32_e32 v88, v88
	v_exp_f32_e32 v89, v89
	v_exp_f32_e32 v90, v90
	s_waitcnt lgkmcnt(12)
	v_mfma_f32_32x32x16_bf16 v[34:49], v[234:237], v[102:105], v[34:49]
	v_exp_f32_e32 v91, v91
	v_exp_f32_e32 v92, v92
	v_exp_f32_e32 v93, v93
	s_waitcnt lgkmcnt(11)
	v_mfma_f32_32x32x16_bf16 v[50:65], v[238:241], v[106:109], v[50:65]
	v_exp_f32_e32 v94, v94
	v_exp_f32_e32 v95, v95
	v_exp_f32_e32 v96, v96
	s_waitcnt lgkmcnt(10)
	v_mfma_f32_32x32x16_bf16 v[34:49], v[242:245], v[106:109], v[34:49]
	ds_read_b64_tr_b16 v[222:223], v170 offset:512
	ds_read_b64_tr_b16 v[224:225], v170 offset:2560
	ds_read_b64_tr_b16 v[226:227], v170 offset:4608
	ds_read_b64_tr_b16 v[228:229], v170 offset:6656
	v_exp_f32_e32 v97, v97
	v_cvt_pk_bf16_f32 v138, v82, v83
	v_cvt_pk_bf16_f32 v139, v84, v85
	v_cvt_pk_bf16_f32 v140, v86, v87
	s_waitcnt lgkmcnt(13)
	v_mfma_f32_32x32x16_bf16 v[50:65], v[246:249], v[110:113], v[50:65]
	v_cvt_pk_bf16_f32 v141, v88, v89
	v_cvt_pk_bf16_f32 v142, v90, v91
	v_cvt_pk_bf16_f32 v143, v92, v93
	v_cvt_pk_bf16_f32 v144, v94, v95
	s_waitcnt lgkmcnt(12)
	v_mfma_f32_32x32x16_bf16 v[34:49], v[250:253], v[110:113], v[34:49]
	ds_read_b64_tr_b16 v[230:231], v170 offset:8704
	ds_read_b64_tr_b16 v[232:233], v170 offset:10752
	ds_read_b64_tr_b16 v[234:235], v170 offset:12800
	s_waitcnt lgkmcnt(14)
	ds_read_b64_tr_b16 v[236:237], v170 offset:14848
	v_cvt_pk_bf16_f32 v145, v96, v97
	s_or_b64 exec, exec, s[2:3]
	s_cmp_ge_u32 s73, s97
	s_cselect_b64 s[2:3], -1, 0
	s_and_b64 vcc, exec, s[2:3]
	s_cbranch_vccnz .Lfast64b_nl
	v_add_co_u32_e32 v114, vcc, 0x2ced4000, v152
	s_nop 1
	v_addc_co_u32_e32 v115, vcc, 0, v153, vcc
	v_add_co_u32_e32 v118, vcc, 0x119d0000, v150
	global_load_dwordx4 v[114:117], v[114:115], off offset:2048
	s_nop 0
	v_addc_co_u32_e32 v119, vcc, 0, v151, vcc
	global_load_dwordx4 v[118:121], v[118:119], off

; #define SBAR() __builtin_amdgcn_sched_barrier(0)
; #define SLOAD(i, key0) do { sr_[i].v = *reinterpret_cast<const bf16x8*>(&Vh[(long)((key0) + vr) * ldv + vc]); \
;     sr_[i].k0 = *reinterpret_cast<const bf16x8*>(&Kh[(long)((key0) + kr0) * ldk + kc0]); \
;     if (k2) sr_[i].k1 = *reinterpret_cast<const bf16x8*>(&Kh[(long)((key0) + kr1) * ldk + kc1]); } while (0)
; __device__ __forceinline__ void finishSM(f32x16& p0, f32x16& p1, float alpha, float& l_reg, bf16x8& pa0, bf16x8& pa1, bf16x8& pa2, bf16x8& pa3) {
; #pragma unroll
;   for (int r = 0; r < 16; ++r) p1[r] = __builtin_amdgcn_exp2f(p1[r]);
;   float ps = 0;
; #pragma unroll
;   for (int r = 0; r < 16; ++r) ps += p0[r];
; #pragma unroll
;   for (int r = 0; r < 16; ++r) ps += p1[r];
;   { auto rr = __builtin_amdgcn_permlane32_swap(__float_as_uint(ps), __float_as_uint(ps), false, false);
;     ps = __uint_as_float(rr[0]) + __uint_as_float(rr[1]); }
;   l_reg = l_reg * alpha + ps;
;     ...
;   PK4(p0, 0, pa0); PK4(p0, 8, pa1); PK4(p1, 0, pa2); PK4(p1, 8, pa3);
; template <int DQK, bool FIX>
; __device__ __forceinline__ void attn_item(const bf16* Qb, const bf16* __restrict__ Kh, const bf16* __restrict__ Vh,
;                                           u16* Ob, int q0, int L, int NT, char* lds, float mC) {
;     ...
;     if (act) { SBAR(); qkt<DQK>(pA0, pA1, K_lds, qr, r32, hi, (j + 1) * KVBLK, L);
;       finishSM(pB0, pB1, alB, l_reg, pa0, pa1, pa2, pa3); SBAR(); }
;     if (j + 3 < NT) SLOAD(SE, (j + 3) * KVBLK); SBAR();
.LBB0_847:
	v_add_f32_e32 v130, 0, v66
	v_add_f32_e32 v130, v67, v130
	v_add_f32_e32 v130, v68, v130
	v_add_f32_e32 v130, v69, v130
	v_add_f32_e32 v130, v70, v130
	v_add_f32_e32 v130, v71, v130
	v_add_f32_e32 v130, v72, v130
	v_add_f32_e32 v130, v73, v130
	v_add_f32_e32 v130, v74, v130
	v_add_f32_e32 v130, v75, v130
	v_add_f32_e32 v130, v76, v130
	v_add_f32_e32 v130, v77, v130
	v_exp_f32_e32 v82, v82
	v_add_f32_e32 v130, v78, v130
	v_exp_f32_e32 v83, v83
	v_add_f32_e32 v130, v79, v130
	v_exp_f32_e32 v84, v84
	v_add_f32_e32 v130, v80, v130
	v_exp_f32_e32 v85, v85
	v_add_f32_e32 v130, v81, v130
	v_exp_f32_e32 v86, v86
	v_add_f32_e32 v130, v82, v130
	v_exp_f32_e32 v87, v87
	v_add_f32_e32 v130, v83, v130
	v_exp_f32_e32 v88, v88
	v_add_f32_e32 v130, v84, v130
	v_exp_f32_e32 v89, v89
	v_add_f32_e32 v130, v85, v130
	v_exp_f32_e32 v90, v90
	v_add_f32_e32 v130, v86, v130
	v_exp_f32_e32 v91, v91
	v_add_f32_e32 v130, v87, v130
	v_exp_f32_e32 v92, v92
	v_add_f32_e32 v130, v88, v130
	v_exp_f32_e32 v93, v93
	v_add_f32_e32 v130, v89, v130
	v_exp_f32_e32 v94, v94
	v_add_f32_e32 v130, v90, v130
	v_exp_f32_e32 v95, v95
	v_add_f32_e32 v130, v91, v130
	v_exp_f32_e32 v96, v96
	v_add_f32_e32 v130, v92, v130
	v_exp_f32_e32 v97, v97
	v_add_f32_e32 v130, v93, v130
	v_add_f32_e32 v130, v94, v130
	v_add_f32_e32 v130, v95, v130
	v_add_f32_e32 v130, v96, v130
	v_add_f32_e32 v130, v97, v130
	v_mov_b32_e32 v131, v130
	s_nop 1
	v_permlane32_swap_b32_e32 v130, v131
	v_add_f32_e32 v130, v130, v131
	v_add_f32_e32 v163, v163, v130
	v_cvt_pk_bf16_f32 v130, v66, v67
	v_cvt_pk_bf16_f32 v131, v68, v69
	v_cvt_pk_bf16_f32 v132, v70, v71
	v_cvt_pk_bf16_f32 v133, v72, v73
	v_cvt_pk_bf16_f32 v134, v74, v75
	v_cvt_pk_bf16_f32 v135, v76, v77
	v_cvt_pk_bf16_f32 v136, v78, v79
	v_cvt_pk_bf16_f32 v137, v80, v81
	v_cvt_pk_bf16_f32 v138, v82, v83
	v_cvt_pk_bf16_f32 v139, v84, v85
	v_cvt_pk_bf16_f32 v140, v86, v87
	v_cvt_pk_bf16_f32 v141, v88, v89
	v_cvt_pk_bf16_f32 v142, v90, v91
	v_cvt_pk_bf16_f32 v143, v92, v93
	v_cvt_pk_bf16_f32 v144, v94, v95
	v_cvt_pk_bf16_f32 v145, v96, v97
.LBB0_848:
	s_or_b64 exec, exec, s[2:3]
	s_cmp_ge_u32 s73, s97
	s_cselect_b64 s[2:3], -1, 0
	s_and_b64 vcc, exec, s[2:3]
	s_cbranch_vccnz .LBB0_850
	v_add_co_u32_e32 v114, vcc, 0x2ced4000, v152
	s_nop 1
	v_addc_co_u32_e32 v115, vcc, 0, v153, vcc
	v_add_co_u32_e32 v118, vcc, 0x119d0000, v150
	global_load_dwordx4 v[114:117], v[114:115], off offset:2048
	s_nop 0
	v_addc_co_u32_e32 v119, vcc, 0, v151, vcc
	global_load_dwordx4 v[118:121], v[118:119], off

; __device__ __forceinline__ void finishSM(f32x16& p0, f32x16& p1, float alpha, float& l_reg, bf16x8& pa0, bf16x8& pa1, bf16x8& pa2, bf16x8& pa3) {
; #pragma unroll
;   for (int r = 0; r < 16; ++r) p1[r] = __builtin_amdgcn_exp2f(p1[r]);
;   float ps = 0;
; #pragma unroll
;   for (int r = 0; r < 16; ++r) ps += p0[r];
; #pragma unroll
;   for (int r = 0; r < 16; ++r) ps += p1[r];
;   { auto rr = __builtin_amdgcn_permlane32_swap(__float_as_uint(ps), __float_as_uint(ps), false, false);
;     ps = __uint_as_float(rr[0]) + __uint_as_float(rr[1]); }
;   l_reg = l_reg * alpha + ps;
;     ...
;   PK4(p0, 0, pa0); PK4(p0, 8, pa1); PK4(p1, 0, pa2); PK4(p1, 8, pa3);
;     ...
; }
; template <int DQK>
; __device__ __forceinline__ void qkt(f32x16& p0, f32x16& p1, const bf16* Ks, const bf16x8* qr, int r32, int hi, int k0, int L) {
;   p0 = f32x16{}; p1 = f32x16{};
; #pragma unroll
;   for (int d0 = 0; d0 < DQK / 16; ++d0) { int cb = (d0 * 16 + hi * 8) * 2;
;     bf16x8 b0 = *reinterpret_cast<const bf16x8*>((const char*)Ks + KSWZ(r32, cb));
;     bf16x8 b1 = *reinterpret_cast<const bf16x8*>((const char*)Ks + KSWZ(32 + r32, cb));
;     p0 = __builtin_amdgcn_mfma_f32_32x32x16_bf16(b0, qr[d0], p0, 0, 0, 0);
;     p1 = __builtin_amdgcn_mfma_f32_32x32x16_bf16(b1, qr[d0], p1, 0, 0, 0); }
;   if (k0 + KVBLK > L) {
; #pragma unroll
;     for (int r = 0; r < 16; ++r) { const int key = k0 + crow(r, hi);
;       if (key >= L) p0[r] = -1e30f;
;       if (key + 32 >= L) p1[r] = -1e30f; }
;   }
; }
; __device__ __forceinline__ int v_st(int k, int c) { const int kk = (k & ~0xC) | ((k & 4) << 1) | ((k & 8) >> 1); return ((kk >> 3) * 4 + (c >> 5)) * 512 + ((kk & 7) * 32 + (c & 31)) * 2; }
; __device__ __forceinline__ int v_rd_base(int lane) { return ((lane & 3) << 3) | (((lane >> 2) & 3) << 6) | (((lane >> 4) & 1) << 5) | (((lane >> 5) & 1) << 8); }
; template <int OFF> __device__ __forceinline__ s16x4 tr_read(int vb) {
;   s16x4 r; asm volatile("ds_read_b64_tr_b16 %0, %1 offset:%2" : "=&v"(r) : "v"(vb), "i"(OFF) : "memory"); return r;
; }
; template <int D0> __device__ __forceinline__ void pv_one(f32x16& od, int vb, bf16x8 pa0, bf16x8 pa1, bf16x8 pa2, bf16x8 pa3) {
;   const s16x4 l0 = tr_read<v_rd_off(D0, 0, 0)>(vb), h0 = tr_read<v_rd_off(D0, 0, 1)>(vb), l1 = tr_read<v_rd_off(D0, 1, 0)>(vb), h1 = tr_read<v_rd_off(D0, 1, 1)>(vb);
.LBB0_853:
	s_and_saveexec_b64 s[2:3], s[8:9]
	v_readlane_b32 s6, v254, 61
	s_cbranch_execz .LBB0_855
	v_exp_f32_e32 v66, v34
	v_add_f32_e32 v34, 0, v50
	v_add_f32_e32 v34, v51, v34
	v_add_f32_e32 v34, v52, v34
	v_add_f32_e32 v34, v53, v34
	v_add_f32_e32 v34, v54, v34
	v_add_f32_e32 v34, v55, v34
	v_add_f32_e32 v34, v56, v34
	v_add_f32_e32 v34, v57, v34
	v_add_f32_e32 v34, v58, v34
	v_add_f32_e32 v34, v59, v34
	v_add_f32_e32 v34, v60, v34
	v_add_f32_e32 v34, v61, v34
	v_add_f32_e32 v34, v62, v34
	v_exp_f32_e32 v67, v35
	v_add_f32_e32 v34, v63, v34
	v_exp_f32_e32 v68, v36
	v_add_f32_e32 v34, v64, v34
	v_exp_f32_e32 v69, v37
	v_add_f32_e32 v34, v65, v34
	v_exp_f32_e32 v70, v38
	v_add_f32_e32 v34, v66, v34
	v_exp_f32_e32 v71, v39
	v_add_f32_e32 v34, v67, v34
	v_exp_f32_e32 v72, v40
	v_add_f32_e32 v34, v68, v34
	v_exp_f32_e32 v73, v41
	v_add_f32_e32 v34, v69, v34
	v_exp_f32_e32 v74, v42
	v_add_f32_e32 v34, v70, v34
	v_exp_f32_e32 v75, v43
	v_add_f32_e32 v34, v71, v34
	v_exp_f32_e32 v76, v44
	v_add_f32_e32 v34, v72, v34
	v_exp_f32_e32 v77, v45
	v_add_f32_e32 v34, v73, v34
	v_exp_f32_e32 v78, v46
	v_add_f32_e32 v34, v74, v34
	v_exp_f32_e32 v79, v47
	v_add_f32_e32 v34, v75, v34
	v_exp_f32_e32 v80, v48
	v_add_f32_e32 v34, v76, v34
	v_exp_f32_e32 v49, v49
	v_add_f32_e32 v34, v77, v34
	v_add_f32_e32 v34, v78, v34
	v_add_f32_e32 v34, v79, v34
	v_add_f32_e32 v34, v80, v34
	v_add_f32_e32 v34, v49, v34
	v_mov_b32_e32 v35, v34
	s_nop 1
	v_permlane32_swap_b32_e32 v34, v35
	v_add_f32_e32 v34, v34, v35
	v_add_f32_e32 v163, v163, v34
	v_cvt_pk_bf16_f32 v34, v50, v51
	v_cvt_pk_bf16_f32 v35, v52, v53
	v_cvt_pk_bf16_f32 v36, v54, v55
	v_cvt_pk_bf16_f32 v37, v56, v57
	v_cvt_pk_bf16_f32 v38, v58, v59
	v_cvt_pk_bf16_f32 v39, v60, v61
	v_cvt_pk_bf16_f32 v40, v62, v63
	v_cvt_pk_bf16_f32 v41, v64, v65
	v_cvt_pk_bf16_f32 v42, v66, v67
	v_cvt_pk_bf16_f32 v43, v68, v69
	v_cvt_pk_bf16_f32 v44, v70, v71
	v_cvt_pk_bf16_f32 v45, v72, v73
	v_cvt_pk_bf16_f32 v46, v74, v75
	v_cvt_pk_bf16_f32 v47, v76, v77
	v_cvt_pk_bf16_f32 v48, v78, v79
	v_cvt_pk_bf16_f32 v49, v80, v49
	ds_read_b64_tr_b16 v[50:51], v166 offset:0
	ds_read_b64_tr_b16 v[52:53], v166 offset:0x800
	ds_read_b64_tr_b16 v[54:55], v166 offset:0x1000
	ds_read_b64_tr_b16 v[56:57], v166 offset:0x1800
	ds_read_b64_tr_b16 v[58:59], v166 offset:0x2000
	ds_read_b64_tr_b16 v[60:61], v166 offset:0x2800
	ds_read_b64_tr_b16 v[62:63], v166 offset:0x3000
	ds_read_b64_tr_b16 v[64:65], v166 offset:0x3800
	s_waitcnt lgkmcnt(0)
	s_nop 0
	v_mfma_f32_32x32x16_bf16 v[2:17], v[34:37], v[50:53], v[2:17]
	ds_read_b64_tr_b16 v[50:51], v166 offset:0x200
	ds_read_b64_tr_b16 v[52:53], v166 offset:0xa00
	v_mfma_f32_32x32x16_bf16 v[2:17], v[38:41], v[54:57], v[2:17]
	ds_read_b64_tr_b16 v[54:55], v166 offset:0x1200
	ds_read_b64_tr_b16 v[56:57], v166 offset:0x1a00
	v_mfma_f32_32x32x16_bf16 v[2:17], v[42:45], v[58:61], v[2:17]
	ds_read_b64_tr_b16 v[58:59], v166 offset:0x2200
	ds_read_b64_tr_b16 v[60:61], v166 offset:0x2a00
	v_mfma_f32_32x32x16_bf16 v[2:17], v[46:49], v[62:65], v[2:17]
	ds_read_b64_tr_b16 v[62:63], v166 offset:0x3200
	ds_read_b64_tr_b16 v[64:65], v166 offset:0x3a00
	s_waitcnt lgkmcnt(0)
	v_mfma_f32_32x32x16_bf16 v[18:33], v[34:37], v[50:53], v[18:33]
	v_mfma_f32_32x32x16_bf16 v[18:33], v[38:41], v[54:57], v[18:33]
	v_mfma_f32_32x32x16_bf16 v[18:33], v[42:45], v[58:61], v[18:33]
	v_mfma_f32_32x32x16_bf16 v[18:33], v[46:49], v[62:65], v[18:33]

; __device__ __forceinline__ int v_st(int k, int c) { const int kk = (k & ~0xC) | ((k & 4) << 1) | ((k & 8) >> 1); return ((kk >> 3) * 4 + (c >> 5)) * 512 + ((kk & 7) * 32 + (c & 31)) * 2; }
; __device__ __forceinline__ int v_rd_base(int lane) { return ((lane & 3) << 3) | (((lane >> 2) & 3) << 6) | (((lane >> 4) & 1) << 5) | (((lane >> 5) & 1) << 8); }
; template <int OFF> __device__ __forceinline__ s16x4 tr_read(int vb) {
;   s16x4 r; asm volatile("ds_read_b64_tr_b16 %0, %1 offset:%2" : "=&v"(r) : "v"(vb), "i"(OFF) : "memory"); return r;
; }
; template <int D0> __device__ __forceinline__ void pv_one(f32x16& od, int vb, bf16x8 pa0, bf16x8 pa1, bf16x8 pa2, bf16x8 pa3) {
;   const s16x4 l0 = tr_read<v_rd_off(D0, 0, 0)>(vb), h0 = tr_read<v_rd_off(D0, 0, 1)>(vb), l1 = tr_read<v_rd_off(D0, 1, 0)>(vb), h1 = tr_read<v_rd_off(D0, 1, 1)>(vb);
;   const s16x4 l2 = tr_read<v_rd_off(D0, 2, 0)>(vb), h2 = tr_read<v_rd_off(D0, 2, 1)>(vb), l3 = tr_read<v_rd_off(D0, 3, 0)>(vb), h3 = tr_read<v_rd_off(D0, 3, 1)>(vb);
;   asm volatile("s_waitcnt lgkmcnt(0)" ::: "memory"); SBAR();
;     ...
;   od = __builtin_amdgcn_mfma_f32_32x32x16_bf16(pa0, PK(l0, h0), od, 0, 0, 0);
;   od = __builtin_amdgcn_mfma_f32_32x32x16_bf16(pa1, PK(l1, h1), od, 0, 0, 0);
;   od = __builtin_amdgcn_mfma_f32_32x32x16_bf16(pa2, PK(l2, h2), od, 0, 0, 0);
;   od = __builtin_amdgcn_mfma_f32_32x32x16_bf16(pa3, PK(l3, h3), od, 0, 0, 0);
;     ...
; }
; __device__ __forceinline__ void pv_d0(f32x16* o, int vb, bf16x8 pa0, bf16x8 pa1, bf16x8 pa2, bf16x8 pa3) {
;   pv_one<0>(o[0], vb, pa0, pa1, pa2, pa3); pv_one<1>(o[1], vb, pa0, pa1, pa2, pa3);
; }
; template <int DQK, bool FIX>
; __device__ __forceinline__ void attn_item(const bf16* Qb, const bf16* __restrict__ Kh, const bf16* __restrict__ Vh,
;                                           u16* Ob, int q0, int L, int NT, char* lds, float mC) {
;   constexpr int ldq = DQK == 96 ? 768 : 512, ldk = DQK == 96 ? 768 : 128, ldv = DQK == 96 ? 512 : 128, ldo = ldq;
;   constexpr int ND = DQK / 16, KCH = DQK / 8;
;   int tid = threadIdx.x; asm volatile("" : "+v"(tid));
;   const int wid = tid >> 6, lane = tid & 63, r32 = lane & 31, hi = lane >> 5;
;   bf16* V_lds = (bf16*)lds; bf16* K_lds = (bf16*)(lds + 2 * SHM_V);
;   float* ws = (float*)(lds + 2 * SHM_V + 2 * SHM_K) + wid * 64; float* li_l = ws; float* al_l = ws + 32;
;   float m_reg = -1e30f, l_reg = 0; f32x16 o[2] = {}; bf16x8 qr[ND];
.LBB0_869:
	s_or_b64 exec, exec, s[10:11]
	v_and_b32_e32 v13, 0xfffff8, v24
	v_lshlrev_b32_e32 v14, 1, v24
	v_and_or_b32 v13, v14, 0, v13
	v_lshrrev_b32_e32 v13, 1, v13
	v_lshrrev_b32_e32 v11, 5, v11
	v_lshrrev_b32_e32 v14, 1, v24
	v_or_b32_e32 v11, v13, v11
	v_and_b32_e32 v13, 7, v24
	v_and_or_b32 v13, v14, 0, v13
	v_and_b32_e32 v14, 48, v26
	v_lshl_or_b32 v13, v13, 6, v14
	v_lshl_or_b32 v11, v11, 9, v13
	v_lshlrev_b32_e32 v13, 8, v30
	v_bitop3_b32 v10, v30, v10, 7 bitop3:0x6c
	v_lshl_add_u32 v10, v10, 4, v13
	v_lshlrev_b32_e32 v13, 8, v28
	v_bitop3_b32 v12, v28, v12, 7 bitop3:0x6c
	s_waitcnt vmcnt(0)
	v_lshl_add_u32 v12, v12, 4, v13
	v_add_u32_e32 v193, 0, v11
	v_add_u32_e32 v194, 0, v10
	v_add_u32_e32 v195, 0, v12
	s_waitcnt vmcnt(1)
	ds_write_b128 v193, v[2:5]
	s_waitcnt vmcnt(0)
	ds_write_b128 v194, v[6:9] offset:32768
	s_and_saveexec_b64 s[10:11], s[8:9]
	ds_write_b128 v195, v[136:139] offset:32768
	s_or_b64 exec, exec, s[10:11]
	v_readlane_b32 s4, v254, 55
	v_readlane_b32 s5, v254, 56
	v_cmp_gt_i32_e64 s[10:11], s96, v175
	v_lshlrev_b32_e32 v29, 8, v190
	v_cndmask_b32_e64 v2, 0, 1, s[4:5]
	v_lshlrev_b32_e32 v31, 4, v190
	v_cmp_ne_u32_e64 s[12:13], 1, v2
	s_waitcnt lgkmcnt(0)
	s_barrier
	s_and_saveexec_b64 s[16:17], s[10:11]
	s_cbranch_execz .LBB0_875
	s_movk_i32 s4, 0x70
	v_bitop3_b32 v2, v0, v31, s4 bitop3:0x78
	v_add3_u32 v27, 0, v2, v29
	ds_read_b128 v[2:5], v27 offset:32768
	ds_read_b128 v[32:35], v27 offset:40960
	v_and_b32_e32 v27, 0x70, v31
	s_movk_i32 s4, 0x60
	s_and_b64 vcc, exec, s[12:13]
	s_waitcnt lgkmcnt(0)
	v_mfma_f32_32x32x16_bf16 v[48:63], v[32:35], v[112:115], 0
	v_bitop3_b32 v32, v0, v27, 32 bitop3:0x36
	v_add3_u32 v36, 0, v32, v29
	ds_read_b128 v[32:35], v36 offset:32768
	v_mfma_f32_32x32x16_bf16 v[2:17], v[2:5], v[112:115], 0
	s_waitcnt lgkmcnt(0)
	v_mfma_f32_32x32x16_bf16 v[2:17], v[32:35], v[116:119], v[2:17]
	ds_read_b128 v[32:35], v36 offset:40960
	s_waitcnt lgkmcnt(0)
	v_mfma_f32_32x32x16_bf16 v[48:63], v[32:35], v[116:119], v[48:63]
	v_bitop3_b32 v32, v0, v27, 64 bitop3:0x36
	v_add3_u32 v36, 0, v32, v29
	ds_read_b128 v[32:35], v36 offset:32768
	s_waitcnt lgkmcnt(0)
	v_mfma_f32_32x32x16_bf16 v[2:17], v[32:35], v[120:123], v[2:17]
	ds_read_b128 v[32:35], v36 offset:40960
	s_waitcnt lgkmcnt(0)
	v_mfma_f32_32x32x16_bf16 v[48:63], v[32:35], v[120:123], v[48:63]
	v_bitop3_b32 v32, v0, v27, s4 bitop3:0x36
	v_add3_u32 v36, 0, v32, v29
	ds_read_b128 v[32:35], v36 offset:32768
	s_movk_i32 s4, 0x80
	s_waitcnt lgkmcnt(0)
	v_mfma_f32_32x32x16_bf16 v[2:17], v[32:35], v[124:127], v[2:17]
	ds_read_b128 v[32:35], v36 offset:40960
	s_waitcnt lgkmcnt(0)
	v_mfma_f32_32x32x16_bf16 v[48:63], v[32:35], v[124:127], v[48:63]
	v_bitop3_b32 v32, v0, v27, s4 bitop3:0x36
	v_add3_u32 v36, 0, v32, v29
	ds_read_b128 v[32:35], v36 offset:32768
	s_movk_i32 s4, 0xa0
	v_bitop3_b32 v27, v0, v27, s4 bitop3:0x36
	v_add3_u32 v27, 0, v27, v29
	s_waitcnt lgkmcnt(0)
	v_mfma_f32_32x32x16_bf16 v[2:17], v[32:35], v[128:131], v[2:17]
	ds_read_b128 v[32:35], v36 offset:40960
	s_waitcnt lgkmcnt(0)
	v_mfma_f32_32x32x16_bf16 v[48:63], v[32:35], v[128:131], v[48:63]
	ds_read_b128 v[32:35], v27 offset:32768
	s_waitcnt lgkmcnt(0)
	v_mfma_f32_32x32x16_bf16 v[2:17], v[32:35], v[132:135], v[2:17]
	ds_read_b128 v[32:35], v27 offset:40960
	s_waitcnt lgkmcnt(0)
	v_mfma_f32_32x32x16_bf16 v[48:63], v[32:35], v[132:135], v[48:63]
	s_cbranch_vccnz .LBB0_874
	s_nop 7
	v_sub_f32_e32 v17, v17, v173
	v_sub_f32_e32 v16, v16, v173
	v_sub_f32_e32 v15, v15, v173
	v_sub_f32_e32 v14, v14, v173
	v_sub_f32_e32 v13, v13, v173
	v_sub_f32_e32 v12, v12, v173
	v_sub_f32_e32 v11, v11, v173
	v_sub_f32_e32 v10, v10, v173
	v_sub_f32_e32 v9, v9, v173
	v_sub_f32_e32 v8, v8, v173
	v_sub_f32_e32 v7, v7, v173
	v_sub_f32_e32 v6, v6, v173
	v_sub_f32_e32 v5, v5, v173
	v_sub_f32_e32 v4, v4, v173
	v_sub_f32_e32 v3, v3, v173
	v_sub_f32_e32 v2, v2, v173
	v_sub_f32_e32 v63, v63, v173
	v_sub_f32_e32 v62, v62, v173
	v_sub_f32_e32 v61, v61, v173
	v_sub_f32_e32 v60, v60, v173
	v_sub_f32_e32 v59, v59, v173
	v_sub_f32_e32 v58, v58, v173
	v_sub_f32_e32 v57, v57, v173
	v_sub_f32_e32 v56, v56, v173
	v_sub_f32_e32 v55, v55, v173
	v_sub_f32_e32 v54, v54, v173
	v_sub_f32_e32 v53, v53, v173
	v_sub_f32_e32 v52, v52, v173
	v_sub_f32_e32 v51, v51, v173
	v_sub_f32_e32 v50, v50, v173
	v_sub_f32_e32 v49, v49, v173
	v_sub_f32_e32 v48, v48, v173

; #define SBAR() __builtin_amdgcn_sched_barrier(0)
; #define SLOAD(i, key0) do { sr_[i].v = *reinterpret_cast<const bf16x8*>(&Vh[(long)((key0) + vr) * ldv + vc]); \
;     sr_[i].k0 = *reinterpret_cast<const bf16x8*>(&Kh[(long)((key0) + kr0) * ldk + kc0]); \
;     if (k2) sr_[i].k1 = *reinterpret_cast<const bf16x8*>(&Kh[(long)((key0) + kr1) * ldk + kc1]); } while (0)
; __device__ __forceinline__ void finishSM(f32x16& p0, f32x16& p1, float alpha, float& l_reg, bf16x8& pa0, bf16x8& pa1, bf16x8& pa2, bf16x8& pa3) {
; #pragma unroll
;   for (int r = 0; r < 16; ++r) p1[r] = __builtin_amdgcn_exp2f(p1[r]);
;   float ps = 0;
; #pragma unroll
;   for (int r = 0; r < 16; ++r) ps += p0[r];
; #pragma unroll
;   for (int r = 0; r < 16; ++r) ps += p1[r];
;   { auto rr = __builtin_amdgcn_permlane32_swap(__float_as_uint(ps), __float_as_uint(ps), false, false);
;     ps = __uint_as_float(rr[0]) + __uint_as_float(rr[1]); }
;   l_reg = l_reg * alpha + ps;
;     ...
;   PK4(p0, 0, pa0); PK4(p0, 8, pa1); PK4(p1, 0, pa2); PK4(p1, 8, pa3);
;     ...
; }
; template <int DQK>
; __device__ __forceinline__ void qkt(f32x16& p0, f32x16& p1, const bf16* Ks, const bf16x8* qr, int r32, int hi, int k0, int L) {
;   p0 = f32x16{}; p1 = f32x16{};
; #pragma unroll
;   for (int d0 = 0; d0 < DQK / 16; ++d0) { int cb = (d0 * 16 + hi * 8) * 2;
;     bf16x8 b0 = *reinterpret_cast<const bf16x8*>((const char*)Ks + KSWZ(r32, cb));
;     bf16x8 b1 = *reinterpret_cast<const bf16x8*>((const char*)Ks + KSWZ(32 + r32, cb));
;     p0 = __builtin_amdgcn_mfma_f32_32x32x16_bf16(b0, qr[d0], p0, 0, 0, 0);
;     p1 = __builtin_amdgcn_mfma_f32_32x32x16_bf16(b1, qr[d0], p1, 0, 0, 0); }
; template <int DQK, bool FIX>
; __device__ __forceinline__ void attn_item(const bf16* Qb, const bf16* __restrict__ Kh, const bf16* __restrict__ Vh,
;                                           u16* Ob, int q0, int L, int NT, char* lds, float mC) {
;     ...
;     if (act) { SBAR(); qkt<DQK>(pB0, pB1, (bf16*)((char*)K_lds + SHM_K), qr, r32, hi, j * KVBLK, L);
;       finishSM(pA0, pA1, alA, l_reg, pa0, pa1, pa2, pa3); SBAR(); }
;     SLOAD(SO, (j + 2) * KVBLK); SBAR();
;     if (act) { pv_d0(o, vb0, pa0, pa1, pa2, pa3); partialSM<DQK, FIX>(pB0, pB1, m_reg, mnB, alB, mC); }
.LBB0_883:
	s_and_saveexec_b64 s[2:3], s[10:11]
	s_cbranch_execz .LBB0_889
	s_add_i32 s14, s4, 64
	s_cmp_le_u32 s14, s5
	s_cbranch_scc0 .Lslow96a
	s_and_b64 vcc, exec, s[12:13]
	s_cbranch_vccz .Lslow96a
	ds_read_b128 v[222:225], v200 offset:49152
	ds_read_b128 v[226:229], v200 offset:57344
	ds_read_b128 v[230:233], v201 offset:49152
	ds_read_b128 v[234:237], v201 offset:57344
	ds_read_b128 v[238:241], v202 offset:49152
	ds_read_b128 v[242:245], v202 offset:57344
	ds_read_b128 v[246:249], v203 offset:49152
	ds_read_b128 v[250:253], v203 offset:57344
	v_cvt_pk_bf16_f32 v10, v64, v65
	v_cvt_pk_bf16_f32 v11, v66, v67
	v_cvt_pk_bf16_f32 v12, v68, v69
	v_cvt_pk_bf16_f32 v13, v70, v71
	v_cvt_pk_bf16_f32 v152, v72, v73
	v_cvt_pk_bf16_f32 v153, v74, v75
	v_cvt_pk_bf16_f32 v154, v76, v77
	v_cvt_pk_bf16_f32 v155, v78, v79
	s_waitcnt lgkmcnt(7)
	v_mfma_f32_32x32x16_bf16 v[80:95], v[222:225], v[112:115], 0
	ds_read_b128 v[222:225], v204 offset:49152
	ds_read_b64_tr_b16 v[206:207], v197 offset:0
	ds_read_b64_tr_b16 v[208:209], v197 offset:2048
	ds_read_b64_tr_b16 v[210:211], v197 offset:4096
	ds_read_b64_tr_b16 v[212:213], v197 offset:6144
	v_exp_f32_e32 v48, v48
	v_exp_f32_e32 v49, v49
	v_add_f32_e32 v0, 0, v64
	s_waitcnt lgkmcnt(11)
	v_mfma_f32_32x32x16_bf16 v[96:111], v[226:229], v[112:115], 0
	ds_read_b128 v[226:229], v204 offset:57344
	ds_read_b64_tr_b16 v[214:215], v197 offset:8192
	ds_read_b64_tr_b16 v[216:217], v197 offset:10240
	ds_read_b64_tr_b16 v[218:219], v197 offset:12288
	s_waitcnt lgkmcnt(14)
	ds_read_b64_tr_b16 v[220:221], v197 offset:14336
	v_exp_f32_e32 v50, v50
	v_exp_f32_e32 v51, v51
	v_add_f32_e32 v0, v65, v0
	v_mfma_f32_32x32x16_bf16 v[80:95], v[230:233], v[116:119], v[80:95]
	s_waitcnt lgkmcnt(14)
	ds_read_b128 v[230:233], v205 offset:49152
	v_exp_f32_e32 v52, v52
	v_exp_f32_e32 v53, v53
	v_add_f32_e32 v0, v66, v0
	v_mfma_f32_32x32x16_bf16 v[96:111], v[234:237], v[116:119], v[96:111]
	s_waitcnt lgkmcnt(14)
	ds_read_b128 v[234:237], v205 offset:57344
	v_exp_f32_e32 v54, v54
	v_exp_f32_e32 v55, v55
	v_add_f32_e32 v0, v67, v0
	v_mfma_f32_32x32x16_bf16 v[80:95], v[238:241], v[120:123], v[80:95]
	v_exp_f32_e32 v56, v56
	v_exp_f32_e32 v57, v57
	v_add_f32_e32 v0, v68, v0
	s_waitcnt lgkmcnt(14)
	v_mfma_f32_32x32x16_bf16 v[96:111], v[242:245], v[120:123], v[96:111]
	v_exp_f32_e32 v58, v58
	v_exp_f32_e32 v59, v59
	v_add_f32_e32 v0, v69, v0
	s_waitcnt lgkmcnt(13)
	v_mfma_f32_32x32x16_bf16 v[80:95], v[246:249], v[124:127], v[80:95]
	v_exp_f32_e32 v60, v60
	v_exp_f32_e32 v61, v61
	v_add_f32_e32 v0, v70, v0
	s_waitcnt lgkmcnt(12)
	v_mfma_f32_32x32x16_bf16 v[96:111], v[250:253], v[124:127], v[96:111]
	v_exp_f32_e32 v62, v62
	v_exp_f32_e32 v63, v63
	v_add_f32_e32 v0, v71, v0
	s_waitcnt lgkmcnt(11)
	v_mfma_f32_32x32x16_bf16 v[80:95], v[222:225], v[128:131], v[80:95]
	ds_read_b64_tr_b16 v[238:239], v197 offset:512
	ds_read_b64_tr_b16 v[240:241], v197 offset:2560
	ds_read_b64_tr_b16 v[242:243], v197 offset:4608
	ds_read_b64_tr_b16 v[244:245], v197 offset:6656
	v_cvt_pk_bf16_f32 v156, v48, v49
	v_cvt_pk_bf16_f32 v157, v50, v51
	v_cvt_pk_bf16_f32 v158, v52, v53
	v_cvt_pk_bf16_f32 v159, v54, v55
	v_add_f32_e32 v0, v72, v0
	v_add_f32_e32 v0, v73, v0
	s_waitcnt lgkmcnt(10)
	v_mfma_f32_32x32x16_bf16 v[96:111], v[226:229], v[128:131], v[96:111]
	v_cvt_pk_bf16_f32 v160, v56, v57
	v_cvt_pk_bf16_f32 v161, v58, v59
	v_cvt_pk_bf16_f32 v162, v60, v61
	v_cvt_pk_bf16_f32 v163, v62, v63
	v_add_f32_e32 v0, v74, v0
	v_add_f32_e32 v0, v75, v0
	s_waitcnt lgkmcnt(5)
	v_mfma_f32_32x32x16_bf16 v[80:95], v[230:233], v[132:135], v[80:95]
	ds_read_b64_tr_b16 v[246:247], v197 offset:8704
	ds_read_b64_tr_b16 v[248:249], v197 offset:10752
	ds_read_b64_tr_b16 v[250:251], v197 offset:12800
	ds_read_b64_tr_b16 v[252:253], v197 offset:14848
	v_add_f32_e32 v0, v76, v0
	v_add_f32_e32 v0, v77, v0
	s_waitcnt lgkmcnt(8)
	v_mfma_f32_32x32x16_bf16 v[96:111], v[234:237], v[132:135], v[96:111]
	v_add_f32_e32 v0, v78, v0
	v_add_f32_e32 v0, v79, v0
	s_or_b64 exec, exec, s[2:3]
	v_add_co_u32_e32 v2, vcc, 0xffff0000, v170
	v_lshl_add_u64 v[14:15], v[168:169], 0, s[6:7]
	s_nop 0
	v_addc_co_u32_e32 v3, vcc, -1, v171, vcc
	v_add_co_u32_e32 v6, vcc, 0xa148000, v14
	global_load_dwordx4 v[2:5], v[2:3], off
	s_nop 0
	v_addc_co_u32_e32 v7, vcc, 0, v15, vcc
	global_load_dwordx4 v[6:9], v[6:7], off
	s_and_saveexec_b64 s[2:3], s[8:9]
	s_cbranch_execz .Lfast96a_k2
	v_lshl_add_u64 v[140:141], v[166:167], 0, s[6:7]
	v_add_co_u32_e32 v140, vcc, 0xa148000, v140
	s_nop 1
	v_addc_co_u32_e32 v141, vcc, 0, v141, vcc
	global_load_dwordx4 v[140:143], v[140:141], off
.Lfast96a_k2:
	s_or_b64 exec, exec, s[2:3]
	s_and_saveexec_b64 s[2:3], s[10:11]
	v_mfma_f32_32x32x16_bf16 v[32:47], v[10:13], v[206:209], v[32:47]
	v_add_f32_e32 v0, v48, v0
	v_add_f32_e32 v0, v49, v0
	v_exp_f32_e32 v80, v80
	v_exp_f32_e32 v81, v81
	v_mfma_f32_32x32x16_bf16 v[32:47], v[152:155], v[210:213], v[32:47]
	v_add_f32_e32 v0, v50, v0
	v_add_f32_e32 v0, v51, v0
	v_exp_f32_e32 v82, v82
	v_exp_f32_e32 v83, v83
	v_mfma_f32_32x32x16_bf16 v[32:47], v[156:159], v[214:217], v[32:47]
	v_add_f32_e32 v0, v52, v0
	v_add_f32_e32 v0, v53, v0
	v_exp_f32_e32 v84, v84
	v_exp_f32_e32 v85, v85
	v_mfma_f32_32x32x16_bf16 v[32:47], v[160:163], v[218:221], v[32:47]
	v_add_f32_e32 v0, v54, v0
	v_add_f32_e32 v0, v55, v0
	v_exp_f32_e32 v86, v86
	v_exp_f32_e32 v87, v87
	s_waitcnt lgkmcnt(6)
	v_mfma_f32_32x32x16_bf16 v[16:31], v[10:13], v[238:241], v[16:31]
	v_add_f32_e32 v0, v56, v0
	v_add_f32_e32 v0, v57, v0
	v_exp_f32_e32 v88, v88
	v_exp_f32_e32 v89, v89
	s_waitcnt lgkmcnt(4)
	v_mfma_f32_32x32x16_bf16 v[16:31], v[152:155], v[242:245], v[16:31]
	v_add_f32_e32 v0, v58, v0
	v_add_f32_e32 v0, v59, v0
	v_exp_f32_e32 v90, v90
	v_exp_f32_e32 v91, v91
	s_waitcnt lgkmcnt(2)
	v_mfma_f32_32x32x16_bf16 v[16:31], v[156:159], v[246:249], v[16:31]
	v_add_f32_e32 v0, v60, v0
	v_add_f32_e32 v0, v61, v0
	v_exp_f32_e32 v92, v92
	v_exp_f32_e32 v93, v93
	s_waitcnt lgkmcnt(0)
	v_mfma_f32_32x32x16_bf16 v[16:31], v[160:163], v[250:253], v[16:31]
	v_add_f32_e32 v0, v62, v0
	v_add_f32_e32 v0, v63, v0
	v_exp_f32_e32 v94, v94
	v_exp_f32_e32 v95, v95
	v_mov_b32_e32 v222, v0
	s_nop 1
	v_permlane32_swap_b32_e32 v0, v222
	v_add_f32_e32 v0, v0, v222
	v_add_f32_e32 v198, v198, v0
	s_branch .LBB0_895

; #define SBAR() __builtin_amdgcn_sched_barrier(0)
; #define SLOAD(i, key0) do { sr_[i].v = *reinterpret_cast<const bf16x8*>(&Vh[(long)((key0) + vr) * ldv + vc]); \
;     sr_[i].k0 = *reinterpret_cast<const bf16x8*>(&Kh[(long)((key0) + kr0) * ldk + kc0]); \
;     if (k2) sr_[i].k1 = *reinterpret_cast<const bf16x8*>(&Kh[(long)((key0) + kr1) * ldk + kc1]); } while (0)
; __device__ __forceinline__ void finishSM(f32x16& p0, f32x16& p1, float alpha, float& l_reg, bf16x8& pa0, bf16x8& pa1, bf16x8& pa2, bf16x8& pa3) {
; #pragma unroll
;   for (int r = 0; r < 16; ++r) p1[r] = __builtin_amdgcn_exp2f(p1[r]);
;   float ps = 0;
; #pragma unroll
;   for (int r = 0; r < 16; ++r) ps += p0[r];
; #pragma unroll
;   for (int r = 0; r < 16; ++r) ps += p1[r];
;   { auto rr = __builtin_amdgcn_permlane32_swap(__float_as_uint(ps), __float_as_uint(ps), false, false);
;     ps = __uint_as_float(rr[0]) + __uint_as_float(rr[1]); }
;   l_reg = l_reg * alpha + ps;
;     ...
;   PK4(p0, 0, pa0); PK4(p0, 8, pa1); PK4(p1, 0, pa2); PK4(p1, 8, pa3);
; template <int DQK, bool FIX>
; __device__ __forceinline__ void attn_item(const bf16* Qb, const bf16* __restrict__ Kh, const bf16* __restrict__ Vh,
;                                           u16* Ob, int q0, int L, int NT, char* lds, float mC) {
;     ...
;     if (act) { SBAR(); qkt<DQK>(pB0, pB1, (bf16*)((char*)K_lds + SHM_K), qr, r32, hi, j * KVBLK, L);
;       finishSM(pA0, pA1, alA, l_reg, pa0, pa1, pa2, pa3); SBAR(); }
;     SLOAD(SO, (j + 2) * KVBLK); SBAR();
.LBB0_888:
	v_add_f32_e32 v0, 0, v64
	v_add_f32_e32 v0, v65, v0
	v_add_f32_e32 v0, v66, v0
	v_add_f32_e32 v0, v67, v0
	v_add_f32_e32 v0, v68, v0
	v_add_f32_e32 v0, v69, v0
	v_add_f32_e32 v0, v70, v0
	v_add_f32_e32 v0, v71, v0
	v_add_f32_e32 v0, v72, v0
	v_add_f32_e32 v0, v73, v0
	v_add_f32_e32 v0, v74, v0
	v_add_f32_e32 v0, v75, v0
	v_exp_f32_e32 v48, v48
	v_add_f32_e32 v0, v76, v0
	v_exp_f32_e32 v49, v49
	v_add_f32_e32 v0, v77, v0
	v_exp_f32_e32 v50, v50
	v_add_f32_e32 v0, v78, v0
	v_exp_f32_e32 v51, v51
	v_add_f32_e32 v0, v79, v0
	v_exp_f32_e32 v52, v52
	v_add_f32_e32 v0, v48, v0
	v_exp_f32_e32 v53, v53
	v_add_f32_e32 v0, v49, v0
	v_exp_f32_e32 v54, v54
	v_add_f32_e32 v0, v50, v0
	v_exp_f32_e32 v55, v55
	v_add_f32_e32 v0, v51, v0
	v_exp_f32_e32 v56, v56
	v_add_f32_e32 v0, v52, v0
	v_exp_f32_e32 v57, v57
	v_add_f32_e32 v0, v53, v0
	v_exp_f32_e32 v58, v58
	v_add_f32_e32 v0, v54, v0
	v_exp_f32_e32 v59, v59
	v_add_f32_e32 v0, v55, v0
	v_exp_f32_e32 v60, v60
	v_add_f32_e32 v0, v56, v0
	v_exp_f32_e32 v61, v61
	v_add_f32_e32 v0, v57, v0
	v_exp_f32_e32 v62, v62
	v_add_f32_e32 v0, v58, v0
	v_exp_f32_e32 v63, v63
	v_add_f32_e32 v0, v59, v0
	v_add_f32_e32 v0, v60, v0
	v_add_f32_e32 v0, v61, v0
	v_add_f32_e32 v0, v62, v0
	v_add_f32_e32 v0, v63, v0
	v_mov_b32_e32 v2, v0
	s_nop 1
	v_permlane32_swap_b32_e32 v0, v2
	v_add_f32_e32 v0, v0, v2
	v_cvt_pk_bf16_f32 v10, v64, v65
	v_cvt_pk_bf16_f32 v11, v66, v67
	v_cvt_pk_bf16_f32 v12, v68, v69
	v_cvt_pk_bf16_f32 v13, v70, v71
	v_cvt_pk_bf16_f32 v152, v72, v73
	v_cvt_pk_bf16_f32 v153, v74, v75
	v_cvt_pk_bf16_f32 v154, v76, v77
	v_cvt_pk_bf16_f32 v155, v78, v79
	v_cvt_pk_bf16_f32 v156, v48, v49
	v_cvt_pk_bf16_f32 v157, v50, v51
	v_cvt_pk_bf16_f32 v158, v52, v53
	v_cvt_pk_bf16_f32 v159, v54, v55
	v_cvt_pk_bf16_f32 v160, v56, v57
	v_cvt_pk_bf16_f32 v161, v58, v59
	v_cvt_pk_bf16_f32 v162, v60, v61
	v_cvt_pk_bf16_f32 v163, v62, v63
	v_add_f32_e32 v198, v198, v0
.LBB0_889:
	s_or_b64 exec, exec, s[2:3]
	v_add_co_u32_e32 v2, vcc, 0xffff0000, v170
	v_lshl_add_u64 v[14:15], v[168:169], 0, s[6:7]
	s_nop 0
	v_addc_co_u32_e32 v3, vcc, -1, v171, vcc
	v_add_co_u32_e32 v6, vcc, 0xa148000, v14
	global_load_dwordx4 v[2:5], v[2:3], off
	s_nop 0
	v_addc_co_u32_e32 v7, vcc, 0, v15, vcc
	global_load_dwordx4 v[6:9], v[6:7], off
	s_and_saveexec_b64 s[2:3], s[8:9]
	s_cbranch_execz .LBB0_891
	v_lshl_add_u64 v[140:141], v[166:167], 0, s[6:7]
	v_add_co_u32_e32 v140, vcc, 0xa148000, v140
	s_nop 1
	v_addc_co_u32_e32 v141, vcc, 0, v141, vcc
	global_load_dwordx4 v[140:143], v[140:141], off

; #define SBAR() __builtin_amdgcn_sched_barrier(0)
; #define SLOAD(i, key0) do { sr_[i].v = *reinterpret_cast<const bf16x8*>(&Vh[(long)((key0) + vr) * ldv + vc]); \
;     sr_[i].k0 = *reinterpret_cast<const bf16x8*>(&Kh[(long)((key0) + kr0) * ldk + kc0]); \
;     if (k2) sr_[i].k1 = *reinterpret_cast<const bf16x8*>(&Kh[(long)((key0) + kr1) * ldk + kc1]); } while (0)
; #define SWAIT() asm volatile("s_waitcnt vmcnt(2)" ::: "memory")
; __device__ __forceinline__ void finishSM(f32x16& p0, f32x16& p1, float alpha, float& l_reg, bf16x8& pa0, bf16x8& pa1, bf16x8& pa2, bf16x8& pa3) {
; #pragma unroll
;   for (int r = 0; r < 16; ++r) p1[r] = __builtin_amdgcn_exp2f(p1[r]);
;   float ps = 0;
; #pragma unroll
;   for (int r = 0; r < 16; ++r) ps += p0[r];
; #pragma unroll
;   for (int r = 0; r < 16; ++r) ps += p1[r];
;   { auto rr = __builtin_amdgcn_permlane32_swap(__float_as_uint(ps), __float_as_uint(ps), false, false);
;     ps = __uint_as_float(rr[0]) + __uint_as_float(rr[1]); }
;   l_reg = l_reg * alpha + ps;
;     ...
;   PK4(p0, 0, pa0); PK4(p0, 8, pa1); PK4(p1, 0, pa2); PK4(p1, 8, pa3);
;     ...
; }
; template <int DQK>
; __device__ __forceinline__ void qkt(f32x16& p0, f32x16& p1, const bf16* Ks, const bf16x8* qr, int r32, int hi, int k0, int L) {
;   p0 = f32x16{}; p1 = f32x16{};
; #pragma unroll
;   for (int d0 = 0; d0 < DQK / 16; ++d0) { int cb = (d0 * 16 + hi * 8) * 2;
;     bf16x8 b0 = *reinterpret_cast<const bf16x8*>((const char*)Ks + KSWZ(r32, cb));
;     bf16x8 b1 = *reinterpret_cast<const bf16x8*>((const char*)Ks + KSWZ(32 + r32, cb));
;     p0 = __builtin_amdgcn_mfma_f32_32x32x16_bf16(b0, qr[d0], p0, 0, 0, 0);
;     p1 = __builtin_amdgcn_mfma_f32_32x32x16_bf16(b1, qr[d0], p1, 0, 0, 0); }
; template <int DQK, bool FIX>
; __device__ __forceinline__ void attn_item(const bf16* Qb, const bf16* __restrict__ Kh, const bf16* __restrict__ Vh,
;                                           u16* Ob, int q0, int L, int NT, char* lds, float mC) {
;     ...
;     __syncthreads(); SWAIT(); SWRITE(0, SE);
;     if (act) { RESC(alB); } __syncthreads();
;     if (act) { SBAR(); qkt<DQK>(pA0, pA1, K_lds, qr, r32, hi, (j + 1) * KVBLK, L);
;       finishSM(pB0, pB1, alB, l_reg, pa0, pa1, pa2, pa3); SBAR(); }
;     if (j + 3 < NT) SLOAD(SE, (j + 3) * KVBLK); SBAR();
.LBB0_895:
	s_or_b64 exec, exec, s[2:3]
	s_barrier
	s_waitcnt vmcnt(2)
	s_waitcnt vmcnt(3)
	ds_write_b128 v193, v[144:147]
	s_waitcnt vmcnt(2)
	ds_write_b128 v194, v[148:151] offset:32768
	s_and_saveexec_b64 s[2:3], s[8:9]
	ds_write_b128 v195, v[136:139] offset:32768
	s_or_b64 exec, exec, s[2:3]
	s_waitcnt lgkmcnt(0)
	s_barrier
	s_and_saveexec_b64 s[2:3], s[10:11]
	s_cbranch_execz .LBB0_903
	s_add_i32 s14, s4, 0x80
	s_cmp_le_u32 s14, s5
	s_cbranch_scc0 .Lslow96b
	s_and_b64 vcc, exec, s[12:13]
	s_cbranch_vccz .Lslow96b
	ds_read_b128 v[222:225], v200 offset:32768
	ds_read_b128 v[226:229], v200 offset:40960
	ds_read_b128 v[230:233], v201 offset:32768
	ds_read_b128 v[234:237], v201 offset:40960
	ds_read_b128 v[238:241], v202 offset:32768
	ds_read_b128 v[242:245], v202 offset:40960
	ds_read_b128 v[246:249], v203 offset:32768
	ds_read_b128 v[250:253], v203 offset:40960
	v_cvt_pk_bf16_f32 v10, v80, v81
	v_cvt_pk_bf16_f32 v11, v82, v83
	v_cvt_pk_bf16_f32 v12, v84, v85
	v_cvt_pk_bf16_f32 v13, v86, v87
	v_cvt_pk_bf16_f32 v152, v88, v89
	v_cvt_pk_bf16_f32 v153, v90, v91
	v_cvt_pk_bf16_f32 v154, v92, v93
	v_cvt_pk_bf16_f32 v155, v94, v95
	s_waitcnt lgkmcnt(7)
	v_mfma_f32_32x32x16_bf16 v[64:79], v[222:225], v[112:115], 0
	ds_read_b128 v[222:225], v204 offset:32768
	ds_read_b64_tr_b16 v[206:207], v199 offset:0
	ds_read_b64_tr_b16 v[208:209], v199 offset:2048
	ds_read_b64_tr_b16 v[210:211], v199 offset:4096
	ds_read_b64_tr_b16 v[212:213], v199 offset:6144
	v_exp_f32_e32 v96, v96
	v_exp_f32_e32 v97, v97
	v_add_f32_e32 v0, 0, v80
	s_waitcnt lgkmcnt(11)
	v_mfma_f32_32x32x16_bf16 v[48:63], v[226:229], v[112:115], 0
	ds_read_b128 v[226:229], v204 offset:40960
	ds_read_b64_tr_b16 v[214:215], v199 offset:8192
	ds_read_b64_tr_b16 v[216:217], v199 offset:10240
	ds_read_b64_tr_b16 v[218:219], v199 offset:12288
	s_waitcnt lgkmcnt(14)
	ds_read_b64_tr_b16 v[220:221], v199 offset:14336
	v_exp_f32_e32 v98, v98
	v_exp_f32_e32 v99, v99
	v_add_f32_e32 v0, v81, v0
	v_mfma_f32_32x32x16_bf16 v[64:79], v[230:233], v[116:119], v[64:79]
	s_waitcnt lgkmcnt(14)
	ds_read_b128 v[230:233], v205 offset:32768
	v_exp_f32_e32 v100, v100
	v_exp_f32_e32 v101, v101
	v_add_f32_e32 v0, v82, v0
	v_mfma_f32_32x32x16_bf16 v[48:63], v[234:237], v[116:119], v[48:63]
	s_waitcnt lgkmcnt(14)
	ds_read_b128 v[234:237], v205 offset:40960
	v_exp_f32_e32 v102, v102
	v_exp_f32_e32 v103, v103
	v_add_f32_e32 v0, v83, v0
	v_mfma_f32_32x32x16_bf16 v[64:79], v[238:241], v[120:123], v[64:79]
	v_exp_f32_e32 v104, v104
	v_exp_f32_e32 v105, v105
	v_add_f32_e32 v0, v84, v0
	s_waitcnt lgkmcnt(14)
	v_mfma_f32_32x32x16_bf16 v[48:63], v[242:245], v[120:123], v[48:63]
	v_exp_f32_e32 v106, v106
	v_exp_f32_e32 v107, v107
	v_add_f32_e32 v0, v85, v0
	s_waitcnt lgkmcnt(13)
	v_mfma_f32_32x32x16_bf16 v[64:79], v[246:249], v[124:127], v[64:79]
	v_exp_f32_e32 v108, v108
	v_exp_f32_e32 v109, v109
	v_add_f32_e32 v0, v86, v0
	s_waitcnt lgkmcnt(12)
	v_mfma_f32_32x32x16_bf16 v[48:63], v[250:253], v[124:127], v[48:63]
	v_exp_f32_e32 v110, v110
	v_exp_f32_e32 v111, v111
	v_add_f32_e32 v0, v87, v0
	s_waitcnt lgkmcnt(11)
	v_mfma_f32_32x32x16_bf16 v[64:79], v[222:225], v[128:131], v[64:79]
	ds_read_b64_tr_b16 v[238:239], v199 offset:512
	ds_read_b64_tr_b16 v[240:241], v199 offset:2560
	ds_read_b64_tr_b16 v[242:243], v199 offset:4608
	ds_read_b64_tr_b16 v[244:245], v199 offset:6656
	v_cvt_pk_bf16_f32 v156, v96, v97
	v_cvt_pk_bf16_f32 v157, v98, v99
	v_cvt_pk_bf16_f32 v158, v100, v101
	v_cvt_pk_bf16_f32 v159, v102, v103
	v_add_f32_e32 v0, v88, v0
	v_add_f32_e32 v0, v89, v0
	s_waitcnt lgkmcnt(10)
	v_mfma_f32_32x32x16_bf16 v[48:63], v[226:229], v[128:131], v[48:63]
	v_cvt_pk_bf16_f32 v160, v104, v105
	v_cvt_pk_bf16_f32 v161, v106, v107
	v_cvt_pk_bf16_f32 v162, v108, v109
	v_cvt_pk_bf16_f32 v163, v110, v111
	v_add_f32_e32 v0, v90, v0
	v_add_f32_e32 v0, v91, v0
	s_waitcnt lgkmcnt(5)
	v_mfma_f32_32x32x16_bf16 v[64:79], v[230:233], v[132:135], v[64:79]
	ds_read_b64_tr_b16 v[246:247], v199 offset:8704
	ds_read_b64_tr_b16 v[248:249], v199 offset:10752
	ds_read_b64_tr_b16 v[250:251], v199 offset:12800
	ds_read_b64_tr_b16 v[252:253], v199 offset:14848
	v_add_f32_e32 v0, v92, v0
	v_add_f32_e32 v0, v93, v0
	s_waitcnt lgkmcnt(8)
	v_mfma_f32_32x32x16_bf16 v[48:63], v[234:237], v[132:135], v[48:63]
	v_add_f32_e32 v0, v94, v0
	v_add_f32_e32 v0, v95, v0
	s_or_b64 exec, exec, s[2:3]
	s_cmp_ge_u32 s79, s97
	s_cselect_b64 s[2:3], -1, 0
	s_and_b64 vcc, exec, s[2:3]
	s_cbranch_vccnz .Lfast96b_nl
	v_add_co_u32_e32 v14, vcc, 0xa160000, v14
	global_load_dwordx4 v[144:147], v[170:171], off
	s_nop 0
	v_addc_co_u32_e32 v15, vcc, 0, v15, vcc
	global_load_dwordx4 v[148:151], v[14:15], off
	s_and_saveexec_b64 s[14:15], s[8:9]
	s_cbranch_execz .Lfast96b_k2
	v_lshl_add_u64 v[14:15], v[166:167], 0, s[6:7]
	v_add_co_u32_e32 v14, vcc, 0xa160000, v14
	s_nop 1
	v_addc_co_u32_e32 v15, vcc, 0, v15, vcc
	global_load_dwordx4 v[136:139], v[14:15], off

; #define SBAR() __builtin_amdgcn_sched_barrier(0)
; #define SLOAD(i, key0) do { sr_[i].v = *reinterpret_cast<const bf16x8*>(&Vh[(long)((key0) + vr) * ldv + vc]); \
;     sr_[i].k0 = *reinterpret_cast<const bf16x8*>(&Kh[(long)((key0) + kr0) * ldk + kc0]); \
;     if (k2) sr_[i].k1 = *reinterpret_cast<const bf16x8*>(&Kh[(long)((key0) + kr1) * ldk + kc1]); } while (0)
; template <int D0> __device__ __forceinline__ void pv_one(f32x16& od, int vb, bf16x8 pa0, bf16x8 pa1, bf16x8 pa2, bf16x8 pa3) {
;   const s16x4 l0 = tr_read<v_rd_off(D0, 0, 0)>(vb), h0 = tr_read<v_rd_off(D0, 0, 1)>(vb), l1 = tr_read<v_rd_off(D0, 1, 0)>(vb), h1 = tr_read<v_rd_off(D0, 1, 1)>(vb);
;   const s16x4 l2 = tr_read<v_rd_off(D0, 2, 0)>(vb), h2 = tr_read<v_rd_off(D0, 2, 1)>(vb), l3 = tr_read<v_rd_off(D0, 3, 0)>(vb), h3 = tr_read<v_rd_off(D0, 3, 1)>(vb);
;   asm volatile("s_waitcnt lgkmcnt(0)" ::: "memory"); SBAR();
;     ...
;   od = __builtin_amdgcn_mfma_f32_32x32x16_bf16(pa0, PK(l0, h0), od, 0, 0, 0);
;   od = __builtin_amdgcn_mfma_f32_32x32x16_bf16(pa1, PK(l1, h1), od, 0, 0, 0);
;   od = __builtin_amdgcn_mfma_f32_32x32x16_bf16(pa2, PK(l2, h2), od, 0, 0, 0);
;   od = __builtin_amdgcn_mfma_f32_32x32x16_bf16(pa3, PK(l3, h3), od, 0, 0, 0);
;     ...
; }
; __device__ __forceinline__ void pv_d0(f32x16* o, int vb, bf16x8 pa0, bf16x8 pa1, bf16x8 pa2, bf16x8 pa3) {
;   pv_one<0>(o[0], vb, pa0, pa1, pa2, pa3); pv_one<1>(o[1], vb, pa0, pa1, pa2, pa3);
; }
; template <int DQK, bool FIX>
; __device__ __forceinline__ void attn_item(const bf16* Qb, const bf16* __restrict__ Kh, const bf16* __restrict__ Vh,
;                                           u16* Ob, int q0, int L, int NT, char* lds, float mC) {
;     ...
;     if (act) { SBAR(); qkt<DQK>(pA0, pA1, K_lds, qr, r32, hi, (j + 1) * KVBLK, L);
;       finishSM(pB0, pB1, alB, l_reg, pa0, pa1, pa2, pa3); SBAR(); }
;     if (j + 3 < NT) SLOAD(SE, (j + 3) * KVBLK); SBAR();
;     if (act) { pv_d0(o, vb0 + (int)SHM_V, pa0, pa1, pa2, pa3); partialSM<DQK, FIX>(pA0, pA1, m_reg, mnA, alA, mC); }
.Lfast96b_nl:
	s_and_saveexec_b64 s[14:15], s[10:11]
	v_mfma_f32_32x32x16_bf16 v[32:47], v[10:13], v[206:209], v[32:47]
	v_add_f32_e32 v0, v96, v0
	v_add_f32_e32 v0, v97, v0
	v_exp_f32_e32 v64, v64
	v_exp_f32_e32 v65, v65
	v_mfma_f32_32x32x16_bf16 v[32:47], v[152:155], v[210:213], v[32:47]
	v_add_f32_e32 v0, v98, v0
	v_add_f32_e32 v0, v99, v0
	v_exp_f32_e32 v66, v66
	v_exp_f32_e32 v67, v67
	v_mfma_f32_32x32x16_bf16 v[32:47], v[156:159], v[214:217], v[32:47]
	v_add_f32_e32 v0, v100, v0
	v_add_f32_e32 v0, v101, v0
	v_exp_f32_e32 v68, v68
	v_exp_f32_e32 v69, v69
	v_mfma_f32_32x32x16_bf16 v[32:47], v[160:163], v[218:221], v[32:47]
	v_add_f32_e32 v0, v102, v0
	v_add_f32_e32 v0, v103, v0
	v_exp_f32_e32 v70, v70
	v_exp_f32_e32 v71, v71
	s_waitcnt lgkmcnt(6)
	v_mfma_f32_32x32x16_bf16 v[16:31], v[10:13], v[238:241], v[16:31]
	v_add_f32_e32 v0, v104, v0
	v_add_f32_e32 v0, v105, v0
	v_exp_f32_e32 v72, v72
	v_exp_f32_e32 v73, v73
	s_waitcnt lgkmcnt(4)
	v_mfma_f32_32x32x16_bf16 v[16:31], v[152:155], v[242:245], v[16:31]
	v_add_f32_e32 v0, v106, v0
	v_add_f32_e32 v0, v107, v0
	v_exp_f32_e32 v74, v74
	v_exp_f32_e32 v75, v75
	s_waitcnt lgkmcnt(2)
	v_mfma_f32_32x32x16_bf16 v[16:31], v[156:159], v[246:249], v[16:31]
	v_add_f32_e32 v0, v108, v0
	v_add_f32_e32 v0, v109, v0
	v_exp_f32_e32 v76, v76
	v_exp_f32_e32 v77, v77
	s_waitcnt lgkmcnt(0)
	v_mfma_f32_32x32x16_bf16 v[16:31], v[160:163], v[250:253], v[16:31]
	v_add_f32_e32 v0, v110, v0
	v_add_f32_e32 v0, v111, v0
	v_exp_f32_e32 v78, v78
	v_exp_f32_e32 v79, v79
	v_mov_b32_e32 v222, v0
	s_nop 1
	v_permlane32_swap_b32_e32 v0, v222
	v_add_f32_e32 v0, v0, v222
	v_add_f32_e32 v198, v198, v0
	s_branch .LBB0_911

; #define SBAR() __builtin_amdgcn_sched_barrier(0)
; #define SLOAD(i, key0) do { sr_[i].v = *reinterpret_cast<const bf16x8*>(&Vh[(long)((key0) + vr) * ldv + vc]); \
;     sr_[i].k0 = *reinterpret_cast<const bf16x8*>(&Kh[(long)((key0) + kr0) * ldk + kc0]); \
;     if (k2) sr_[i].k1 = *reinterpret_cast<const bf16x8*>(&Kh[(long)((key0) + kr1) * ldk + kc1]); } while (0)
; __device__ __forceinline__ void finishSM(f32x16& p0, f32x16& p1, float alpha, float& l_reg, bf16x8& pa0, bf16x8& pa1, bf16x8& pa2, bf16x8& pa3) {
; #pragma unroll
;   for (int r = 0; r < 16; ++r) p1[r] = __builtin_amdgcn_exp2f(p1[r]);
;   float ps = 0;
; #pragma unroll
;   for (int r = 0; r < 16; ++r) ps += p0[r];
; #pragma unroll
;   for (int r = 0; r < 16; ++r) ps += p1[r];
;   { auto rr = __builtin_amdgcn_permlane32_swap(__float_as_uint(ps), __float_as_uint(ps), false, false);
;     ps = __uint_as_float(rr[0]) + __uint_as_float(rr[1]); }
;   l_reg = l_reg * alpha + ps;
;     ...
;   PK4(p0, 0, pa0); PK4(p0, 8, pa1); PK4(p1, 0, pa2); PK4(p1, 8, pa3);
; template <int DQK, bool FIX>
; __device__ __forceinline__ void attn_item(const bf16* Qb, const bf16* __restrict__ Kh, const bf16* __restrict__ Vh,
;                                           u16* Ob, int q0, int L, int NT, char* lds, float mC) {
;     ...
;     if (act) { SBAR(); qkt<DQK>(pA0, pA1, K_lds, qr, r32, hi, (j + 1) * KVBLK, L);
;       finishSM(pB0, pB1, alB, l_reg, pa0, pa1, pa2, pa3); SBAR(); }
;     if (j + 3 < NT) SLOAD(SE, (j + 3) * KVBLK); SBAR();
.LBB0_902:
	v_add_f32_e32 v0, 0, v80
	v_add_f32_e32 v0, v81, v0
	v_add_f32_e32 v0, v82, v0
	v_add_f32_e32 v0, v83, v0
	v_add_f32_e32 v0, v84, v0
	v_add_f32_e32 v0, v85, v0
	v_add_f32_e32 v0, v86, v0
	v_add_f32_e32 v0, v87, v0
	v_add_f32_e32 v0, v88, v0
	v_add_f32_e32 v0, v89, v0
	v_add_f32_e32 v0, v90, v0
	v_add_f32_e32 v0, v91, v0
	v_exp_f32_e32 v96, v96
	v_add_f32_e32 v0, v92, v0
	v_exp_f32_e32 v97, v97
	v_add_f32_e32 v0, v93, v0
	v_exp_f32_e32 v98, v98
	v_add_f32_e32 v0, v94, v0
	v_exp_f32_e32 v99, v99
	v_add_f32_e32 v0, v95, v0
	v_exp_f32_e32 v100, v100
	v_add_f32_e32 v0, v96, v0
	v_exp_f32_e32 v101, v101
	v_add_f32_e32 v0, v97, v0
	v_exp_f32_e32 v102, v102
	v_add_f32_e32 v0, v98, v0
	v_exp_f32_e32 v103, v103
	v_add_f32_e32 v0, v99, v0
	v_exp_f32_e32 v104, v104
	v_add_f32_e32 v0, v100, v0
	v_exp_f32_e32 v105, v105
	v_add_f32_e32 v0, v101, v0
	v_exp_f32_e32 v106, v106
	v_add_f32_e32 v0, v102, v0
	v_exp_f32_e32 v107, v107
	v_add_f32_e32 v0, v103, v0
	v_exp_f32_e32 v108, v108
	v_add_f32_e32 v0, v104, v0
	v_exp_f32_e32 v109, v109
	v_add_f32_e32 v0, v105, v0
	v_exp_f32_e32 v110, v110
	v_add_f32_e32 v0, v106, v0
	v_exp_f32_e32 v111, v111
	v_add_f32_e32 v0, v107, v0
	v_add_f32_e32 v0, v108, v0
	v_add_f32_e32 v0, v109, v0
	v_add_f32_e32 v0, v110, v0
	v_add_f32_e32 v0, v111, v0
	v_mov_b32_e32 v10, v0
	s_nop 1
	v_permlane32_swap_b32_e32 v0, v10
	v_add_f32_e32 v0, v0, v10
	v_cvt_pk_bf16_f32 v10, v80, v81
	v_cvt_pk_bf16_f32 v11, v82, v83
	v_cvt_pk_bf16_f32 v12, v84, v85
	v_cvt_pk_bf16_f32 v13, v86, v87
	v_cvt_pk_bf16_f32 v152, v88, v89
	v_cvt_pk_bf16_f32 v153, v90, v91
	v_cvt_pk_bf16_f32 v154, v92, v93
	v_cvt_pk_bf16_f32 v155, v94, v95
	v_cvt_pk_bf16_f32 v156, v96, v97
	v_cvt_pk_bf16_f32 v157, v98, v99
	v_cvt_pk_bf16_f32 v158, v100, v101
	v_cvt_pk_bf16_f32 v159, v102, v103
	v_cvt_pk_bf16_f32 v160, v104, v105
	v_cvt_pk_bf16_f32 v161, v106, v107
	v_cvt_pk_bf16_f32 v162, v108, v109
	v_cvt_pk_bf16_f32 v163, v110, v111
	v_add_f32_e32 v198, v198, v0
.LBB0_903:
	s_or_b64 exec, exec, s[2:3]
	s_cmp_ge_u32 s79, s97
	s_cselect_b64 s[2:3], -1, 0
	s_and_b64 vcc, exec, s[2:3]
	s_cbranch_vccnz .LBB0_907
	v_add_co_u32_e32 v14, vcc, 0xa160000, v14
	global_load_dwordx4 v[144:147], v[170:171], off
	s_nop 0
	v_addc_co_u32_e32 v15, vcc, 0, v15, vcc
	global_load_dwordx4 v[148:151], v[14:15], off
	s_and_saveexec_b64 s[14:15], s[8:9]
	s_cbranch_execz .LBB0_906
	v_lshl_add_u64 v[14:15], v[166:167], 0, s[6:7]
	v_add_co_u32_e32 v14, vcc, 0xa160000, v14
	s_nop 1
	v_addc_co_u32_e32 v15, vcc, 0, v15, vcc
	global_load_dwordx4 v[136:139], v[14:15], off

; __device__ __forceinline__ void finishSM(f32x16& p0, f32x16& p1, float alpha, float& l_reg, bf16x8& pa0, bf16x8& pa1, bf16x8& pa2, bf16x8& pa3) {
; #pragma unroll
;   for (int r = 0; r < 16; ++r) p1[r] = __builtin_amdgcn_exp2f(p1[r]);
;   float ps = 0;
; #pragma unroll
;   for (int r = 0; r < 16; ++r) ps += p0[r];
; #pragma unroll
;   for (int r = 0; r < 16; ++r) ps += p1[r];
;   { auto rr = __builtin_amdgcn_permlane32_swap(__float_as_uint(ps), __float_as_uint(ps), false, false);
;     ps = __uint_as_float(rr[0]) + __uint_as_float(rr[1]); }
;   l_reg = l_reg * alpha + ps;
;     ...
;   PK4(p0, 0, pa0); PK4(p0, 8, pa1); PK4(p1, 0, pa2); PK4(p1, 8, pa3);
;     ...
; }
; template <int DQK>
; __device__ __forceinline__ void qkt(f32x16& p0, f32x16& p1, const bf16* Ks, const bf16x8* qr, int r32, int hi, int k0, int L) {
;   p0 = f32x16{}; p1 = f32x16{};
; #pragma unroll
;   for (int d0 = 0; d0 < DQK / 16; ++d0) { int cb = (d0 * 16 + hi * 8) * 2;
;     bf16x8 b0 = *reinterpret_cast<const bf16x8*>((const char*)Ks + KSWZ(r32, cb));
;     bf16x8 b1 = *reinterpret_cast<const bf16x8*>((const char*)Ks + KSWZ(32 + r32, cb));
;     p0 = __builtin_amdgcn_mfma_f32_32x32x16_bf16(b0, qr[d0], p0, 0, 0, 0);
;     p1 = __builtin_amdgcn_mfma_f32_32x32x16_bf16(b1, qr[d0], p1, 0, 0, 0); }
;   if (k0 + KVBLK > L) {
; #pragma unroll
;     for (int r = 0; r < 16; ++r) { const int key = k0 + crow(r, hi);
;       if (key >= L) p0[r] = -1e30f;
;       if (key + 32 >= L) p1[r] = -1e30f; }
;   }
; }
; __device__ __forceinline__ int v_st(int k, int c) { const int kk = (k & ~0xC) | ((k & 4) << 1) | ((k & 8) >> 1); return ((kk >> 3) * 4 + (c >> 5)) * 512 + ((kk & 7) * 32 + (c & 31)) * 2; }
; __device__ __forceinline__ int v_rd_base(int lane) { return ((lane & 3) << 3) | (((lane >> 2) & 3) << 6) | (((lane >> 4) & 1) << 5) | (((lane >> 5) & 1) << 8); }
; template <int OFF> __device__ __forceinline__ s16x4 tr_read(int vb) {
;   s16x4 r; asm volatile("ds_read_b64_tr_b16 %0, %1 offset:%2" : "=&v"(r) : "v"(vb), "i"(OFF) : "memory"); return r;
; }
; template <int D0> __device__ __forceinline__ void pv_one(f32x16& od, int vb, bf16x8 pa0, bf16x8 pa1, bf16x8 pa2, bf16x8 pa3) {
;   const s16x4 l0 = tr_read<v_rd_off(D0, 0, 0)>(vb), h0 = tr_read<v_rd_off(D0, 0, 1)>(vb), l1 = tr_read<v_rd_off(D0, 1, 0)>(vb), h1 = tr_read<v_rd_off(D0, 1, 1)>(vb);
.LBB0_911:
	s_or_b64 exec, exec, s[14:15]
	s_barrier
	s_waitcnt vmcnt(2)
	s_and_b64 vcc, exec, s[2:3]
	s_cbranch_vccz .Lt96b_w
	s_waitcnt vmcnt(0)
.Lt96b_w:
	ds_write_b128 v193, v[2:5] offset:16384
	ds_write_b128 v194, v[6:9] offset:49152
	s_and_saveexec_b64 s[14:15], s[8:9]
	s_cbranch_execz .LBB0_882
	ds_write_b128 v195, v[140:143] offset:49152
	s_branch .LBB0_882
.LBB0_913:
	s_and_saveexec_b64 s[2:3], s[10:11]
	s_cbranch_execz .LBB0_915
	v_add_f32_e32 v2, 0, v64
	v_add_f32_e32 v2, v65, v2
	v_add_f32_e32 v2, v66, v2
	v_add_f32_e32 v2, v67, v2
	v_add_f32_e32 v2, v68, v2
	v_add_f32_e32 v2, v69, v2
	v_add_f32_e32 v2, v70, v2
	v_add_f32_e32 v2, v71, v2
	v_add_f32_e32 v2, v72, v2
	v_add_f32_e32 v2, v73, v2
	v_add_f32_e32 v2, v74, v2
	v_add_f32_e32 v2, v75, v2
	v_exp_f32_e32 v0, v48
	v_add_f32_e32 v2, v76, v2
	v_exp_f32_e32 v10, v49
	v_add_f32_e32 v2, v77, v2
	v_exp_f32_e32 v11, v50
	v_add_f32_e32 v2, v78, v2
	v_exp_f32_e32 v12, v51
	v_add_f32_e32 v2, v79, v2
	v_exp_f32_e32 v13, v52
	v_add_f32_e32 v2, v0, v2
	v_exp_f32_e32 v14, v53
	v_add_f32_e32 v2, v10, v2
	v_exp_f32_e32 v15, v54
	v_add_f32_e32 v2, v11, v2
	v_exp_f32_e32 v48, v55
	v_add_f32_e32 v2, v12, v2
	v_exp_f32_e32 v49, v56
	v_add_f32_e32 v2, v13, v2
	v_exp_f32_e32 v50, v57
	v_add_f32_e32 v2, v14, v2
	v_exp_f32_e32 v51, v58
	v_add_f32_e32 v2, v15, v2
	v_exp_f32_e32 v52, v59
	v_add_f32_e32 v2, v48, v2
	v_exp_f32_e32 v53, v60
	v_add_f32_e32 v2, v49, v2
	v_exp_f32_e32 v54, v61
	v_add_f32_e32 v2, v50, v2
	v_exp_f32_e32 v55, v62
	v_add_f32_e32 v2, v51, v2
	v_exp_f32_e32 v56, v63
	v_add_f32_e32 v2, v52, v2
	v_add_f32_e32 v2, v53, v2
	v_add_f32_e32 v2, v54, v2
	v_add_f32_e32 v2, v55, v2
	v_add_f32_e32 v2, v56, v2
	v_mov_b32_e32 v3, v2
	s_nop 1
	v_permlane32_swap_b32_e32 v2, v3
	v_add_f32_e32 v2, v2, v3
	v_add_f32_e32 v198, v198, v2
	v_cvt_pk_bf16_f32 v2, v64, v65
	v_cvt_pk_bf16_f32 v3, v66, v67
	v_cvt_pk_bf16_f32 v4, v68, v69
	v_cvt_pk_bf16_f32 v5, v70, v71
	v_cvt_pk_bf16_f32 v6, v72, v73
	v_cvt_pk_bf16_f32 v7, v74, v75
	v_cvt_pk_bf16_f32 v8, v76, v77
	v_cvt_pk_bf16_f32 v9, v78, v79
	v_cvt_pk_bf16_f32 v10, v0, v10
	v_cvt_pk_bf16_f32 v11, v11, v12
	v_cvt_pk_bf16_f32 v12, v13, v14
	v_cvt_pk_bf16_f32 v13, v15, v48
	v_cvt_pk_bf16_f32 v48, v49, v50
	v_cvt_pk_bf16_f32 v49, v51, v52
	v_cvt_pk_bf16_f32 v50, v53, v54
	v_cvt_pk_bf16_f32 v51, v55, v56
	ds_read_b64_tr_b16 v[52:53], v197 offset:0
	ds_read_b64_tr_b16 v[54:55], v197 offset:0x800
	ds_read_b64_tr_b16 v[56:57], v197 offset:0x1000
	ds_read_b64_tr_b16 v[58:59], v197 offset:0x1800
	ds_read_b64_tr_b16 v[60:61], v197 offset:0x2000
	ds_read_b64_tr_b16 v[62:63], v197 offset:0x2800
	ds_read_b64_tr_b16 v[64:65], v197 offset:0x3000
	ds_read_b64_tr_b16 v[66:67], v197 offset:0x3800
	s_waitcnt lgkmcnt(0)
	s_nop 0
	v_mfma_f32_32x32x16_bf16 v[32:47], v[2:5], v[52:55], v[32:47]
	ds_read_b64_tr_b16 v[52:53], v197 offset:0x200
	ds_read_b64_tr_b16 v[54:55], v197 offset:0xa00
	v_mfma_f32_32x32x16_bf16 v[32:47], v[6:9], v[56:59], v[32:47]
	ds_read_b64_tr_b16 v[56:57], v197 offset:0x1200
	ds_read_b64_tr_b16 v[58:59], v197 offset:0x1a00
	v_mfma_f32_32x32x16_bf16 v[32:47], v[10:13], v[60:63], v[32:47]
	ds_read_b64_tr_b16 v[60:61], v197 offset:0x2200
	ds_read_b64_tr_b16 v[62:63], v197 offset:0x2a00
	v_mfma_f32_32x32x16_bf16 v[32:47], v[48:51], v[64:67], v[32:47]
	ds_read_b64_tr_b16 v[64:65], v197 offset:0x3200
	ds_read_b64_tr_b16 v[66:67], v197 offset:0x3a00
	s_waitcnt lgkmcnt(0)
	v_mfma_f32_32x32x16_bf16 v[16:31], v[2:5], v[52:55], v[16:31]
	v_mfma_f32_32x32x16_bf16 v[16:31], v[6:9], v[56:59], v[16:31]
	v_mfma_f32_32x32x16_bf16 v[16:31], v[10:13], v[60:63], v[16:31]
	v_mfma_f32_32x32x16_bf16 v[16:31], v[48:51], v[64:67], v[16:31]

; #define ROWSUM4(v) do { v += __shfl_xor(v, 16); v += __shfl_xor(v, 32); } while (0)
; template <int EPI>
; __device__ __forceinline__ void gemm_run(const GD& c, const bool has_next, const GD& nx, const Ctx& e, bf16* shm, float* rs, float* rs_nxt, float* racc_) {
;     ...
;   } else if constexpr (EPI == EPI_RESID) {
;     const float sc = e.resid_scale;
;     ROWLOOP { const int lrow = LROW; const long row = brow + lrow; float ss = 0.f;
;       long orow = -1;
;       if (e.final_) {
;         int ri = (int)row;
;         if (ri < ROWS_P) { int s = ri / LP, pos = ri - s * LP; if (pos >= 16) orow = (long)s * 4096 + pos - 16; }
;         else if (ri < TREAL) { int q = ri - ROWS_P; int s = q / LS, pos = q - s * LS; if (pos >= 16) orow = 65536L + (long)s * 8192 + pos - 16; }
;       }
; #pragma unroll
;       for (int bj = 0; bj < 2; ++bj) {
;         const int col = bcol + bj * 128 + wc * 32 + cq8;
;         const long idx = row * 1024 + col;
;         const uint4 hh = *reinterpret_cast<const uint4*>(e.hb + idx);
;         float h[8];
;         h[0] = BFLO(hh.x) + sc * acc[ai][bj][m][0][0]; h[1] = BFHI(hh.x) + sc * acc[ai][bj][m][0][1];
;         h[2] = BFLO(hh.y) + sc * acc[ai][bj][m][0][2]; h[3] = BFHI(hh.y) + sc * acc[ai][bj][m][0][3];
;         h[4] = BFLO(hh.z) + sc * acc[ai][bj][m][1][0]; h[5] = BFHI(hh.z) + sc * acc[ai][bj][m][1][1];
;         h[6] = BFLO(hh.w) + sc * acc[ai][bj][m][1][2]; h[7] = BFHI(hh.w) + sc * acc[ai][bj][m][1][3];
;         if (e.final_) { if (orow >= 0) { *reinterpret_cast<float4*>(e.out + orow * 1024 + col) = make_float4(h[0], h[1], h[2], h[3]);
;                                          *reinterpret_cast<float4*>(e.out + orow * 1024 + col + 4) = make_float4(h[4], h[5], h[6], h[7]); } }
;         else { const uint4 pk = PK8(h[0], h[1], h[2], h[3], h[4], h[5], h[6], h[7]); *reinterpret_cast<uint4*>(e.hb + idx) = pk;
;                const float q0 = BFLO(pk.x), q1 = BFHI(pk.x), q2 = BFLO(pk.y), q3 = BFHI(pk.y), q4 = BFLO(pk.z), q5 = BFHI(pk.z), q6 = BFLO(pk.w), q7 = BFHI(pk.w);
;                ss += (q0 * q0 + q1 * q1 + q2 * q2 + q3 * q3) + (q4 * q4 + q5 * q5 + q6 * q6 + q7 * q7); }
;       }
;       if (!e.final_) { ROWSUM4(ss); if (fq == 0) racc[wc * 256 + lrow] = ss; }
;     }
;     if (!e.final_) { __syncthreads(); if (t2 < 256) e.rpart[(long)(brow + t2) * 4 + pn] = (racc[t2] + racc[256 + t2]) + (racc[512 + t2] + racc[768 + t2]); }
.LBB0_1040:
	v_mov_b32_e32 v0, v165
	s_movk_i32 s5, 0xffc0
	v_and_b32_e32 v130, 15, v0
	v_ashrrev_i32_e32 v134, 2, v0
	v_bfe_u32 v131, v0, 6, 2
	v_bfe_u32 v132, v0, 4, 2
	v_and_or_b32 v134, v134, s5, v130
	v_lshlrev_b32_e32 v133, 3, v132
	v_lshlrev_b32_e32 v130, 5, v131
	v_cmp_eq_u32_e32 vcc, 0, v132
	v_add_u32_e32 v132, s14, v134
	v_or3_b32 v130, v130, v133, s4
	v_ashrrev_i32_e32 v133, 31, v132
	v_readlane_b32 s4, v254, 25
	v_lshlrev_b64 v[136:137], 11, v[132:133]
	v_lshl_add_u64 v[136:137], s[8:9], 0, v[136:137]
	v_lshl_add_u32 v135, v131, 10, s4
	v_ashrrev_i32_e32 v131, 31, v130
	v_lshl_add_u64 v[142:143], v[130:131], 1, v[136:137]
	v_mov_b32_e32 v160, 0x8000
	v_mov_b32_e32 v161, 0
	v_mov_b32_e32 v162, 0x40000
	v_mov_b32_e32 v163, 0
	v_lshl_add_u64 v[146:147], v[142:143], 0, v[160:161]
	v_lshl_add_u64 v[148:149], v[146:147], 0, v[160:161]
	v_lshl_add_u64 v[150:151], v[148:149], 0, v[160:161]
	v_lshl_add_u64 v[152:153], v[142:143], 0, v[162:163]
	v_lshl_add_u64 v[154:155], v[146:147], 0, v[162:163]
	v_lshl_add_u64 v[156:157], v[148:149], 0, v[162:163]
	v_lshl_add_u64 v[158:159], v[150:151], 0, v[162:163]
	global_load_dwordx4 v[186:189], v[142:143], off
	global_load_dwordx4 v[190:193], v[142:143], off offset:256
	global_load_dwordx4 v[194:197], v[146:147], off
	global_load_dwordx4 v[198:201], v[146:147], off offset:256
	global_load_dwordx4 v[202:205], v[148:149], off
	global_load_dwordx4 v[206:209], v[148:149], off offset:256
	global_load_dwordx4 v[210:213], v[150:151], off
	global_load_dwordx4 v[214:217], v[150:151], off offset:256
	global_load_dwordx4 v[218:221], v[152:153], off
	global_load_dwordx4 v[222:225], v[152:153], off offset:256
	global_load_dwordx4 v[226:229], v[154:155], off
	global_load_dwordx4 v[230:233], v[154:155], off offset:256
	global_load_dwordx4 v[234:237], v[156:157], off
	global_load_dwordx4 v[238:241], v[156:157], off offset:256
	global_load_dwordx4 v[242:245], v[158:159], off
	global_load_dwordx4 v[246:249], v[158:159], off offset:256
	s_waitcnt vmcnt(15)
	v_mov_b64_e32 v[136:137], v[186:187]
	v_mov_b64_e32 v[138:139], v[188:189]
	v_lshlrev_b32_e32 v144, 16, v136
	v_and_b32_e32 v145, 0xffff0000, v136
	v_lshlrev_b32_e32 v136, 16, v137
	v_and_b32_e32 v137, 0xffff0000, v137
	v_pk_add_f32 v[128:129], v[128:129], v[136:137]
	v_lshlrev_b32_e32 v136, 16, v138
	v_and_b32_e32 v137, 0xffff0000, v138
	v_pk_add_f32 v[136:137], v[122:123], v[136:137]
	v_lshlrev_b32_e32 v122, 16, v139
	v_and_b32_e32 v123, 0xffff0000, v139
	v_pk_add_f32 v[126:127], v[126:127], v[144:145]
	v_pk_add_f32 v[138:139], v[124:125], v[122:123]
	v_cvt_pk_bf16_f32 v122, v126, v127
	v_cvt_pk_bf16_f32 v123, v128, v129
	v_cvt_pk_bf16_f32 v124, v136, v137
	v_cvt_pk_bf16_f32 v125, v138, v139
	global_store_dwordx4 v[142:143], v[122:125], off
	v_lshlrev_b32_e32 v126, 16, v122
	v_lshlrev_b32_e32 v127, 16, v123
	v_and_b32_e32 v122, 0xffff0000, v122
	v_mul_f32_e32 v122, v122, v122
	v_fmac_f32_e32 v122, v126, v126
	v_and_b32_e32 v123, 0xffff0000, v123
	v_lshlrev_b32_e32 v128, 16, v124
	v_and_b32_e32 v124, 0xffff0000, v124
	v_fmac_f32_e32 v122, v127, v127
	v_fmac_f32_e32 v122, v123, v123
	v_mul_f32_e32 v123, v124, v124
	v_lshlrev_b32_e32 v129, 16, v125
	v_fmac_f32_e32 v123, v128, v128
	v_and_b32_e32 v125, 0xffff0000, v125
	v_fmac_f32_e32 v123, v129, v129
	v_fmac_f32_e32 v123, v125, v125
	v_add_f32_e32 v128, v122, v123
	s_waitcnt vmcnt(15)
	v_mov_b64_e32 v[122:123], v[190:191]
	v_mov_b64_e32 v[124:125], v[192:193]
	v_lshlrev_b32_e32 v126, 16, v122
	v_and_b32_e32 v127, 0xffff0000, v122
	v_lshlrev_b32_e32 v122, 16, v123
	v_and_b32_e32 v123, 0xffff0000, v123
	v_pk_add_f32 v[120:121], v[120:121], v[122:123]
	v_lshlrev_b32_e32 v122, 16, v124
	v_and_b32_e32 v123, 0xffff0000, v124
	v_pk_add_f32 v[122:123], v[114:115], v[122:123]
	v_lshlrev_b32_e32 v114, 16, v125
	v_and_b32_e32 v115, 0xffff0000, v125
	v_pk_add_f32 v[118:119], v[118:119], v[126:127]
	v_pk_add_f32 v[124:125], v[116:117], v[114:115]
	v_cvt_pk_bf16_f32 v114, v118, v119
	v_cvt_pk_bf16_f32 v115, v120, v121
	v_cvt_pk_bf16_f32 v116, v122, v123
	v_cvt_pk_bf16_f32 v117, v124, v125
	global_store_dwordx4 v[142:143], v[114:117], off offset:256
	v_lshlrev_b32_e32 v118, 16, v114
	v_lshlrev_b32_e32 v119, 16, v115
	v_and_b32_e32 v114, 0xffff0000, v114
	v_mul_f32_e32 v114, v114, v114
	v_fmac_f32_e32 v114, v118, v118
	v_and_b32_e32 v115, 0xffff0000, v115
	v_lshlrev_b32_e32 v120, 16, v116
	v_and_b32_e32 v116, 0xffff0000, v116
	v_fmac_f32_e32 v114, v119, v119
	v_fmac_f32_e32 v114, v115, v115
	v_mul_f32_e32 v115, v116, v116
	v_lshlrev_b32_e32 v121, 16, v117
	v_fmac_f32_e32 v115, v120, v120
	v_and_b32_e32 v117, 0xffff0000, v117
	v_fmac_f32_e32 v115, v121, v121
	v_fmac_f32_e32 v115, v117, v117
	v_and_b32_e32 v116, 64, v180
	v_add_f32_e32 v114, v114, v115
	v_xor_b32_e32 v115, 16, v180
	v_add_u32_e32 v117, 64, v116
	v_cmp_lt_i32_e64 s[4:5], v115, v117
	v_add_f32_e32 v114, v128, v114
	s_nop 0
	v_cndmask_b32_e64 v115, v180, v115, s[4:5]
	v_lshlrev_b32_e32 v116, 2, v115
	ds_bpermute_b32 v115, v116, v114
	s_waitcnt lgkmcnt(0)
	v_add_f32_e32 v114, v114, v115
	v_xor_b32_e32 v115, 32, v180
	v_cmp_lt_i32_e64 s[4:5], v115, v117
	v_lshl_add_u32 v117, v134, 2, v135
	s_nop 0
	v_cndmask_b32_e64 v115, v180, v115, s[4:5]
	v_lshlrev_b32_e32 v118, 2, v115
	ds_bpermute_b32 v115, v118, v114
	s_and_saveexec_b64 s[4:5], vcc
	s_cbranch_execz .LBB0_1042
	s_waitcnt lgkmcnt(0)
	v_add_f32_e32 v114, v114, v115
	ds_write_b32 v117, v114
; #define ROWSUM4(v) do { v += __shfl_xor(v, 16); v += __shfl_xor(v, 32); } while (0)
; template <int EPI>
; __device__ __forceinline__ void gemm_run(const GD& c, const bool has_next, const GD& nx, const Ctx& e, bf16* shm, float* rs, float* rs_nxt, float* racc_) {
;     ...
;   } else if constexpr (EPI == EPI_RESID) {
;     const float sc = e.resid_scale;
;     ROWLOOP { const int lrow = LROW; const long row = brow + lrow; float ss = 0.f;
;       long orow = -1;
;       if (e.final_) {
;         int ri = (int)row;
;         if (ri < ROWS_P) { int s = ri / LP, pos = ri - s * LP; if (pos >= 16) orow = (long)s * 4096 + pos - 16; }
;         else if (ri < TREAL) { int q = ri - ROWS_P; int s = q / LS, pos = q - s * LS; if (pos >= 16) orow = 65536L + (long)s * 8192 + pos - 16; }
;       }
; #pragma unroll
;       for (int bj = 0; bj < 2; ++bj) {
;         const int col = bcol + bj * 128 + wc * 32 + cq8;
;         const long idx = row * 1024 + col;
;         const uint4 hh = *reinterpret_cast<const uint4*>(e.hb + idx);
;         float h[8];
;         h[0] = BFLO(hh.x) + sc * acc[ai][bj][m][0][0]; h[1] = BFHI(hh.x) + sc * acc[ai][bj][m][0][1];
;         h[2] = BFLO(hh.y) + sc * acc[ai][bj][m][0][2]; h[3] = BFHI(hh.y) + sc * acc[ai][bj][m][0][3];
;         h[4] = BFLO(hh.z) + sc * acc[ai][bj][m][1][0]; h[5] = BFHI(hh.z) + sc * acc[ai][bj][m][1][1];
;         h[6] = BFLO(hh.w) + sc * acc[ai][bj][m][1][2]; h[7] = BFHI(hh.w) + sc * acc[ai][bj][m][1][3];
;         if (e.final_) { if (orow >= 0) { *reinterpret_cast<float4*>(e.out + orow * 1024 + col) = make_float4(h[0], h[1], h[2], h[3]);
;                                          *reinterpret_cast<float4*>(e.out + orow * 1024 + col + 4) = make_float4(h[4], h[5], h[6], h[7]); } }
;         else { const uint4 pk = PK8(h[0], h[1], h[2], h[3], h[4], h[5], h[6], h[7]); *reinterpret_cast<uint4*>(e.hb + idx) = pk;
;                const float q0 = BFLO(pk.x), q1 = BFHI(pk.x), q2 = BFLO(pk.y), q3 = BFHI(pk.y), q4 = BFLO(pk.z), q5 = BFHI(pk.z), q6 = BFLO(pk.w), q7 = BFHI(pk.w);
;                ss += (q0 * q0 + q1 * q1 + q2 * q2 + q3 * q3) + (q4 * q4 + q5 * q5 + q6 * q6 + q7 * q7); }
;       }
;       if (!e.final_) { ROWSUM4(ss); if (fq == 0) racc[wc * 256 + lrow] = ss; }
;     }
;     if (!e.final_) { __syncthreads(); if (t2 < 256) e.rpart[(long)(brow + t2) * 4 + pn] = (racc[t2] + racc[256 + t2]) + (racc[512 + t2] + racc[768 + t2]); }
.LBB0_1042:
	s_or_b64 exec, exec, s[4:5]
	v_add3_u32 v114, s14, v134, 16
	s_waitcnt lgkmcnt(0)
	v_ashrrev_i32_e32 v115, 31, v114
	v_lshlrev_b64 v[114:115], 11, v[114:115]
	v_lshl_add_u64 v[114:115], s[8:9], 0, v[114:115]
	v_lshl_add_u64 v[114:115], v[130:131], 1, v[114:115]
	s_waitcnt vmcnt(15)
	v_mov_b64_e32 v[120:121], v[194:195]
	v_mov_b64_e32 v[122:123], v[196:197]
	v_lshlrev_b32_e32 v124, 16, v120
	v_and_b32_e32 v125, 0xffff0000, v120
	v_lshlrev_b32_e32 v120, 16, v121
	v_and_b32_e32 v121, 0xffff0000, v121
	v_pk_add_f32 v[112:113], v[112:113], v[120:121]
	v_lshlrev_b32_e32 v120, 16, v122
	v_and_b32_e32 v121, 0xffff0000, v122
	v_pk_add_f32 v[120:121], v[106:107], v[120:121]
	v_lshlrev_b32_e32 v106, 16, v123
	v_and_b32_e32 v107, 0xffff0000, v123
	v_pk_add_f32 v[110:111], v[110:111], v[124:125]
	v_pk_add_f32 v[122:123], v[108:109], v[106:107]
	v_cvt_pk_bf16_f32 v106, v110, v111
	v_cvt_pk_bf16_f32 v107, v112, v113
	v_cvt_pk_bf16_f32 v108, v120, v121
	v_cvt_pk_bf16_f32 v109, v122, v123
	global_store_dwordx4 v[114:115], v[106:109], off
	v_lshlrev_b32_e32 v110, 16, v106
	v_lshlrev_b32_e32 v111, 16, v107
	v_and_b32_e32 v106, 0xffff0000, v106
	v_mul_f32_e32 v106, v106, v106
	v_fmac_f32_e32 v106, v110, v110
	v_and_b32_e32 v107, 0xffff0000, v107
	v_lshlrev_b32_e32 v112, 16, v108
	v_and_b32_e32 v108, 0xffff0000, v108
	v_fmac_f32_e32 v106, v111, v111
	v_fmac_f32_e32 v106, v107, v107
	v_mul_f32_e32 v107, v108, v108
	v_lshlrev_b32_e32 v113, 16, v109
	v_fmac_f32_e32 v107, v112, v112
	v_and_b32_e32 v109, 0xffff0000, v109
	v_fmac_f32_e32 v107, v113, v113
	v_fmac_f32_e32 v107, v109, v109
	v_add_f32_e32 v112, v106, v107
	s_waitcnt vmcnt(15)
	v_mov_b64_e32 v[106:107], v[198:199]
	v_mov_b64_e32 v[108:109], v[200:201]
	v_lshlrev_b32_e32 v110, 16, v106
	v_and_b32_e32 v111, 0xffff0000, v106
	v_lshlrev_b32_e32 v106, 16, v107
	v_and_b32_e32 v107, 0xffff0000, v107
	v_pk_add_f32 v[104:105], v[104:105], v[106:107]
	v_lshlrev_b32_e32 v106, 16, v108
	v_and_b32_e32 v107, 0xffff0000, v108
	v_pk_add_f32 v[106:107], v[98:99], v[106:107]
	v_lshlrev_b32_e32 v98, 16, v109
	v_and_b32_e32 v99, 0xffff0000, v109
	v_pk_add_f32 v[102:103], v[102:103], v[110:111]
	v_pk_add_f32 v[108:109], v[100:101], v[98:99]
	v_cvt_pk_bf16_f32 v98, v102, v103
	v_cvt_pk_bf16_f32 v99, v104, v105
	v_cvt_pk_bf16_f32 v100, v106, v107
	v_cvt_pk_bf16_f32 v101, v108, v109
	global_store_dwordx4 v[114:115], v[98:101], off offset:256
	v_lshlrev_b32_e32 v102, 16, v98
	v_lshlrev_b32_e32 v103, 16, v99
	v_and_b32_e32 v98, 0xffff0000, v98
	v_mul_f32_e32 v98, v98, v98
	v_fmac_f32_e32 v98, v102, v102
	v_and_b32_e32 v99, 0xffff0000, v99
	v_lshlrev_b32_e32 v104, 16, v100
	v_and_b32_e32 v100, 0xffff0000, v100
	v_fmac_f32_e32 v98, v103, v103
	v_fmac_f32_e32 v98, v99, v99
	v_mul_f32_e32 v99, v100, v100
	v_lshlrev_b32_e32 v105, 16, v101
	v_fmac_f32_e32 v99, v104, v104
	v_and_b32_e32 v101, 0xffff0000, v101
	v_fmac_f32_e32 v99, v105, v105
	v_fmac_f32_e32 v99, v101, v101
	v_add_f32_e32 v98, v98, v99
	v_add_f32_e32 v98, v112, v98
	ds_bpermute_b32 v99, v116, v98
	s_waitcnt lgkmcnt(0)
	v_add_f32_e32 v98, v98, v99
	ds_bpermute_b32 v99, v118, v98
	s_and_saveexec_b64 s[4:5], vcc
	s_cbranch_execz .LBB0_1044
	s_waitcnt lgkmcnt(0)
	v_add_f32_e32 v98, v98, v99
	ds_write_b32 v117, v98 offset:64
.LBB0_1044:
	s_or_b64 exec, exec, s[4:5]
	v_add3_u32 v98, s14, v134, 32
	s_waitcnt lgkmcnt(0)
	v_ashrrev_i32_e32 v99, 31, v98
	v_lshlrev_b64 v[98:99], 11, v[98:99]
	v_lshl_add_u64 v[98:99], s[8:9], 0, v[98:99]
	v_lshl_add_u64 v[98:99], v[130:131], 1, v[98:99]
	s_waitcnt vmcnt(15)
	v_mov_b64_e32 v[100:101], v[202:203]
	v_mov_b64_e32 v[102:103], v[204:205]
	v_lshlrev_b32_e32 v104, 16, v100
	v_and_b32_e32 v105, 0xffff0000, v100
	v_lshlrev_b32_e32 v100, 16, v101
	v_and_b32_e32 v101, 0xffff0000, v101
	v_pk_add_f32 v[96:97], v[96:97], v[100:101]
	v_lshlrev_b32_e32 v100, 16, v102
	v_and_b32_e32 v101, 0xffff0000, v102
	v_pk_add_f32 v[100:101], v[90:91], v[100:101]
	v_lshlrev_b32_e32 v90, 16, v103
	v_and_b32_e32 v91, 0xffff0000, v103
	v_pk_add_f32 v[94:95], v[94:95], v[104:105]
	v_pk_add_f32 v[102:103], v[92:93], v[90:91]
	v_cvt_pk_bf16_f32 v90, v94, v95
	v_cvt_pk_bf16_f32 v91, v96, v97
	v_cvt_pk_bf16_f32 v92, v100, v101
	v_cvt_pk_bf16_f32 v93, v102, v103
	global_store_dwordx4 v[98:99], v[90:93], off
	v_lshlrev_b32_e32 v94, 16, v90
	v_lshlrev_b32_e32 v95, 16, v91
	v_and_b32_e32 v90, 0xffff0000, v90
	v_mul_f32_e32 v90, v90, v90
	v_fmac_f32_e32 v90, v94, v94
	v_and_b32_e32 v91, 0xffff0000, v91
	v_lshlrev_b32_e32 v96, 16, v92
	v_and_b32_e32 v92, 0xffff0000, v92
	v_fmac_f32_e32 v90, v95, v95
	v_fmac_f32_e32 v90, v91, v91
	v_mul_f32_e32 v91, v92, v92
	v_lshlrev_b32_e32 v97, 16, v93
	v_fmac_f32_e32 v91, v96, v96
	v_and_b32_e32 v93, 0xffff0000, v93
	v_fmac_f32_e32 v91, v97, v97
	v_fmac_f32_e32 v91, v93, v93
	v_add_f32_e32 v96, v90, v91
	s_waitcnt vmcnt(15)
	v_mov_b64_e32 v[90:91], v[206:207]
	v_mov_b64_e32 v[92:93], v[208:209]
	v_lshlrev_b32_e32 v94, 16, v90
	v_and_b32_e32 v95, 0xffff0000, v90
	v_lshlrev_b32_e32 v90, 16, v91
	v_and_b32_e32 v91, 0xffff0000, v91
	v_pk_add_f32 v[88:89], v[88:89], v[90:91]
	v_lshlrev_b32_e32 v90, 16, v92
	v_and_b32_e32 v91, 0xffff0000, v92
	v_pk_add_f32 v[90:91], v[82:83], v[90:91]
	v_lshlrev_b32_e32 v82, 16, v93
	v_and_b32_e32 v83, 0xffff0000, v93
	v_pk_add_f32 v[86:87], v[86:87], v[94:95]
	v_pk_add_f32 v[92:93], v[84:85], v[82:83]
	v_cvt_pk_bf16_f32 v82, v86, v87
	v_cvt_pk_bf16_f32 v83, v88, v89
	v_cvt_pk_bf16_f32 v84, v90, v91
	v_cvt_pk_bf16_f32 v85, v92, v93
	global_store_dwordx4 v[98:99], v[82:85], off offset:256
	v_lshlrev_b32_e32 v86, 16, v82
	v_lshlrev_b32_e32 v87, 16, v83
	v_and_b32_e32 v82, 0xffff0000, v82
	v_mul_f32_e32 v82, v82, v82
	v_fmac_f32_e32 v82, v86, v86
	v_and_b32_e32 v83, 0xffff0000, v83
	v_lshlrev_b32_e32 v88, 16, v84
	v_and_b32_e32 v84, 0xffff0000, v84
	v_fmac_f32_e32 v82, v87, v87
	v_fmac_f32_e32 v82, v83, v83
	v_mul_f32_e32 v83, v84, v84
	v_lshlrev_b32_e32 v89, 16, v85
	v_fmac_f32_e32 v83, v88, v88
	v_and_b32_e32 v85, 0xffff0000, v85
	v_fmac_f32_e32 v83, v89, v89
	v_fmac_f32_e32 v83, v85, v85
	v_add_f32_e32 v82, v82, v83
	v_add_f32_e32 v82, v96, v82
	ds_bpermute_b32 v83, v116, v82
	s_waitcnt lgkmcnt(0)
	v_add_f32_e32 v82, v82, v83
	ds_bpermute_b32 v83, v118, v82
	s_and_saveexec_b64 s[4:5], vcc
	s_cbranch_execz .LBB0_1046
	s_waitcnt lgkmcnt(0)
	v_add_f32_e32 v82, v82, v83
	ds_write_b32 v117, v82 offset:128
; #define ROWSUM4(v) do { v += __shfl_xor(v, 16); v += __shfl_xor(v, 32); } while (0)
; template <int EPI>
; __device__ __forceinline__ void gemm_run(const GD& c, const bool has_next, const GD& nx, const Ctx& e, bf16* shm, float* rs, float* rs_nxt, float* racc_) {
;     ...
;   } else if constexpr (EPI == EPI_RESID) {
;     const float sc = e.resid_scale;
;     ROWLOOP { const int lrow = LROW; const long row = brow + lrow; float ss = 0.f;
;       long orow = -1;
;       if (e.final_) {
;         int ri = (int)row;
;         if (ri < ROWS_P) { int s = ri / LP, pos = ri - s * LP; if (pos >= 16) orow = (long)s * 4096 + pos - 16; }
;         else if (ri < TREAL) { int q = ri - ROWS_P; int s = q / LS, pos = q - s * LS; if (pos >= 16) orow = 65536L + (long)s * 8192 + pos - 16; }
;       }
; #pragma unroll
;       for (int bj = 0; bj < 2; ++bj) {
;         const int col = bcol + bj * 128 + wc * 32 + cq8;
;         const long idx = row * 1024 + col;
;         const uint4 hh = *reinterpret_cast<const uint4*>(e.hb + idx);
;         float h[8];
;         h[0] = BFLO(hh.x) + sc * acc[ai][bj][m][0][0]; h[1] = BFHI(hh.x) + sc * acc[ai][bj][m][0][1];
;         h[2] = BFLO(hh.y) + sc * acc[ai][bj][m][0][2]; h[3] = BFHI(hh.y) + sc * acc[ai][bj][m][0][3];
;         h[4] = BFLO(hh.z) + sc * acc[ai][bj][m][1][0]; h[5] = BFHI(hh.z) + sc * acc[ai][bj][m][1][1];
;         h[6] = BFLO(hh.w) + sc * acc[ai][bj][m][1][2]; h[7] = BFHI(hh.w) + sc * acc[ai][bj][m][1][3];
;         if (e.final_) { if (orow >= 0) { *reinterpret_cast<float4*>(e.out + orow * 1024 + col) = make_float4(h[0], h[1], h[2], h[3]);
;                                          *reinterpret_cast<float4*>(e.out + orow * 1024 + col + 4) = make_float4(h[4], h[5], h[6], h[7]); } }
;         else { const uint4 pk = PK8(h[0], h[1], h[2], h[3], h[4], h[5], h[6], h[7]); *reinterpret_cast<uint4*>(e.hb + idx) = pk;
;                const float q0 = BFLO(pk.x), q1 = BFHI(pk.x), q2 = BFLO(pk.y), q3 = BFHI(pk.y), q4 = BFLO(pk.z), q5 = BFHI(pk.z), q6 = BFLO(pk.w), q7 = BFHI(pk.w);
;                ss += (q0 * q0 + q1 * q1 + q2 * q2 + q3 * q3) + (q4 * q4 + q5 * q5 + q6 * q6 + q7 * q7); }
;       }
;       if (!e.final_) { ROWSUM4(ss); if (fq == 0) racc[wc * 256 + lrow] = ss; }
;     }
;     if (!e.final_) { __syncthreads(); if (t2 < 256) e.rpart[(long)(brow + t2) * 4 + pn] = (racc[t2] + racc[256 + t2]) + (racc[512 + t2] + racc[768 + t2]); }
.LBB0_1046:
	s_or_b64 exec, exec, s[4:5]
	v_add3_u32 v82, s14, v134, 48
	s_waitcnt lgkmcnt(0)
	v_ashrrev_i32_e32 v83, 31, v82
	v_lshlrev_b64 v[82:83], 11, v[82:83]
	v_lshl_add_u64 v[82:83], s[8:9], 0, v[82:83]
	v_lshl_add_u64 v[82:83], v[130:131], 1, v[82:83]
	s_waitcnt vmcnt(15)
	v_mov_b64_e32 v[84:85], v[210:211]
	v_mov_b64_e32 v[86:87], v[212:213]
	v_lshlrev_b32_e32 v88, 16, v84
	v_and_b32_e32 v89, 0xffff0000, v84
	v_lshlrev_b32_e32 v84, 16, v85
	v_and_b32_e32 v85, 0xffff0000, v85
	v_pk_add_f32 v[80:81], v[80:81], v[84:85]
	v_lshlrev_b32_e32 v84, 16, v86
	v_and_b32_e32 v85, 0xffff0000, v86
	v_pk_add_f32 v[84:85], v[74:75], v[84:85]
	v_lshlrev_b32_e32 v74, 16, v87
	v_and_b32_e32 v75, 0xffff0000, v87
	v_pk_add_f32 v[78:79], v[78:79], v[88:89]
	v_pk_add_f32 v[86:87], v[76:77], v[74:75]
	v_cvt_pk_bf16_f32 v74, v78, v79
	v_cvt_pk_bf16_f32 v75, v80, v81
	v_cvt_pk_bf16_f32 v76, v84, v85
	v_cvt_pk_bf16_f32 v77, v86, v87
	global_store_dwordx4 v[82:83], v[74:77], off
	v_lshlrev_b32_e32 v78, 16, v74
	v_lshlrev_b32_e32 v79, 16, v75
	v_and_b32_e32 v74, 0xffff0000, v74
	v_mul_f32_e32 v74, v74, v74
	v_fmac_f32_e32 v74, v78, v78
	v_and_b32_e32 v75, 0xffff0000, v75
	v_lshlrev_b32_e32 v80, 16, v76
	v_and_b32_e32 v76, 0xffff0000, v76
	v_fmac_f32_e32 v74, v79, v79
	v_fmac_f32_e32 v74, v75, v75
	v_mul_f32_e32 v75, v76, v76
	v_lshlrev_b32_e32 v81, 16, v77
	v_fmac_f32_e32 v75, v80, v80
	v_and_b32_e32 v77, 0xffff0000, v77
	v_fmac_f32_e32 v75, v81, v81
	v_fmac_f32_e32 v75, v77, v77
	v_add_f32_e32 v80, v74, v75
	s_waitcnt vmcnt(15)
	v_mov_b64_e32 v[74:75], v[214:215]
	v_mov_b64_e32 v[76:77], v[216:217]
	v_lshlrev_b32_e32 v78, 16, v74
	v_and_b32_e32 v79, 0xffff0000, v74
	v_lshlrev_b32_e32 v74, 16, v75
	v_and_b32_e32 v75, 0xffff0000, v75
	v_pk_add_f32 v[72:73], v[72:73], v[74:75]
	v_lshlrev_b32_e32 v74, 16, v76
	v_and_b32_e32 v75, 0xffff0000, v76
	v_pk_add_f32 v[74:75], v[66:67], v[74:75]
	v_lshlrev_b32_e32 v66, 16, v77
	v_and_b32_e32 v67, 0xffff0000, v77
	v_pk_add_f32 v[70:71], v[70:71], v[78:79]
	v_pk_add_f32 v[76:77], v[68:69], v[66:67]
	v_cvt_pk_bf16_f32 v66, v70, v71
	v_cvt_pk_bf16_f32 v67, v72, v73
	v_cvt_pk_bf16_f32 v68, v74, v75
	v_cvt_pk_bf16_f32 v69, v76, v77
	global_store_dwordx4 v[82:83], v[66:69], off offset:256
	v_lshlrev_b32_e32 v70, 16, v66
	v_lshlrev_b32_e32 v71, 16, v67
	v_and_b32_e32 v66, 0xffff0000, v66
	v_mul_f32_e32 v66, v66, v66
	v_fmac_f32_e32 v66, v70, v70
	v_and_b32_e32 v67, 0xffff0000, v67
	v_lshlrev_b32_e32 v72, 16, v68
	v_and_b32_e32 v68, 0xffff0000, v68
	v_fmac_f32_e32 v66, v71, v71
	v_fmac_f32_e32 v66, v67, v67
	v_mul_f32_e32 v67, v68, v68
	v_lshlrev_b32_e32 v73, 16, v69
	v_fmac_f32_e32 v67, v72, v72
	v_and_b32_e32 v69, 0xffff0000, v69
	v_fmac_f32_e32 v67, v73, v73
	v_fmac_f32_e32 v67, v69, v69
	v_add_f32_e32 v66, v66, v67
	v_add_f32_e32 v66, v80, v66
	ds_bpermute_b32 v67, v116, v66
	s_waitcnt lgkmcnt(0)
	v_add_f32_e32 v66, v66, v67
	ds_bpermute_b32 v67, v118, v66
	s_and_saveexec_b64 s[4:5], vcc
	s_cbranch_execz .LBB0_1048
	s_waitcnt lgkmcnt(0)
	v_add_f32_e32 v66, v66, v67
	ds_write_b32 v117, v66 offset:192
.LBB0_1048:
	s_or_b64 exec, exec, s[4:5]
	v_add_u32_e32 v66, 0x80, v132
	s_waitcnt lgkmcnt(0)
	v_ashrrev_i32_e32 v67, 31, v66
	v_lshlrev_b64 v[66:67], 11, v[66:67]
	v_lshl_add_u64 v[66:67], s[8:9], 0, v[66:67]
	v_lshl_add_u64 v[66:67], v[130:131], 1, v[66:67]
	s_waitcnt vmcnt(15)
	v_mov_b64_e32 v[68:69], v[218:219]
	v_mov_b64_e32 v[70:71], v[220:221]
	v_lshlrev_b32_e32 v72, 16, v68
	v_and_b32_e32 v73, 0xffff0000, v68
	v_lshlrev_b32_e32 v68, 16, v69
	v_and_b32_e32 v69, 0xffff0000, v69
	v_pk_add_f32 v[64:65], v[64:65], v[68:69]
	v_lshlrev_b32_e32 v68, 16, v70
	v_and_b32_e32 v69, 0xffff0000, v70
	v_pk_add_f32 v[68:69], v[58:59], v[68:69]
	v_lshlrev_b32_e32 v58, 16, v71
	v_and_b32_e32 v59, 0xffff0000, v71
	v_pk_add_f32 v[62:63], v[62:63], v[72:73]
	v_pk_add_f32 v[70:71], v[60:61], v[58:59]
	v_cvt_pk_bf16_f32 v58, v62, v63
	v_cvt_pk_bf16_f32 v59, v64, v65
	v_cvt_pk_bf16_f32 v60, v68, v69
	v_cvt_pk_bf16_f32 v61, v70, v71
	global_store_dwordx4 v[66:67], v[58:61], off
	v_lshlrev_b32_e32 v62, 16, v58
	v_lshlrev_b32_e32 v63, 16, v59
	v_and_b32_e32 v58, 0xffff0000, v58
	v_mul_f32_e32 v58, v58, v58
	v_fmac_f32_e32 v58, v62, v62
	v_and_b32_e32 v59, 0xffff0000, v59
	v_lshlrev_b32_e32 v64, 16, v60
	v_and_b32_e32 v60, 0xffff0000, v60
	v_fmac_f32_e32 v58, v63, v63
	v_fmac_f32_e32 v58, v59, v59
	v_mul_f32_e32 v59, v60, v60
	v_lshlrev_b32_e32 v65, 16, v61
	v_fmac_f32_e32 v59, v64, v64
	v_and_b32_e32 v61, 0xffff0000, v61
	v_fmac_f32_e32 v59, v65, v65
	v_fmac_f32_e32 v59, v61, v61
	v_add_f32_e32 v64, v58, v59
	s_waitcnt vmcnt(15)
	v_mov_b64_e32 v[58:59], v[222:223]
	v_mov_b64_e32 v[60:61], v[224:225]
	v_lshlrev_b32_e32 v62, 16, v58
	v_and_b32_e32 v63, 0xffff0000, v58
	v_lshlrev_b32_e32 v58, 16, v59
	v_and_b32_e32 v59, 0xffff0000, v59
	v_pk_add_f32 v[56:57], v[56:57], v[58:59]
	v_lshlrev_b32_e32 v58, 16, v60
	v_and_b32_e32 v59, 0xffff0000, v60
	v_pk_add_f32 v[58:59], v[50:51], v[58:59]
	v_lshlrev_b32_e32 v50, 16, v61
	v_and_b32_e32 v51, 0xffff0000, v61
	v_pk_add_f32 v[54:55], v[54:55], v[62:63]
	v_pk_add_f32 v[60:61], v[52:53], v[50:51]
	v_cvt_pk_bf16_f32 v50, v54, v55
	v_cvt_pk_bf16_f32 v51, v56, v57
	v_cvt_pk_bf16_f32 v52, v58, v59
	v_cvt_pk_bf16_f32 v53, v60, v61
	global_store_dwordx4 v[66:67], v[50:53], off offset:256
	v_lshlrev_b32_e32 v54, 16, v50
	v_lshlrev_b32_e32 v55, 16, v51
	v_and_b32_e32 v50, 0xffff0000, v50
	v_mul_f32_e32 v50, v50, v50
	v_fmac_f32_e32 v50, v54, v54
	v_and_b32_e32 v51, 0xffff0000, v51
	v_lshlrev_b32_e32 v56, 16, v52
	v_and_b32_e32 v52, 0xffff0000, v52
	v_fmac_f32_e32 v50, v55, v55
	v_fmac_f32_e32 v50, v51, v51
	v_mul_f32_e32 v51, v52, v52
	v_lshlrev_b32_e32 v57, 16, v53
	v_fmac_f32_e32 v51, v56, v56
	v_and_b32_e32 v53, 0xffff0000, v53
	v_fmac_f32_e32 v51, v57, v57
	v_fmac_f32_e32 v51, v53, v53
	v_add_f32_e32 v50, v50, v51
	v_add_f32_e32 v50, v64, v50
	ds_bpermute_b32 v51, v116, v50
	s_waitcnt lgkmcnt(0)
	v_add_f32_e32 v50, v50, v51
	ds_bpermute_b32 v51, v118, v50
	s_and_saveexec_b64 s[4:5], vcc
	s_cbranch_execz .LBB0_1050
	s_waitcnt lgkmcnt(0)
	v_add_f32_e32 v50, v50, v51
	ds_write_b32 v117, v50 offset:512
; #define ROWSUM4(v) do { v += __shfl_xor(v, 16); v += __shfl_xor(v, 32); } while (0)
; template <int EPI>
; __device__ __forceinline__ void gemm_run(const GD& c, const bool has_next, const GD& nx, const Ctx& e, bf16* shm, float* rs, float* rs_nxt, float* racc_) {
;     ...
;   } else if constexpr (EPI == EPI_RESID) {
;     const float sc = e.resid_scale;
;     ROWLOOP { const int lrow = LROW; const long row = brow + lrow; float ss = 0.f;
;       long orow = -1;
;       if (e.final_) {
;         int ri = (int)row;
;         if (ri < ROWS_P) { int s = ri / LP, pos = ri - s * LP; if (pos >= 16) orow = (long)s * 4096 + pos - 16; }
;         else if (ri < TREAL) { int q = ri - ROWS_P; int s = q / LS, pos = q - s * LS; if (pos >= 16) orow = 65536L + (long)s * 8192 + pos - 16; }
;       }
; #pragma unroll
;       for (int bj = 0; bj < 2; ++bj) {
;         const int col = bcol + bj * 128 + wc * 32 + cq8;
;         const long idx = row * 1024 + col;
;         const uint4 hh = *reinterpret_cast<const uint4*>(e.hb + idx);
;         float h[8];
;         h[0] = BFLO(hh.x) + sc * acc[ai][bj][m][0][0]; h[1] = BFHI(hh.x) + sc * acc[ai][bj][m][0][1];
;         h[2] = BFLO(hh.y) + sc * acc[ai][bj][m][0][2]; h[3] = BFHI(hh.y) + sc * acc[ai][bj][m][0][3];
;         h[4] = BFLO(hh.z) + sc * acc[ai][bj][m][1][0]; h[5] = BFHI(hh.z) + sc * acc[ai][bj][m][1][1];
;         h[6] = BFLO(hh.w) + sc * acc[ai][bj][m][1][2]; h[7] = BFHI(hh.w) + sc * acc[ai][bj][m][1][3];
;         if (e.final_) { if (orow >= 0) { *reinterpret_cast<float4*>(e.out + orow * 1024 + col) = make_float4(h[0], h[1], h[2], h[3]);
;                                          *reinterpret_cast<float4*>(e.out + orow * 1024 + col + 4) = make_float4(h[4], h[5], h[6], h[7]); } }
;         else { const uint4 pk = PK8(h[0], h[1], h[2], h[3], h[4], h[5], h[6], h[7]); *reinterpret_cast<uint4*>(e.hb + idx) = pk;
;                const float q0 = BFLO(pk.x), q1 = BFHI(pk.x), q2 = BFLO(pk.y), q3 = BFHI(pk.y), q4 = BFLO(pk.z), q5 = BFHI(pk.z), q6 = BFLO(pk.w), q7 = BFHI(pk.w);
;                ss += (q0 * q0 + q1 * q1 + q2 * q2 + q3 * q3) + (q4 * q4 + q5 * q5 + q6 * q6 + q7 * q7); }
;       }
;       if (!e.final_) { ROWSUM4(ss); if (fq == 0) racc[wc * 256 + lrow] = ss; }
;     }
;     if (!e.final_) { __syncthreads(); if (t2 < 256) e.rpart[(long)(brow + t2) * 4 + pn] = (racc[t2] + racc[256 + t2]) + (racc[512 + t2] + racc[768 + t2]); }
.LBB0_1050:
	s_or_b64 exec, exec, s[4:5]
	v_add_u32_e32 v50, 0x90, v132
	s_waitcnt lgkmcnt(0)
	v_ashrrev_i32_e32 v51, 31, v50
	v_lshlrev_b64 v[50:51], 11, v[50:51]
	v_lshl_add_u64 v[50:51], s[8:9], 0, v[50:51]
	v_lshl_add_u64 v[50:51], v[130:131], 1, v[50:51]
	s_waitcnt vmcnt(15)
	v_mov_b64_e32 v[52:53], v[226:227]
	v_mov_b64_e32 v[54:55], v[228:229]
	v_lshlrev_b32_e32 v56, 16, v52
	v_and_b32_e32 v57, 0xffff0000, v52
	v_lshlrev_b32_e32 v52, 16, v53
	v_and_b32_e32 v53, 0xffff0000, v53
	v_pk_add_f32 v[48:49], v[48:49], v[52:53]
	v_lshlrev_b32_e32 v52, 16, v54
	v_and_b32_e32 v53, 0xffff0000, v54
	v_pk_add_f32 v[52:53], v[42:43], v[52:53]
	v_lshlrev_b32_e32 v42, 16, v55
	v_and_b32_e32 v43, 0xffff0000, v55
	v_pk_add_f32 v[46:47], v[46:47], v[56:57]
	v_pk_add_f32 v[54:55], v[44:45], v[42:43]
	v_cvt_pk_bf16_f32 v42, v46, v47
	v_cvt_pk_bf16_f32 v43, v48, v49
	v_cvt_pk_bf16_f32 v44, v52, v53
	v_cvt_pk_bf16_f32 v45, v54, v55
	global_store_dwordx4 v[50:51], v[42:45], off
	v_lshlrev_b32_e32 v46, 16, v42
	v_lshlrev_b32_e32 v47, 16, v43
	v_and_b32_e32 v42, 0xffff0000, v42
	v_mul_f32_e32 v42, v42, v42
	v_fmac_f32_e32 v42, v46, v46
	v_and_b32_e32 v43, 0xffff0000, v43
	v_lshlrev_b32_e32 v48, 16, v44
	v_and_b32_e32 v44, 0xffff0000, v44
	v_fmac_f32_e32 v42, v47, v47
	v_fmac_f32_e32 v42, v43, v43
	v_mul_f32_e32 v43, v44, v44
	v_lshlrev_b32_e32 v49, 16, v45
	v_fmac_f32_e32 v43, v48, v48
	v_and_b32_e32 v45, 0xffff0000, v45
	v_fmac_f32_e32 v43, v49, v49
	v_fmac_f32_e32 v43, v45, v45
	v_add_f32_e32 v48, v42, v43
	s_waitcnt vmcnt(15)
	v_mov_b64_e32 v[42:43], v[230:231]
	v_mov_b64_e32 v[44:45], v[232:233]
	v_lshlrev_b32_e32 v46, 16, v42
	v_and_b32_e32 v47, 0xffff0000, v42
	v_lshlrev_b32_e32 v42, 16, v43
	v_and_b32_e32 v43, 0xffff0000, v43
	v_pk_add_f32 v[40:41], v[40:41], v[42:43]
	v_lshlrev_b32_e32 v42, 16, v44
	v_and_b32_e32 v43, 0xffff0000, v44
	v_pk_add_f32 v[42:43], v[34:35], v[42:43]
	v_lshlrev_b32_e32 v34, 16, v45
	v_and_b32_e32 v35, 0xffff0000, v45
	v_pk_add_f32 v[38:39], v[38:39], v[46:47]
	v_pk_add_f32 v[44:45], v[36:37], v[34:35]
	v_cvt_pk_bf16_f32 v34, v38, v39
	v_cvt_pk_bf16_f32 v35, v40, v41
	v_cvt_pk_bf16_f32 v36, v42, v43
	v_cvt_pk_bf16_f32 v37, v44, v45
	global_store_dwordx4 v[50:51], v[34:37], off offset:256
	v_lshlrev_b32_e32 v38, 16, v34
	v_lshlrev_b32_e32 v39, 16, v35
	v_and_b32_e32 v34, 0xffff0000, v34
	v_mul_f32_e32 v34, v34, v34
	v_fmac_f32_e32 v34, v38, v38
	v_and_b32_e32 v35, 0xffff0000, v35
	v_lshlrev_b32_e32 v40, 16, v36
	v_and_b32_e32 v36, 0xffff0000, v36
	v_fmac_f32_e32 v34, v39, v39
	v_fmac_f32_e32 v34, v35, v35
	v_mul_f32_e32 v35, v36, v36
	v_lshlrev_b32_e32 v41, 16, v37
	v_fmac_f32_e32 v35, v40, v40
	v_and_b32_e32 v37, 0xffff0000, v37
	v_fmac_f32_e32 v35, v41, v41
	v_fmac_f32_e32 v35, v37, v37
	v_add_f32_e32 v34, v34, v35
	v_add_f32_e32 v34, v48, v34
	ds_bpermute_b32 v35, v116, v34
	s_waitcnt lgkmcnt(0)
	v_add_f32_e32 v34, v34, v35
	ds_bpermute_b32 v35, v118, v34
	s_and_saveexec_b64 s[4:5], vcc
	s_cbranch_execz .LBB0_1052
	s_waitcnt lgkmcnt(0)
	v_add_f32_e32 v34, v34, v35
	ds_write_b32 v117, v34 offset:576
; #define ROWSUM4(v) do { v += __shfl_xor(v, 16); v += __shfl_xor(v, 32); } while (0)
; template <int EPI>
; __device__ __forceinline__ void gemm_run(const GD& c, const bool has_next, const GD& nx, const Ctx& e, bf16* shm, float* rs, float* rs_nxt, float* racc_) {
;     ...
;   } else if constexpr (EPI == EPI_RESID) {
;     const float sc = e.resid_scale;
;     ROWLOOP { const int lrow = LROW; const long row = brow + lrow; float ss = 0.f;
;       long orow = -1;
;       if (e.final_) {
;         int ri = (int)row;
;         if (ri < ROWS_P) { int s = ri / LP, pos = ri - s * LP; if (pos >= 16) orow = (long)s * 4096 + pos - 16; }
;         else if (ri < TREAL) { int q = ri - ROWS_P; int s = q / LS, pos = q - s * LS; if (pos >= 16) orow = 65536L + (long)s * 8192 + pos - 16; }
;       }
; #pragma unroll
;       for (int bj = 0; bj < 2; ++bj) {
;         const int col = bcol + bj * 128 + wc * 32 + cq8;
;         const long idx = row * 1024 + col;
;         const uint4 hh = *reinterpret_cast<const uint4*>(e.hb + idx);
;         float h[8];
;         h[0] = BFLO(hh.x) + sc * acc[ai][bj][m][0][0]; h[1] = BFHI(hh.x) + sc * acc[ai][bj][m][0][1];
;         h[2] = BFLO(hh.y) + sc * acc[ai][bj][m][0][2]; h[3] = BFHI(hh.y) + sc * acc[ai][bj][m][0][3];
;         h[4] = BFLO(hh.z) + sc * acc[ai][bj][m][1][0]; h[5] = BFHI(hh.z) + sc * acc[ai][bj][m][1][1];
;         h[6] = BFLO(hh.w) + sc * acc[ai][bj][m][1][2]; h[7] = BFHI(hh.w) + sc * acc[ai][bj][m][1][3];
;         if (e.final_) { if (orow >= 0) { *reinterpret_cast<float4*>(e.out + orow * 1024 + col) = make_float4(h[0], h[1], h[2], h[3]);
;                                          *reinterpret_cast<float4*>(e.out + orow * 1024 + col + 4) = make_float4(h[4], h[5], h[6], h[7]); } }
;         else { const uint4 pk = PK8(h[0], h[1], h[2], h[3], h[4], h[5], h[6], h[7]); *reinterpret_cast<uint4*>(e.hb + idx) = pk;
;                const float q0 = BFLO(pk.x), q1 = BFHI(pk.x), q2 = BFLO(pk.y), q3 = BFHI(pk.y), q4 = BFLO(pk.z), q5 = BFHI(pk.z), q6 = BFLO(pk.w), q7 = BFHI(pk.w);
;                ss += (q0 * q0 + q1 * q1 + q2 * q2 + q3 * q3) + (q4 * q4 + q5 * q5 + q6 * q6 + q7 * q7); }
;       }
;       if (!e.final_) { ROWSUM4(ss); if (fq == 0) racc[wc * 256 + lrow] = ss; }
;     }
;     if (!e.final_) { __syncthreads(); if (t2 < 256) e.rpart[(long)(brow + t2) * 4 + pn] = (racc[t2] + racc[256 + t2]) + (racc[512 + t2] + racc[768 + t2]); }
.LBB0_1052:
	s_or_b64 exec, exec, s[4:5]
	v_add_u32_e32 v34, 0xa0, v132
	s_waitcnt lgkmcnt(0)
	v_ashrrev_i32_e32 v35, 31, v34
	v_lshlrev_b64 v[34:35], 11, v[34:35]
	v_lshl_add_u64 v[34:35], s[8:9], 0, v[34:35]
	v_lshl_add_u64 v[34:35], v[130:131], 1, v[34:35]
	s_waitcnt vmcnt(15)
	v_mov_b64_e32 v[36:37], v[234:235]
	v_mov_b64_e32 v[38:39], v[236:237]
	v_lshlrev_b32_e32 v40, 16, v36
	v_and_b32_e32 v41, 0xffff0000, v36
	v_lshlrev_b32_e32 v36, 16, v37
	v_and_b32_e32 v37, 0xffff0000, v37
	v_pk_add_f32 v[32:33], v[32:33], v[36:37]
	v_lshlrev_b32_e32 v36, 16, v38
	v_and_b32_e32 v37, 0xffff0000, v38
	v_pk_add_f32 v[36:37], v[26:27], v[36:37]
	v_lshlrev_b32_e32 v26, 16, v39
	v_and_b32_e32 v27, 0xffff0000, v39
	v_pk_add_f32 v[30:31], v[30:31], v[40:41]
	v_pk_add_f32 v[38:39], v[28:29], v[26:27]
	v_cvt_pk_bf16_f32 v26, v30, v31
	v_cvt_pk_bf16_f32 v27, v32, v33
	v_cvt_pk_bf16_f32 v28, v36, v37
	v_cvt_pk_bf16_f32 v29, v38, v39
	global_store_dwordx4 v[34:35], v[26:29], off
	v_lshlrev_b32_e32 v30, 16, v26
	v_lshlrev_b32_e32 v31, 16, v27
	v_and_b32_e32 v26, 0xffff0000, v26
	v_mul_f32_e32 v26, v26, v26
	v_fmac_f32_e32 v26, v30, v30
	v_and_b32_e32 v27, 0xffff0000, v27
	v_lshlrev_b32_e32 v32, 16, v28
	v_and_b32_e32 v28, 0xffff0000, v28
	v_fmac_f32_e32 v26, v31, v31
	v_fmac_f32_e32 v26, v27, v27
	v_mul_f32_e32 v27, v28, v28
	v_lshlrev_b32_e32 v33, 16, v29
	v_fmac_f32_e32 v27, v32, v32
	v_and_b32_e32 v29, 0xffff0000, v29
	v_fmac_f32_e32 v27, v33, v33
	v_fmac_f32_e32 v27, v29, v29
	v_add_f32_e32 v32, v26, v27
	s_waitcnt vmcnt(15)
	v_mov_b64_e32 v[26:27], v[238:239]
	v_mov_b64_e32 v[28:29], v[240:241]
	v_lshlrev_b32_e32 v30, 16, v26
	v_and_b32_e32 v31, 0xffff0000, v26
	v_lshlrev_b32_e32 v26, 16, v27
	v_and_b32_e32 v27, 0xffff0000, v27
	v_pk_add_f32 v[24:25], v[24:25], v[26:27]
	v_lshlrev_b32_e32 v26, 16, v28
	v_and_b32_e32 v27, 0xffff0000, v28
	v_pk_add_f32 v[26:27], v[18:19], v[26:27]
	v_lshlrev_b32_e32 v18, 16, v29
	v_and_b32_e32 v19, 0xffff0000, v29
	v_pk_add_f32 v[22:23], v[22:23], v[30:31]
	v_pk_add_f32 v[28:29], v[20:21], v[18:19]
	v_cvt_pk_bf16_f32 v18, v22, v23
	v_cvt_pk_bf16_f32 v19, v24, v25
	v_cvt_pk_bf16_f32 v20, v26, v27
	v_cvt_pk_bf16_f32 v21, v28, v29
	global_store_dwordx4 v[34:35], v[18:21], off offset:256
	v_lshlrev_b32_e32 v22, 16, v18
	v_lshlrev_b32_e32 v23, 16, v19
	v_and_b32_e32 v18, 0xffff0000, v18
	v_mul_f32_e32 v18, v18, v18
	v_fmac_f32_e32 v18, v22, v22
	v_and_b32_e32 v19, 0xffff0000, v19
	v_lshlrev_b32_e32 v24, 16, v20
	v_and_b32_e32 v20, 0xffff0000, v20
	v_fmac_f32_e32 v18, v23, v23
	v_fmac_f32_e32 v18, v19, v19
	v_mul_f32_e32 v19, v20, v20
	v_lshlrev_b32_e32 v25, 16, v21
	v_fmac_f32_e32 v19, v24, v24
	v_and_b32_e32 v21, 0xffff0000, v21
	v_fmac_f32_e32 v19, v25, v25
	v_fmac_f32_e32 v19, v21, v21
	v_add_f32_e32 v18, v18, v19
	v_add_f32_e32 v18, v32, v18
	ds_bpermute_b32 v19, v116, v18
	s_waitcnt lgkmcnt(0)
	v_add_f32_e32 v18, v18, v19
	ds_bpermute_b32 v19, v118, v18
	s_and_saveexec_b64 s[4:5], vcc
	s_cbranch_execz .LBB0_1054
	s_waitcnt lgkmcnt(0)
	v_add_f32_e32 v18, v18, v19
	ds_write_b32 v117, v18 offset:640
.LBB0_1054:
	s_or_b64 exec, exec, s[4:5]
	v_add_u32_e32 v18, 0xb0, v132
	s_waitcnt lgkmcnt(0)
	v_ashrrev_i32_e32 v19, 31, v18
	v_lshlrev_b64 v[18:19], 11, v[18:19]
	v_lshl_add_u64 v[18:19], s[8:9], 0, v[18:19]
	v_lshl_add_u64 v[18:19], v[130:131], 1, v[18:19]
	s_waitcnt vmcnt(15)
	v_mov_b64_e32 v[20:21], v[242:243]
	v_mov_b64_e32 v[22:23], v[244:245]
	v_lshlrev_b32_e32 v24, 16, v20
	v_and_b32_e32 v25, 0xffff0000, v20
	v_lshlrev_b32_e32 v20, 16, v21
	v_and_b32_e32 v21, 0xffff0000, v21
	v_pk_add_f32 v[16:17], v[16:17], v[20:21]
	v_lshlrev_b32_e32 v20, 16, v22
	v_and_b32_e32 v21, 0xffff0000, v22
	v_pk_add_f32 v[20:21], v[10:11], v[20:21]
	v_lshlrev_b32_e32 v10, 16, v23
	v_and_b32_e32 v11, 0xffff0000, v23
	v_pk_add_f32 v[14:15], v[14:15], v[24:25]
	v_pk_add_f32 v[22:23], v[12:13], v[10:11]
	v_cvt_pk_bf16_f32 v10, v14, v15
	v_cvt_pk_bf16_f32 v11, v16, v17
	v_cvt_pk_bf16_f32 v12, v20, v21
	v_cvt_pk_bf16_f32 v13, v22, v23
	global_store_dwordx4 v[18:19], v[10:13], off
	v_lshlrev_b32_e32 v14, 16, v10
	v_lshlrev_b32_e32 v15, 16, v11
	v_and_b32_e32 v10, 0xffff0000, v10
	v_mul_f32_e32 v10, v10, v10
	v_fmac_f32_e32 v10, v14, v14
	v_and_b32_e32 v11, 0xffff0000, v11
	v_lshlrev_b32_e32 v16, 16, v12
	v_and_b32_e32 v12, 0xffff0000, v12
	v_fmac_f32_e32 v10, v15, v15
	v_fmac_f32_e32 v10, v11, v11
	v_mul_f32_e32 v11, v12, v12
	v_lshlrev_b32_e32 v17, 16, v13
	v_fmac_f32_e32 v11, v16, v16
	v_and_b32_e32 v13, 0xffff0000, v13
	v_fmac_f32_e32 v11, v17, v17
	v_fmac_f32_e32 v11, v13, v13
	v_add_f32_e32 v16, v10, v11
	s_waitcnt vmcnt(15)
	v_mov_b64_e32 v[10:11], v[246:247]
	v_mov_b64_e32 v[12:13], v[248:249]
	v_lshlrev_b32_e32 v14, 16, v10
	v_and_b32_e32 v15, 0xffff0000, v10
	v_lshlrev_b32_e32 v10, 16, v11
	v_and_b32_e32 v11, 0xffff0000, v11
	v_pk_add_f32 v[8:9], v[8:9], v[10:11]
	v_lshlrev_b32_e32 v10, 16, v12
	v_and_b32_e32 v11, 0xffff0000, v12
	v_pk_add_f32 v[10:11], v[2:3], v[10:11]
	v_lshlrev_b32_e32 v2, 16, v13
	v_and_b32_e32 v3, 0xffff0000, v13
	v_pk_add_f32 v[6:7], v[6:7], v[14:15]
	v_pk_add_f32 v[12:13], v[4:5], v[2:3]
	v_cvt_pk_bf16_f32 v2, v6, v7
	v_cvt_pk_bf16_f32 v3, v8, v9
	v_cvt_pk_bf16_f32 v4, v10, v11
	v_cvt_pk_bf16_f32 v5, v12, v13
	global_store_dwordx4 v[18:19], v[2:5], off offset:256
	v_lshlrev_b32_e32 v6, 16, v2
	v_lshlrev_b32_e32 v7, 16, v3
	v_and_b32_e32 v2, 0xffff0000, v2
	v_mul_f32_e32 v2, v2, v2
	v_fmac_f32_e32 v2, v6, v6
	v_and_b32_e32 v3, 0xffff0000, v3
	v_lshlrev_b32_e32 v8, 16, v4
	v_and_b32_e32 v4, 0xffff0000, v4
	v_fmac_f32_e32 v2, v7, v7
	v_fmac_f32_e32 v2, v3, v3
	v_mul_f32_e32 v3, v4, v4
	v_lshlrev_b32_e32 v9, 16, v5
	v_fmac_f32_e32 v3, v8, v8
	v_and_b32_e32 v5, 0xffff0000, v5
	v_fmac_f32_e32 v3, v9, v9
	v_fmac_f32_e32 v3, v5, v5
	v_add_f32_e32 v2, v2, v3
	v_add_f32_e32 v2, v16, v2
	ds_bpermute_b32 v3, v116, v2
	s_waitcnt lgkmcnt(0)
	v_add_f32_e32 v2, v2, v3
	ds_bpermute_b32 v3, v118, v2
	s_and_saveexec_b64 s[4:5], vcc
	s_cbranch_execz .LBB0_1056
	s_waitcnt lgkmcnt(0)
	v_add_f32_e32 v2, v2, v3
	ds_write_b32 v117, v2 offset:704

; #define ROWSUM4(v) do { v += __shfl_xor(v, 16); v += __shfl_xor(v, 32); } while (0)
; template <int EPI>
; __device__ __forceinline__ void gemm_run(const GD& c, const bool has_next, const GD& nx, const Ctx& e, bf16* shm, float* rs, float* rs_nxt, float* racc_) {
;     ...
;   } else if constexpr (EPI == EPI_RESID) {
;     const float sc = e.resid_scale;
;     ROWLOOP { const int lrow = LROW; const long row = brow + lrow; float ss = 0.f;
;       long orow = -1;
;       if (e.final_) {
;         int ri = (int)row;
;         if (ri < ROWS_P) { int s = ri / LP, pos = ri - s * LP; if (pos >= 16) orow = (long)s * 4096 + pos - 16; }
;         else if (ri < TREAL) { int q = ri - ROWS_P; int s = q / LS, pos = q - s * LS; if (pos >= 16) orow = 65536L + (long)s * 8192 + pos - 16; }
;       }
; #pragma unroll
;       for (int bj = 0; bj < 2; ++bj) {
;         const int col = bcol + bj * 128 + wc * 32 + cq8;
;         const long idx = row * 1024 + col;
;         const uint4 hh = *reinterpret_cast<const uint4*>(e.hb + idx);
;         float h[8];
;         h[0] = BFLO(hh.x) + sc * acc[ai][bj][m][0][0]; h[1] = BFHI(hh.x) + sc * acc[ai][bj][m][0][1];
;         h[2] = BFLO(hh.y) + sc * acc[ai][bj][m][0][2]; h[3] = BFHI(hh.y) + sc * acc[ai][bj][m][0][3];
;         h[4] = BFLO(hh.z) + sc * acc[ai][bj][m][1][0]; h[5] = BFHI(hh.z) + sc * acc[ai][bj][m][1][1];
;         h[6] = BFLO(hh.w) + sc * acc[ai][bj][m][1][2]; h[7] = BFHI(hh.w) + sc * acc[ai][bj][m][1][3];
;         if (e.final_) { if (orow >= 0) { *reinterpret_cast<float4*>(e.out + orow * 1024 + col) = make_float4(h[0], h[1], h[2], h[3]);
;                                          *reinterpret_cast<float4*>(e.out + orow * 1024 + col + 4) = make_float4(h[4], h[5], h[6], h[7]); } }
;         else { const uint4 pk = PK8(h[0], h[1], h[2], h[3], h[4], h[5], h[6], h[7]); *reinterpret_cast<uint4*>(e.hb + idx) = pk;
;                const float q0 = BFLO(pk.x), q1 = BFHI(pk.x), q2 = BFLO(pk.y), q3 = BFHI(pk.y), q4 = BFLO(pk.z), q5 = BFHI(pk.z), q6 = BFLO(pk.w), q7 = BFHI(pk.w);
;                ss += (q0 * q0 + q1 * q1 + q2 * q2 + q3 * q3) + (q4 * q4 + q5 * q5 + q6 * q6 + q7 * q7); }
;       }
;       if (!e.final_) { ROWSUM4(ss); if (fq == 0) racc[wc * 256 + lrow] = ss; }
;     }
;     if (!e.final_) { __syncthreads(); if (t2 < 256) e.rpart[(long)(brow + t2) * 4 + pn] = (racc[t2] + racc[256 + t2]) + (racc[512 + t2] + racc[768 + t2]); }
.LBB0_1183:
	v_mov_b32_e32 v0, v165
	s_movk_i32 s4, 0xffc0
	v_and_b32_e32 v130, 15, v0
	v_ashrrev_i32_e32 v134, 2, v0
	v_bfe_u32 v131, v0, 6, 2
	v_bfe_u32 v132, v0, 4, 2
	v_and_or_b32 v134, v134, s4, v130
	v_lshlrev_b32_e32 v133, 3, v132
	v_lshlrev_b32_e32 v130, 5, v131
	v_cmp_eq_u32_e32 vcc, 0, v132
	v_add_u32_e32 v132, s15, v134
	v_or3_b32 v130, v130, v133, s27
	v_ashrrev_i32_e32 v133, 31, v132
	v_readlane_b32 s4, v254, 25
	v_lshlrev_b64 v[136:137], 11, v[132:133]
	v_lshl_add_u64 v[136:137], s[10:11], 0, v[136:137]
	v_lshl_add_u32 v135, v131, 10, s4
	v_ashrrev_i32_e32 v131, 31, v130
	v_lshl_add_u64 v[142:143], v[130:131], 1, v[136:137]
	v_mov_b32_e32 v160, 0x8000
	v_mov_b32_e32 v161, 0
	v_mov_b32_e32 v162, 0x40000
	v_mov_b32_e32 v163, 0
	v_lshl_add_u64 v[146:147], v[142:143], 0, v[160:161]
	v_lshl_add_u64 v[148:149], v[146:147], 0, v[160:161]
	v_lshl_add_u64 v[150:151], v[148:149], 0, v[160:161]
	v_lshl_add_u64 v[152:153], v[142:143], 0, v[162:163]
	v_lshl_add_u64 v[154:155], v[146:147], 0, v[162:163]
	v_lshl_add_u64 v[156:157], v[148:149], 0, v[162:163]
	v_lshl_add_u64 v[158:159], v[150:151], 0, v[162:163]
	global_load_dwordx4 v[186:189], v[142:143], off
	global_load_dwordx4 v[190:193], v[142:143], off offset:256
	global_load_dwordx4 v[194:197], v[146:147], off
	global_load_dwordx4 v[198:201], v[146:147], off offset:256
	global_load_dwordx4 v[202:205], v[148:149], off
	global_load_dwordx4 v[206:209], v[148:149], off offset:256
	global_load_dwordx4 v[210:213], v[150:151], off
	global_load_dwordx4 v[214:217], v[150:151], off offset:256
	global_load_dwordx4 v[218:221], v[152:153], off
	global_load_dwordx4 v[222:225], v[152:153], off offset:256
	global_load_dwordx4 v[226:229], v[154:155], off
	global_load_dwordx4 v[230:233], v[154:155], off offset:256
	global_load_dwordx4 v[234:237], v[156:157], off
	global_load_dwordx4 v[238:241], v[156:157], off offset:256
	global_load_dwordx4 v[242:245], v[158:159], off
	global_load_dwordx4 v[246:249], v[158:159], off offset:256
	s_waitcnt vmcnt(15)
	v_mov_b64_e32 v[136:137], v[186:187]
	v_mov_b64_e32 v[138:139], v[188:189]
	v_lshlrev_b32_e32 v144, 16, v136
	v_and_b32_e32 v145, 0xffff0000, v136
	v_lshlrev_b32_e32 v136, 16, v137
	v_and_b32_e32 v137, 0xffff0000, v137
	v_pk_fma_f32 v[128:129], v[128:129], 0.5, v[136:137] op_sel_hi:[1,0,1]
	v_lshlrev_b32_e32 v136, 16, v138
	v_and_b32_e32 v137, 0xffff0000, v138
	v_pk_fma_f32 v[136:137], v[122:123], 0.5, v[136:137] op_sel_hi:[1,0,1]
	v_lshlrev_b32_e32 v122, 16, v139
	v_and_b32_e32 v123, 0xffff0000, v139
	v_pk_fma_f32 v[126:127], v[126:127], 0.5, v[144:145] op_sel_hi:[1,0,1]
	v_pk_fma_f32 v[138:139], v[124:125], 0.5, v[122:123] op_sel_hi:[1,0,1]
	v_cvt_pk_bf16_f32 v122, v126, v127
	v_cvt_pk_bf16_f32 v123, v128, v129
	v_cvt_pk_bf16_f32 v124, v136, v137
	v_cvt_pk_bf16_f32 v125, v138, v139
	global_store_dwordx4 v[142:143], v[122:125], off
	v_lshlrev_b32_e32 v126, 16, v122
	v_lshlrev_b32_e32 v127, 16, v123
	v_and_b32_e32 v122, 0xffff0000, v122
	v_mul_f32_e32 v122, v122, v122
	v_fmac_f32_e32 v122, v126, v126
	v_and_b32_e32 v123, 0xffff0000, v123
	v_lshlrev_b32_e32 v128, 16, v124
	v_and_b32_e32 v124, 0xffff0000, v124
	v_fmac_f32_e32 v122, v127, v127
	v_fmac_f32_e32 v122, v123, v123
	v_mul_f32_e32 v123, v124, v124
	v_lshlrev_b32_e32 v129, 16, v125
	v_fmac_f32_e32 v123, v128, v128
	v_and_b32_e32 v125, 0xffff0000, v125
	v_fmac_f32_e32 v123, v129, v129
	v_fmac_f32_e32 v123, v125, v125
	v_add_f32_e32 v128, v122, v123
	s_waitcnt vmcnt(15)
	v_mov_b64_e32 v[122:123], v[190:191]
	v_mov_b64_e32 v[124:125], v[192:193]
	v_lshlrev_b32_e32 v126, 16, v122
	v_and_b32_e32 v127, 0xffff0000, v122
	v_lshlrev_b32_e32 v122, 16, v123
	v_and_b32_e32 v123, 0xffff0000, v123
	v_pk_fma_f32 v[120:121], v[120:121], 0.5, v[122:123] op_sel_hi:[1,0,1]
	v_lshlrev_b32_e32 v122, 16, v124
	v_and_b32_e32 v123, 0xffff0000, v124
	v_pk_fma_f32 v[122:123], v[114:115], 0.5, v[122:123] op_sel_hi:[1,0,1]
	v_lshlrev_b32_e32 v114, 16, v125
	v_and_b32_e32 v115, 0xffff0000, v125
	v_pk_fma_f32 v[118:119], v[118:119], 0.5, v[126:127] op_sel_hi:[1,0,1]
	v_pk_fma_f32 v[124:125], v[116:117], 0.5, v[114:115] op_sel_hi:[1,0,1]
	v_cvt_pk_bf16_f32 v114, v118, v119
	v_cvt_pk_bf16_f32 v115, v120, v121
	v_cvt_pk_bf16_f32 v116, v122, v123
	v_cvt_pk_bf16_f32 v117, v124, v125
	global_store_dwordx4 v[142:143], v[114:117], off offset:256
	v_lshlrev_b32_e32 v118, 16, v114
	v_lshlrev_b32_e32 v119, 16, v115
	v_and_b32_e32 v114, 0xffff0000, v114
	v_mul_f32_e32 v114, v114, v114
	v_fmac_f32_e32 v114, v118, v118
	v_and_b32_e32 v115, 0xffff0000, v115
	v_lshlrev_b32_e32 v120, 16, v116
	v_and_b32_e32 v116, 0xffff0000, v116
	v_fmac_f32_e32 v114, v119, v119
	v_fmac_f32_e32 v114, v115, v115
	v_mul_f32_e32 v115, v116, v116
	v_lshlrev_b32_e32 v121, 16, v117
	v_fmac_f32_e32 v115, v120, v120
	v_and_b32_e32 v117, 0xffff0000, v117
	v_fmac_f32_e32 v115, v121, v121
	v_fmac_f32_e32 v115, v117, v117
	v_and_b32_e32 v116, 64, v180
	v_add_f32_e32 v114, v114, v115
	v_xor_b32_e32 v115, 16, v180
	v_add_u32_e32 v117, 64, v116
	v_cmp_lt_i32_e64 s[4:5], v115, v117
	v_add_f32_e32 v114, v128, v114
	s_nop 0
	v_cndmask_b32_e64 v115, v180, v115, s[4:5]
	v_lshlrev_b32_e32 v116, 2, v115
	ds_bpermute_b32 v115, v116, v114
	s_waitcnt lgkmcnt(0)
	v_add_f32_e32 v114, v114, v115
	v_xor_b32_e32 v115, 32, v180
	v_cmp_lt_i32_e64 s[4:5], v115, v117
	v_lshl_add_u32 v117, v134, 2, v135
	s_nop 0
	v_cndmask_b32_e64 v115, v180, v115, s[4:5]
	v_lshlrev_b32_e32 v118, 2, v115
	ds_bpermute_b32 v115, v118, v114
	s_and_saveexec_b64 s[4:5], vcc
	s_cbranch_execz .LBB0_1185
	s_waitcnt lgkmcnt(0)
	v_add_f32_e32 v114, v114, v115
	ds_write_b32 v117, v114
